# epilogue 1/sqrt(x): IEEE sqrt+div sequence replaced by v_rsq_f32 + one Newton step (f32, ~1ulp) in P3, P5a, P7 epilogues; on top of v1 Q prefetch
# speedup vs baseline: 1.0109x; 1.0109x over previous
; __device__ __forceinline__ float rstd_of(const float* ssq, int row) {
;     const f32x4* p = (const f32x4*)ssq + row; const f32x4 s = (p[0] + p[MROWS]) + (p[2 * MROWS] + p[3 * MROWS]);
;     return 1.0f / sqrtf(((s[0] + s[1]) + (s[2] + s[3])) * (1.0f / 1024.0f) + RMS_EPS); }
;     __device__ __forceinline__ void operator()(const f32x4 (&acc)[2][2][4][2], const Unit& u, int wr, int wc, int fr, int fq) const {
;         const int row0 = u.pm * BM + wr * 64 + fr;
;         int type; const float* gain; bf16_t* base; int pitch; float scale = 1.0f;
;         if (u.pn < 4) { base = QO + u.pn * BM + wc * 64; pitch = QOP; scale = 0.125f * 1.4426950408889634f; if (u.pn < 2) { type = 1; gain = gaq; } else { type = 2; gain = gbq; } }
;         else { base = KV + (u.pn - 4) * BM + wc * 64; pitch = KVP; gain = gbk;
;                if (u.pn == 4) { type = (wc < 2) ? 1 : 0; gain = gak; } else if (u.pn < 7) { type = 2; } else { type = 0; } }
;         base += 8 * fq;
;         f32x4 g[4];
; #pragma unroll
;         for (int q = 0; q < 4; ++q) g[q] = *(const f32x4*)(gain + (q >> 1) * 32 + 8 * fq + (q & 1) * 4);
; #pragma unroll
;         for (int ai = 0; ai < 2; ++ai)
; #pragma unroll
;             for (int m = 0; m < 4; ++m) {
;                 const int row = row0 + ai * HALF + m * 16;
;                 const float rs = rstd_of(ssq, row);
;                 float lo[8], hi[8];
; #pragma unroll
;                 for (int n = 0; n < 2; ++n)
; #pragma unroll
;                     for (int e = 0; e < 4; ++e) { lo[4 * n + e] = acc[ai][0][m][n][e] * rs; hi[4 * n + e] = acc[ai][1][m][n][e] * rs; }
.LBB0_507:
	s_cmp_lg_u32 s1, 0
	v_lshl_add_u32 v172, s0, 8, v163
	s_cselect_b64 s[78:79], -1, 0
	s_cmp_lg_u32 s1, 1
	s_cselect_b64 s[12:13], -1, 0
	s_cmp_eq_u32 s1, 1
	v_ashrrev_i32_e32 v173, 31, v172
	s_cselect_b64 vcc, -1, 0
	v_lshl_add_u64 v[174:175], v[172:173], 4, s[24:25]
	s_mov_b32 s0, 0xc0000
	v_cndmask_b32_e32 v223, 32, v162, vcc
	v_add_co_u32_e32 v176, vcc, s0, v174
	v_lshlrev_b32_e32 v36, 2, v162
	s_nop 0
	v_addc_co_u32_e32 v177, vcc, 0, v175, vcc
	global_load_dwordx4 v[28:31], v36, s[16:17] offset:16
	global_load_dwordx4 v[32:35], v36, s[16:17]
	global_load_dwordx4 v[24:27], v36, s[16:17] offset:144
	s_nop 0
	global_load_dwordx4 v[36:39], v36, s[16:17] offset:128
	s_mov_b32 s0, 0x180000
	global_load_dwordx4 v[144:147], v[174:175], off
	global_load_dwordx4 v[148:151], v[176:177], off
	v_add_co_u32_e32 v178, vcc, s0, v174
	s_mov_b32 s0, 0x240000
	s_nop 0
	v_addc_co_u32_e32 v179, vcc, 0, v175, vcc
	v_add_co_u32_e32 v180, vcc, s0, v174
	s_cmp_eq_u32 s1, 0
	s_nop 0
	v_addc_co_u32_e32 v181, vcc, 0, v175, vcc
	s_waitcnt vmcnt(0)
	v_pk_add_f32 v[182:183], v[146:147], v[150:151]
	v_pk_add_f32 v[184:185], v[144:145], v[148:149]
	global_load_dwordx4 v[144:147], v[178:179], off
	global_load_dwordx4 v[148:151], v[180:181], off
	s_waitcnt vmcnt(0)
	v_pk_add_f32 v[146:147], v[146:147], v[150:151]
	v_pk_add_f32 v[144:145], v[144:145], v[148:149]
	v_pk_add_f32 v[146:147], v[182:183], v[146:147]
	v_pk_add_f32 v[144:145], v[184:185], v[144:145]
	s_nop 0
	v_pk_mov_b32 v[148:149], v[144:145], v[146:147] op_sel:[1,0]
	v_mov_b32_e32 v145, v147
	v_pk_add_f32 v[144:145], v[148:149], v[144:145]
	s_nop 0
	v_add_f32_e32 v144, v144, v145
	v_fmamk_f32 v144, v144, 0x3a800000, v212
	v_cmp_gt_f32_e32 vcc, s95, v144
	v_rsq_f32_e32 v252, v144
	s_nop 0
	v_mul_f32_e32 v250, v144, v252
	v_fma_f32 v250, -v250, v252, 1.0
	v_mul_f32_e32 v251, 0.5, v252
	v_fma_f32 v144, v251, v250, v252
	v_mov_b32_e32 v147, v5
	v_mov_b32_e32 v5, v141
	v_pk_mul_f32 v[188:189], v[4:5], v[144:145] op_sel_hi:[1,0]
	v_mov_b32_e32 v5, v7
	v_mov_b32_e32 v7, v143
	v_pk_mul_f32 v[190:191], v[6:7], v[144:145] op_sel_hi:[1,0]
	v_mov_b32_e32 v7, v1
	v_mov_b32_e32 v1, v137
	v_mov_b32_e32 v146, v140
	v_mov_b32_e32 v4, v142
	v_mov_b32_e32 v6, v136
	v_pk_mul_f32 v[192:193], v[0:1], v[144:145] op_sel_hi:[1,0]
	v_mul_f32_e32 v1, v138, v144
	v_mov_b32_e32 v138, v3
	v_cndmask_b32_e64 v0, 0, 1, s[12:13]
	v_pk_mul_f32 v[184:185], v[146:147], v[144:145] op_sel_hi:[1,0]
	v_pk_mul_f32 v[4:5], v[4:5], v[144:145] op_sel_hi:[1,0]
	v_pk_mul_f32 v[186:187], v[6:7], v[144:145] op_sel_hi:[1,0]
	v_mul_f32_e32 v183, v2, v144
	v_pk_mul_f32 v[6:7], v[138:139], v[144:145] op_sel_hi:[1,0]
	v_cmp_ne_u32_e64 s[12:13], 1, v0
	s_cbranch_scc1 .LBB0_513
;     __device__ __forceinline__ void operator()(const f32x4 (&acc)[2][2][4][2], const Unit& u, int wr, int wc, int fr, int fq) const {
;     ...
;                 if (type != 0) {
;                     float ss = 0.f;
; #pragma unroll
;                     for (int k = 0; k < 8; ++k) ss += lo[k] * lo[k] + hi[k] * hi[k];
;                     ss += __shfl_xor(ss, 16); ss += __shfl_xor(ss, 32);
;                     const float rn = 1.0f / sqrtf(ss * (1.0f / 64.0f) + RMS_EPS);
; #pragma unroll
;                     for (int k = 0; k < 8; ++k) { lo[k] *= rn * g[k >> 2][k & 3]; hi[k] *= rn * g[2 + (k >> 2)][k & 3]; }
;                     const int t = (row < M_P) ? (row & 8191) : ((row - M_P) & 4095);
;                     const f32x4* rp = (const f32x4*)(rope + ((size_t)t * 40 + (type == 1 ? 8 * fq : 32)) * 2);
;                     const f32x4 c01 = rp[0], c23 = rp[1], c45 = rp[2], c67 = rp[3];
;                     const float cs[16] = {c01[0], c01[1], c01[2], c01[3], c23[0], c23[1], c23[2], c23[3], c45[0], c45[1], c45[2], c45[3], c67[0], c67[1], c67[2], c67[3]};
;                     if (type == 1) {
; #pragma unroll
;                         for (int k = 0; k < 8; ++k) { const float a = lo[k], b = hi[k]; lo[k] = a * cs[2 * k] - b * cs[2 * k + 1]; hi[k] = b * cs[2 * k] + a * cs[2 * k + 1]; }
;                     } else {
; #pragma unroll
;                         for (int k = 0; k < 8; ++k) { const float p = __shfl_xor(lo[k], 16); const float r = (fq == 0) ? lo[k] * cs[2 * k] - p * cs[2 * k + 1] : lo[k] * cs[2 * k] + p * cs[2 * k + 1]; lo[k] = (fq < 2) ? r : lo[k]; }
	v_pk_mul_f32 v[2:3], v[188:189], v[188:189]
	v_mov_b32_e32 v182, v6
	v_pk_fma_f32 v[2:3], v[184:185], v[184:185], v[2:3]
	v_pk_mul_f32 v[136:137], v[190:191], v[190:191]
	v_mov_b32_e32 v0, v7
	v_pk_mul_f32 v[140:141], v[182:183], v[182:183]
	v_pk_fma_f32 v[136:137], v[4:5], v[4:5], v[136:137]
	v_pk_fma_f32 v[140:141], v[0:1], v[0:1], v[140:141]
	v_add_f32_e32 v0, v2, v3
	v_pk_mul_f32 v[138:139], v[192:193], v[192:193]
	v_add_f32_e32 v0, v136, v0
	v_pk_fma_f32 v[138:139], v[186:187], v[186:187], v[138:139]
	v_add_f32_e32 v0, v137, v0
	v_and_b32_e32 v3, 64, v214
	v_add_f32_e32 v0, v138, v0
	v_xor_b32_e32 v2, 16, v214
	v_add_u32_e32 v3, 64, v3
	v_add_f32_e32 v0, v139, v0
	v_cmp_lt_i32_e32 vcc, v2, v3
	v_add_f32_e32 v0, v141, v0
	v_add_f32_e32 v0, v140, v0
	v_cndmask_b32_e32 v2, v214, v2, vcc
	v_lshlrev_b32_e32 v173, 2, v2
	ds_bpermute_b32 v2, v173, v0
	v_cmp_gt_i32_e32 vcc, s86, v172
	s_waitcnt lgkmcnt(0)
	v_add_f32_e32 v0, v0, v2
	v_cndmask_b32_e32 v2, v215, v216, vcc
	v_and_b32_e32 v2, v2, v172
	v_mul_u32_u24_e32 v2, 40, v2
	v_add_lshl_u32 v2, v223, v2, 3
	global_load_dwordx4 v[136:139], v2, s[44:45] offset:48
	global_load_dwordx4 v[140:143], v2, s[44:45] offset:32
	global_load_dwordx4 v[144:147], v2, s[44:45] offset:16
	global_load_dwordx4 v[148:151], v2, s[44:45]
	v_xor_b32_e32 v2, 32, v214
	v_cmp_lt_i32_e32 vcc, v2, v3
	s_nop 1
	v_cndmask_b32_e32 v2, v214, v2, vcc
	v_lshlrev_b32_e32 v2, 2, v2
	ds_bpermute_b32 v2, v2, v0
	s_waitcnt lgkmcnt(0)
	v_add_f32_e32 v0, v0, v2
	v_fmamk_f32 v0, v0, 0x3c800000, v212
	v_rsq_f32_e32 v252, v0
	s_nop 0
	v_mul_f32_e32 v250, v0, v252
	v_fma_f32 v250, -v250, v252, 1.0
	v_mul_f32_e32 v251, 0.5, v252
	s_mov_b64 s[0:1], -1
	v_fma_f32 v182, v251, v250, v252
	v_mov_b32_e32 v2, v32
	v_mov_b32_e32 v3, v37
	v_mov_b32_e32 v194, v36
	v_mov_b32_e32 v195, v33
	v_pk_mul_f32 v[2:3], v[2:3], v[182:183] op_sel_hi:[1,0]
	v_pk_mul_f32 v[194:195], v[194:195], v[182:183] op_sel_hi:[1,0]
	v_pk_mul_f32 v[184:185], v[184:185], v[2:3]
	v_pk_mul_f32 v[196:197], v[188:189], v[194:195]
	v_mov_b32_e32 v2, v34
	v_mov_b32_e32 v3, v39
	v_mov_b32_e32 v188, v38
	v_mov_b32_e32 v189, v35
	v_pk_mul_f32 v[2:3], v[2:3], v[182:183] op_sel_hi:[1,0]
	v_pk_mul_f32 v[188:189], v[188:189], v[182:183] op_sel_hi:[1,0]
	v_mul_f32_e32 v0, v30, v182
	v_pk_mul_f32 v[194:195], v[190:191], v[188:189]
	v_pk_mul_f32 v[188:189], v[4:5], v[2:3]
	v_mov_b32_e32 v2, v28
	v_mov_b32_e32 v3, v25
	v_mov_b32_e32 v4, v24
	v_mov_b32_e32 v5, v29
	v_mul_f32_e32 v224, v1, v0
	v_mov_b32_e32 v0, v27
	v_mov_b32_e32 v1, v31
	v_pk_mul_f32 v[2:3], v[2:3], v[182:183] op_sel_hi:[1,0]
	v_pk_mul_f32 v[4:5], v[4:5], v[182:183] op_sel_hi:[1,0]
	v_pk_mul_f32 v[0:1], v[0:1], v[182:183] op_sel_hi:[1,0]
	v_pk_mul_f32 v[192:193], v[192:193], v[4:5]
	v_pk_mul_f32 v[186:187], v[186:187], v[2:3]
	v_pk_mul_f32 v[190:191], v[6:7], v[0:1]
	s_and_b64 vcc, exec, s[12:13]
	s_cbranch_vccnz .LBB0_510
	ds_bpermute_b32 v0, v173, v184
	ds_bpermute_b32 v1, v173, v197
	ds_bpermute_b32 v2, v173, v188
	ds_bpermute_b32 v3, v173, v195
	ds_bpermute_b32 v4, v173, v186
	ds_bpermute_b32 v5, v173, v193
	ds_bpermute_b32 v6, v173, v224
	ds_bpermute_b32 v7, v173, v191
	s_waitcnt vmcnt(0) lgkmcnt(7)
	v_mul_f32_e32 v0, v149, v0
	s_waitcnt lgkmcnt(6)
	v_mul_f32_e32 v1, v151, v1
	s_waitcnt lgkmcnt(5)
	v_mul_f32_e32 v2, v145, v2
	s_waitcnt lgkmcnt(4)
	v_mul_f32_e32 v3, v147, v3
	s_waitcnt lgkmcnt(3)
	v_mul_f32_e32 v4, v141, v4
	s_waitcnt lgkmcnt(2)
	v_mul_f32_e32 v5, v143, v5
	s_waitcnt lgkmcnt(1)
	v_mul_f32_e32 v6, v137, v6
	s_waitcnt lgkmcnt(0)
	v_mul_f32_e32 v7, v139, v7
	v_cndmask_b32_e64 v0, v0, -v0, s[6:7]
	v_cndmask_b32_e64 v1, v1, -v1, s[6:7]
	v_cndmask_b32_e64 v2, v2, -v2, s[6:7]
	v_cndmask_b32_e64 v3, v3, -v3, s[6:7]
	v_cndmask_b32_e64 v4, v4, -v4, s[6:7]
	v_cndmask_b32_e64 v5, v5, -v5, s[6:7]
	v_cndmask_b32_e64 v6, v6, -v6, s[6:7]
	v_cndmask_b32_e64 v7, v7, -v7, s[6:7]
	v_fmac_f32_e32 v0, v148, v184
	v_fmac_f32_e32 v1, v150, v197
	v_fmac_f32_e32 v2, v144, v188
	v_fmac_f32_e32 v3, v146, v195
	v_fmac_f32_e32 v4, v140, v186
	v_fmac_f32_e32 v5, v142, v193
	v_fmac_f32_e32 v6, v136, v224
	v_fmac_f32_e32 v7, v138, v191
	v_cndmask_b32_e64 v0, v184, v0, s[8:9]
	v_cndmask_b32_e64 v1, v197, v1, s[8:9]
	v_cndmask_b32_e64 v2, v188, v2, s[8:9]
	v_cndmask_b32_e64 v3, v195, v3, s[8:9]
	v_cndmask_b32_e64 v4, v186, v4, s[8:9]
	v_cndmask_b32_e64 v5, v193, v5, s[8:9]
	v_cndmask_b32_e64 v6, v224, v6, s[8:9]
	v_cndmask_b32_e64 v7, v191, v7, s[8:9]
	s_mov_b64 s[0:1], 0
	v_mov_b32_e32 v199, v190
	v_mov_b32_e32 v205, v187
	v_mov_b32_e32 v204, v192
	v_mov_b32_e32 v203, v189
	v_mov_b32_e32 v202, v194
	v_mov_b32_e32 v201, v185
	v_mov_b32_e32 v200, v196

;     __device__ __forceinline__ void operator()(const f32x4 (&acc)[2][2][4][2], const Unit& u, int wr, int wc, int fr, int fq) const {
;     ...
;                 const int row = row0 + ai * HALF + m * 16;
;                 const float rs = rstd_of(ssq, row);
;                 float lo[8], hi[8];
; #pragma unroll
;                 for (int n = 0; n < 2; ++n)
; #pragma unroll
;                     for (int e = 0; e < 4; ++e) { lo[4 * n + e] = acc[ai][0][m][n][e] * rs; hi[4 * n + e] = acc[ai][1][m][n][e] * rs; }
;                 if (type != 0) {
;                     float ss = 0.f;
; #pragma unroll
;                     for (int k = 0; k < 8; ++k) ss += lo[k] * lo[k] + hi[k] * hi[k];
;                     ss += __shfl_xor(ss, 16); ss += __shfl_xor(ss, 32);
;                     const float rn = 1.0f / sqrtf(ss * (1.0f / 64.0f) + RMS_EPS);
; #pragma unroll
;                     for (int k = 0; k < 8; ++k) { lo[k] *= rn * g[k >> 2][k & 3]; hi[k] *= rn * g[2 + (k >> 2)][k & 3]; }
;                     const int t = (row < M_P) ? (row & 8191) : ((row - M_P) & 4095);
;                     const f32x4* rp = (const f32x4*)(rope + ((size_t)t * 40 + (type == 1 ? 8 * fq : 32)) * 2);
;                     const f32x4 c01 = rp[0], c23 = rp[1], c45 = rp[2], c67 = rp[3];
;                     const float cs[16] = {c01[0], c01[1], c01[2], c01[3], c23[0], c23[1], c23[2], c23[3], c45[0], c45[1], c45[2], c45[3], c67[0], c67[1], c67[2], c67[3]};
;                     if (type == 1) {
; #pragma unroll
;                         for (int k = 0; k < 8; ++k) { const float a = lo[k], b = hi[k]; lo[k] = a * cs[2 * k] - b * cs[2 * k + 1]; hi[k] = b * cs[2 * k] + a * cs[2 * k + 1]; }
;                     } else {
; #pragma unroll
;                         for (int k = 0; k < 8; ++k) { const float p = __shfl_xor(lo[k], 16); const float r = (fq == 0) ? lo[k] * cs[2 * k] - p * cs[2 * k + 1] : lo[k] * cs[2 * k] + p * cs[2 * k + 1]; lo[k] = (fq < 2) ? r : lo[k]; }
;                     }
; #pragma unroll
;                     for (int k = 0; k < 8; ++k) { lo[k] *= scale; hi[k] *= scale; }
;                 }
;                 u32x4 w0, w1;
;                 w0.x = cvt_pk_bf16(lo[0], lo[1]); w0.y = cvt_pk_bf16(lo[2], lo[3]); w0.z = cvt_pk_bf16(lo[4], lo[5]); w0.w = cvt_pk_bf16(lo[6], lo[7]);
.LBB0_514:
	s_add_u32 s0, s14, s96
	s_addc_u32 s1, s15, 0
	v_lshl_add_u64 v[136:137], s[0:1], 0, v[160:161]
	v_cvt_pk_bf16_f32 v142, v142, v143
	v_cvt_pk_bf16_f32 v143, v140, v141
	s_waitcnt vmcnt(1)
	v_cvt_pk_bf16_f32 v144, v138, v139
	v_cvt_pk_bf16_f32 v145, v1, v7
	v_cvt_pk_bf16_f32 v0, v184, v185
	v_cvt_pk_bf16_f32 v1, v4, v5
	v_mad_i64_i32 v[4:5], s[0:1], s76, v172, 0
	v_lshl_add_u64 v[4:5], v[4:5], 1, v[136:137]
	v_cvt_pk_bf16_f32 v2, v186, v187
	v_cvt_pk_bf16_f32 v3, v183, v3
	global_store_dwordx4 v[4:5], v[142:145], off
	global_store_dwordx4 v[4:5], v[0:3], off offset:64
	global_load_dwordx4 v[0:3], v[174:175], off offset:256
	s_nop 0
	global_load_dwordx4 v[4:7], v[176:177], off offset:256
	global_load_dwordx4 v[138:141], v[178:179], off offset:256
	global_load_dwordx4 v[142:145], v[180:181], off offset:256
	v_mov_b32_e32 v146, v132
	v_mov_b32_e32 v147, v125
	v_mov_b32_e32 v125, v133
	v_mov_b32_e32 v132, v134
	v_mov_b32_e32 v133, v127
	v_mov_b32_e32 v127, v135
	v_mov_b32_e32 v134, v128
	v_mov_b32_e32 v135, v121
	v_mov_b32_e32 v121, v129
	v_or_b32_e32 v173, 16, v172
	s_waitcnt vmcnt(2)
	v_pk_add_f32 v[2:3], v[2:3], v[6:7]
	v_pk_add_f32 v[0:1], v[0:1], v[4:5]
	s_waitcnt vmcnt(0)
	v_pk_add_f32 v[4:5], v[140:141], v[144:145]
	v_pk_add_f32 v[6:7], v[138:139], v[142:143]
	v_pk_add_f32 v[2:3], v[2:3], v[4:5]
	v_pk_add_f32 v[0:1], v[0:1], v[6:7]
	s_nop 0
	v_pk_mov_b32 v[4:5], v[0:1], v[2:3] op_sel:[1,0]
	v_mov_b32_e32 v1, v3
	v_pk_add_f32 v[0:1], v[4:5], v[0:1]
	v_cndmask_b32_e64 v2, 0, 1, s[78:79]
	v_add_f32_e32 v0, v0, v1
	v_fmamk_f32 v0, v0, 0x3a800000, v212
	v_rsq_f32_e32 v252, v0
	s_nop 0
	v_mul_f32_e32 v250, v0, v252
	v_fma_f32 v250, -v250, v252, 1.0
	v_mul_f32_e32 v251, 0.5, v252
	v_cmp_ne_u32_e64 s[14:15], 1, v2
	s_nop 1
	v_fma_f32 v6, v251, v250, v252
	v_mul_f32_e32 v141, v130, v6
	v_mov_b32_e32 v130, v123
	v_pk_mul_f32 v[4:5], v[146:147], v[6:7] op_sel_hi:[1,0]
	v_pk_mul_f32 v[142:143], v[124:125], v[6:7] op_sel_hi:[1,0]
	v_pk_mul_f32 v[2:3], v[132:133], v[6:7] op_sel_hi:[1,0]
	v_pk_mul_f32 v[144:145], v[126:127], v[6:7] op_sel_hi:[1,0]
	v_pk_mul_f32 v[0:1], v[134:135], v[6:7] op_sel_hi:[1,0]
	v_pk_mul_f32 v[146:147], v[120:121], v[6:7] op_sel_hi:[1,0]
	v_mul_f32_e32 v139, v122, v6
	s_andn2_b64 vcc, exec, s[78:79]
	v_pk_mul_f32 v[6:7], v[130:131], v[6:7] op_sel_hi:[1,0]
	s_cbranch_vccnz .LBB0_520
;     __device__ __forceinline__ void operator()(const f32x4 (&acc)[2][2][4][2], const Unit& u, int wr, int wc, int fr, int fq) const {
;     ...
;                 if (type != 0) {
;                     float ss = 0.f;
; #pragma unroll
;                     for (int k = 0; k < 8; ++k) ss += lo[k] * lo[k] + hi[k] * hi[k];
;                     ss += __shfl_xor(ss, 16); ss += __shfl_xor(ss, 32);
;                     const float rn = 1.0f / sqrtf(ss * (1.0f / 64.0f) + RMS_EPS);
; #pragma unroll
;                     for (int k = 0; k < 8; ++k) { lo[k] *= rn * g[k >> 2][k & 3]; hi[k] *= rn * g[2 + (k >> 2)][k & 3]; }
;                     const int t = (row < M_P) ? (row & 8191) : ((row - M_P) & 4095);
;                     const f32x4* rp = (const f32x4*)(rope + ((size_t)t * 40 + (type == 1 ? 8 * fq : 32)) * 2);
;                     const f32x4 c01 = rp[0], c23 = rp[1], c45 = rp[2], c67 = rp[3];
;                     const float cs[16] = {c01[0], c01[1], c01[2], c01[3], c23[0], c23[1], c23[2], c23[3], c45[0], c45[1], c45[2], c45[3], c67[0], c67[1], c67[2], c67[3]};
;                     if (type == 1) {
; #pragma unroll
;                         for (int k = 0; k < 8; ++k) { const float a = lo[k], b = hi[k]; lo[k] = a * cs[2 * k] - b * cs[2 * k + 1]; hi[k] = b * cs[2 * k] + a * cs[2 * k + 1]; }
;                     } else {
; #pragma unroll
;                         for (int k = 0; k < 8; ++k) { const float p = __shfl_xor(lo[k], 16); const float r = (fq == 0) ? lo[k] * cs[2 * k] - p * cs[2 * k + 1] : lo[k] * cs[2 * k] + p * cs[2 * k + 1]; lo[k] = (fq < 2) ? r : lo[k]; }
	v_pk_mul_f32 v[120:121], v[142:143], v[142:143]
	v_pk_mul_f32 v[122:123], v[144:145], v[144:145]
	v_pk_fma_f32 v[120:121], v[4:5], v[4:5], v[120:121]
	v_pk_fma_f32 v[122:123], v[2:3], v[2:3], v[122:123]
	v_add_f32_e32 v120, v120, v121
	v_pk_mul_f32 v[124:125], v[146:147], v[146:147]
	v_add_f32_e32 v120, v122, v120
	v_pk_fma_f32 v[124:125], v[0:1], v[0:1], v[124:125]
	v_mov_b32_e32 v138, v6
	v_add_f32_e32 v120, v123, v120
	v_and_b32_e32 v122, 64, v214
	v_mov_b32_e32 v140, v7
	v_pk_mul_f32 v[126:127], v[138:139], v[138:139]
	v_add_f32_e32 v120, v124, v120
	v_xor_b32_e32 v121, 16, v214
	v_add_u32_e32 v138, 64, v122
	v_pk_fma_f32 v[126:127], v[140:141], v[140:141], v[126:127]
	v_add_f32_e32 v120, v125, v120
	v_cmp_lt_i32_e32 vcc, v121, v138
	v_add_f32_e32 v120, v127, v120
	v_add_f32_e32 v120, v126, v120
	v_cndmask_b32_e32 v121, v214, v121, vcc
	v_lshlrev_b32_e32 v184, 2, v121
	ds_bpermute_b32 v121, v184, v120
	v_cmp_gt_i32_e32 vcc, s86, v173
	v_xor_b32_e32 v148, 32, v214
	s_waitcnt lgkmcnt(0)
	v_add_f32_e32 v140, v120, v121
	v_cndmask_b32_e32 v120, v217, v218, vcc
	v_and_b32_e32 v120, v120, v173
	v_mul_u32_u24_e32 v120, 40, v120
	v_add_lshl_u32 v132, v223, v120, 3
	global_load_dwordx4 v[120:123], v132, s[44:45] offset:48
	global_load_dwordx4 v[124:127], v132, s[44:45] offset:32
	global_load_dwordx4 v[128:131], v132, s[44:45] offset:16
	s_nop 0
	global_load_dwordx4 v[132:135], v132, s[44:45]
	v_cmp_lt_i32_e32 vcc, v148, v138
	s_nop 1
	v_cndmask_b32_e32 v138, v214, v148, vcc
	v_lshlrev_b32_e32 v138, 2, v138
	ds_bpermute_b32 v138, v138, v140
	s_waitcnt lgkmcnt(0)
	v_add_f32_e32 v138, v140, v138
	v_fmamk_f32 v138, v138, 0x3c800000, v212
	v_rsq_f32_e32 v252, v138
	s_nop 0
	v_mul_f32_e32 v250, v138, v252
	v_fma_f32 v250, -v250, v252, 1.0
	v_mul_f32_e32 v251, 0.5, v252
	s_mov_b64 s[0:1], -1
	v_fma_f32 v138, v251, v250, v252
	v_mov_b32_e32 v148, v32
	v_mov_b32_e32 v149, v37
	v_mov_b32_e32 v150, v36
	v_mov_b32_e32 v151, v33
	v_pk_mul_f32 v[148:149], v[148:149], v[138:139] op_sel_hi:[1,0]
	v_pk_mul_f32 v[150:151], v[150:151], v[138:139] op_sel_hi:[1,0]
	s_and_b64 vcc, exec, s[12:13]
	v_pk_mul_f32 v[182:183], v[142:143], v[150:151]
	v_pk_mul_f32 v[142:143], v[4:5], v[148:149]
	v_mov_b32_e32 v4, v34
	v_mov_b32_e32 v5, v39
	v_mov_b32_e32 v148, v38
	v_mov_b32_e32 v149, v35
	v_pk_mul_f32 v[4:5], v[4:5], v[138:139] op_sel_hi:[1,0]
	v_pk_mul_f32 v[148:149], v[148:149], v[138:139] op_sel_hi:[1,0]
	s_nop 0
	v_pk_mul_f32 v[150:151], v[144:145], v[148:149]
	v_pk_mul_f32 v[144:145], v[2:3], v[4:5]
	v_mov_b32_e32 v2, v28
	v_mov_b32_e32 v3, v25
	v_mov_b32_e32 v4, v24
	v_mov_b32_e32 v5, v29
	v_pk_mul_f32 v[2:3], v[2:3], v[138:139] op_sel_hi:[1,0]
	v_pk_mul_f32 v[4:5], v[4:5], v[138:139] op_sel_hi:[1,0]
	s_nop 0
	v_pk_mul_f32 v[148:149], v[146:147], v[4:5]
	v_pk_mul_f32 v[146:147], v[0:1], v[2:3]
	v_mul_f32_e32 v0, v30, v138
	v_mul_f32_e32 v192, v141, v0
	v_mov_b32_e32 v0, v27
	v_mov_b32_e32 v1, v31
	v_pk_mul_f32 v[0:1], v[0:1], v[138:139] op_sel_hi:[1,0]
	s_nop 0
	v_pk_mul_f32 v[140:141], v[6:7], v[0:1]
	s_cbranch_vccnz .LBB0_517
	ds_bpermute_b32 v0, v184, v142
	ds_bpermute_b32 v1, v184, v183
	ds_bpermute_b32 v2, v184, v144
	ds_bpermute_b32 v3, v184, v151
	ds_bpermute_b32 v4, v184, v146
	ds_bpermute_b32 v5, v184, v149
	ds_bpermute_b32 v6, v184, v192
	ds_bpermute_b32 v7, v184, v141
	s_waitcnt vmcnt(0) lgkmcnt(7)
	v_mul_f32_e32 v0, v133, v0
	s_waitcnt lgkmcnt(6)
	v_mul_f32_e32 v1, v135, v1
	s_waitcnt lgkmcnt(5)
	v_mul_f32_e32 v2, v129, v2
	s_waitcnt lgkmcnt(4)
	v_mul_f32_e32 v3, v131, v3
	s_waitcnt lgkmcnt(3)
	v_mul_f32_e32 v4, v125, v4
	s_waitcnt lgkmcnt(2)
	v_mul_f32_e32 v5, v127, v5
	s_waitcnt lgkmcnt(1)
	v_mul_f32_e32 v6, v121, v6
	s_waitcnt lgkmcnt(0)
	v_mul_f32_e32 v7, v123, v7
	v_cndmask_b32_e64 v0, v0, -v0, s[6:7]
	v_cndmask_b32_e64 v1, v1, -v1, s[6:7]
	v_cndmask_b32_e64 v2, v2, -v2, s[6:7]
	v_cndmask_b32_e64 v3, v3, -v3, s[6:7]
	v_cndmask_b32_e64 v4, v4, -v4, s[6:7]
	v_cndmask_b32_e64 v5, v5, -v5, s[6:7]
	v_cndmask_b32_e64 v6, v6, -v6, s[6:7]
	v_cndmask_b32_e64 v7, v7, -v7, s[6:7]
	v_fmac_f32_e32 v0, v132, v142
	v_fmac_f32_e32 v1, v134, v183
	v_fmac_f32_e32 v2, v128, v144
	v_fmac_f32_e32 v3, v130, v151
	v_fmac_f32_e32 v4, v124, v146
	v_fmac_f32_e32 v5, v126, v149
	v_fmac_f32_e32 v6, v120, v192
	v_fmac_f32_e32 v7, v122, v141
	v_cndmask_b32_e64 v0, v142, v0, s[8:9]
	v_cndmask_b32_e64 v1, v183, v1, s[8:9]
	v_cndmask_b32_e64 v2, v144, v2, s[8:9]
	v_cndmask_b32_e64 v3, v151, v3, s[8:9]
	v_cndmask_b32_e64 v4, v146, v4, s[8:9]
	v_cndmask_b32_e64 v5, v149, v5, s[8:9]
	v_cndmask_b32_e64 v6, v192, v6, s[8:9]
	v_cndmask_b32_e64 v7, v141, v7, s[8:9]
	s_mov_b64 s[0:1], 0
	v_mov_b32_e32 v185, v140
	v_mov_b32_e32 v191, v147
	v_mov_b32_e32 v190, v148
	v_mov_b32_e32 v189, v145
	v_mov_b32_e32 v188, v150
	v_mov_b32_e32 v187, v143
	v_mov_b32_e32 v186, v182

;     __device__ __forceinline__ void operator()(const f32x4 (&acc)[2][2][4][2], const Unit& u, int wr, int wc, int fr, int fq) const {
;     ...
;                 const int row = row0 + ai * HALF + m * 16;
;                 const float rs = rstd_of(ssq, row);
;                 float lo[8], hi[8];
; #pragma unroll
;                 for (int n = 0; n < 2; ++n)
; #pragma unroll
;                     for (int e = 0; e < 4; ++e) { lo[4 * n + e] = acc[ai][0][m][n][e] * rs; hi[4 * n + e] = acc[ai][1][m][n][e] * rs; }
;                 if (type != 0) {
;                     float ss = 0.f;
; #pragma unroll
;                     for (int k = 0; k < 8; ++k) ss += lo[k] * lo[k] + hi[k] * hi[k];
;                     ss += __shfl_xor(ss, 16); ss += __shfl_xor(ss, 32);
;                     const float rn = 1.0f / sqrtf(ss * (1.0f / 64.0f) + RMS_EPS);
; #pragma unroll
;                     for (int k = 0; k < 8; ++k) { lo[k] *= rn * g[k >> 2][k & 3]; hi[k] *= rn * g[2 + (k >> 2)][k & 3]; }
;                     const int t = (row < M_P) ? (row & 8191) : ((row - M_P) & 4095);
;                     const f32x4* rp = (const f32x4*)(rope + ((size_t)t * 40 + (type == 1 ? 8 * fq : 32)) * 2);
;                     const f32x4 c01 = rp[0], c23 = rp[1], c45 = rp[2], c67 = rp[3];
;                     const float cs[16] = {c01[0], c01[1], c01[2], c01[3], c23[0], c23[1], c23[2], c23[3], c45[0], c45[1], c45[2], c45[3], c67[0], c67[1], c67[2], c67[3]};
;                     if (type == 1) {
; #pragma unroll
;                         for (int k = 0; k < 8; ++k) { const float a = lo[k], b = hi[k]; lo[k] = a * cs[2 * k] - b * cs[2 * k + 1]; hi[k] = b * cs[2 * k] + a * cs[2 * k + 1]; }
;                     } else {
; #pragma unroll
;                         for (int k = 0; k < 8; ++k) { const float p = __shfl_xor(lo[k], 16); const float r = (fq == 0) ? lo[k] * cs[2 * k] - p * cs[2 * k + 1] : lo[k] * cs[2 * k] + p * cs[2 * k + 1]; lo[k] = (fq < 2) ? r : lo[k]; }
;                     }
; #pragma unroll
;                     for (int k = 0; k < 8; ++k) { lo[k] *= scale; hi[k] *= scale; }
;                 }
;                 u32x4 w0, w1;
;                 w0.x = cvt_pk_bf16(lo[0], lo[1]); w0.y = cvt_pk_bf16(lo[2], lo[3]); w0.z = cvt_pk_bf16(lo[4], lo[5]); w0.w = cvt_pk_bf16(lo[6], lo[7]);
.LBB0_521:
	v_cvt_pk_bf16_f32 v126, v126, v127
	v_cvt_pk_bf16_f32 v127, v124, v125
	s_waitcnt vmcnt(1)
	v_cvt_pk_bf16_f32 v128, v120, v121
	v_cvt_pk_bf16_f32 v129, v141, v7
	v_cvt_pk_bf16_f32 v4, v4, v5
	v_cvt_pk_bf16_f32 v5, v2, v3
	v_cvt_pk_bf16_f32 v6, v0, v1
	v_mad_i64_i32 v[0:1], s[0:1], s76, v173, 0
	v_lshl_add_u64 v[0:1], v[0:1], 1, v[136:137]
	v_cvt_pk_bf16_f32 v7, v139, v123
	global_store_dwordx4 v[0:1], v[126:129], off
	global_store_dwordx4 v[0:1], v[4:7], off offset:64
	global_load_dwordx4 v[0:3], v[174:175], off offset:512
	s_nop 0
	global_load_dwordx4 v[4:7], v[176:177], off offset:512
	v_or_b32_e32 v146, 32, v172
	s_waitcnt vmcnt(0)
	v_pk_add_f32 v[120:121], v[2:3], v[6:7]
	v_pk_add_f32 v[122:123], v[0:1], v[4:5]
	global_load_dwordx4 v[0:3], v[178:179], off offset:512
	global_load_dwordx4 v[4:7], v[180:181], off offset:512
	s_waitcnt vmcnt(0)
	v_pk_add_f32 v[2:3], v[2:3], v[6:7]
	v_pk_add_f32 v[0:1], v[0:1], v[4:5]
	v_pk_add_f32 v[2:3], v[120:121], v[2:3]
	v_pk_add_f32 v[0:1], v[122:123], v[0:1]
	s_nop 0
	v_pk_mov_b32 v[4:5], v[0:1], v[2:3] op_sel:[1,0]
	v_mov_b32_e32 v1, v3
	v_pk_add_f32 v[0:1], v[4:5], v[0:1]
	s_nop 0
	v_add_f32_e32 v0, v0, v1
	v_fmamk_f32 v0, v0, 0x3a800000, v212
	v_cmp_gt_f32_e32 vcc, s95, v0
	v_rsq_f32_e32 v252, v0
	s_nop 0
	v_mul_f32_e32 v250, v0, v252
	v_fma_f32 v250, -v250, v252, 1.0
	v_mul_f32_e32 v251, 0.5, v252
	v_fma_f32 v120, v251, v250, v252
	v_mov_b32_e32 v0, v116
	v_mov_b32_e32 v1, v113
	v_mov_b32_e32 v113, v117
	v_mov_b32_e32 v2, v118
	v_mov_b32_e32 v3, v115
	v_mov_b32_e32 v115, v119
	v_mov_b32_e32 v4, v108
	v_mov_b32_e32 v5, v105
	v_mov_b32_e32 v105, v109
	v_pk_mul_f32 v[0:1], v[0:1], v[120:121] op_sel_hi:[1,0]
	v_pk_mul_f32 v[6:7], v[112:113], v[120:121] op_sel_hi:[1,0]
	v_pk_mul_f32 v[2:3], v[2:3], v[120:121] op_sel_hi:[1,0]
	v_pk_mul_f32 v[122:123], v[114:115], v[120:121] op_sel_hi:[1,0]
	v_pk_mul_f32 v[4:5], v[4:5], v[120:121] op_sel_hi:[1,0]
	v_pk_mul_f32 v[130:131], v[104:105], v[120:121] op_sel_hi:[1,0]
	v_mul_f32_e32 v127, v110, v120
	v_mul_f32_e32 v121, v106, v120
	v_mov_b32_e32 v110, v107
	v_pk_mul_f32 v[124:125], v[110:111], v[120:121] op_sel_hi:[1,0]
	s_and_b64 vcc, exec, s[14:15]
	s_cbranch_vccnz .LBB0_527
	v_pk_mul_f32 v[104:105], v[6:7], v[6:7]
	v_pk_mul_f32 v[106:107], v[122:123], v[122:123]
	v_pk_fma_f32 v[104:105], v[0:1], v[0:1], v[104:105]
	v_pk_fma_f32 v[106:107], v[2:3], v[2:3], v[106:107]
	v_add_f32_e32 v104, v104, v105
	v_pk_mul_f32 v[108:109], v[130:131], v[130:131]
	v_add_f32_e32 v104, v106, v104
	v_pk_fma_f32 v[108:109], v[4:5], v[4:5], v[108:109]
	v_mov_b32_e32 v120, v124
	v_add_f32_e32 v104, v107, v104
	v_and_b32_e32 v106, 64, v214
	v_mov_b32_e32 v126, v125
	v_pk_mul_f32 v[110:111], v[120:121], v[120:121]
	v_add_f32_e32 v104, v108, v104
	v_xor_b32_e32 v105, 16, v214
	v_add_u32_e32 v120, 64, v106
	v_pk_fma_f32 v[110:111], v[126:127], v[126:127], v[110:111]
	v_add_f32_e32 v104, v109, v104
	v_cmp_lt_i32_e32 vcc, v105, v120
	v_add_f32_e32 v104, v111, v104
	v_add_f32_e32 v104, v110, v104
	v_cndmask_b32_e32 v105, v214, v105, vcc
	v_lshlrev_b32_e32 v126, 2, v105
	ds_bpermute_b32 v105, v126, v104
	v_cmp_gt_i32_e32 vcc, s86, v146
	v_xor_b32_e32 v129, 32, v214
	s_waitcnt lgkmcnt(0)
	v_add_f32_e32 v128, v104, v105
	v_cndmask_b32_e32 v104, v219, v220, vcc
	v_and_b32_e32 v104, v104, v146
	v_mul_u32_u24_e32 v104, 40, v104
	v_add_lshl_u32 v116, v223, v104, 3
	global_load_dwordx4 v[104:107], v116, s[44:45] offset:48
	global_load_dwordx4 v[108:111], v116, s[44:45] offset:32
	global_load_dwordx4 v[112:115], v116, s[44:45] offset:16
	s_nop 0
	global_load_dwordx4 v[116:119], v116, s[44:45]
	v_cmp_lt_i32_e32 vcc, v129, v120
	s_nop 1
	v_cndmask_b32_e32 v120, v214, v129, vcc
	v_lshlrev_b32_e32 v120, 2, v120
	ds_bpermute_b32 v120, v120, v128
	s_waitcnt lgkmcnt(0)
	v_add_f32_e32 v120, v128, v120
	v_fmamk_f32 v120, v120, 0x3c800000, v212
	v_rsq_f32_e32 v252, v120
	s_nop 0
	v_mul_f32_e32 v250, v120, v252
	v_fma_f32 v250, -v250, v252, 1.0
	v_mul_f32_e32 v251, 0.5, v252
	s_mov_b64 s[0:1], -1
	v_fma_f32 v120, v251, v250, v252
	v_mov_b32_e32 v128, v32
	v_mov_b32_e32 v129, v37
	v_mov_b32_e32 v132, v36
	v_mov_b32_e32 v133, v33
	v_pk_mul_f32 v[128:129], v[128:129], v[120:121] op_sel_hi:[1,0]
	v_pk_mul_f32 v[132:133], v[132:133], v[120:121] op_sel_hi:[1,0]
	v_pk_mul_f32 v[128:129], v[0:1], v[128:129]
	v_pk_mul_f32 v[138:139], v[6:7], v[132:133]
	v_mov_b32_e32 v0, v34
	v_mov_b32_e32 v1, v39
	v_mov_b32_e32 v6, v38
	v_mov_b32_e32 v7, v35
	v_pk_mul_f32 v[0:1], v[0:1], v[120:121] op_sel_hi:[1,0]
	v_pk_mul_f32 v[6:7], v[6:7], v[120:121] op_sel_hi:[1,0]
	s_and_b64 vcc, exec, s[12:13]
	v_pk_mul_f32 v[134:135], v[122:123], v[6:7]
	v_pk_mul_f32 v[122:123], v[2:3], v[0:1]
	v_mov_b32_e32 v0, v28
	v_mov_b32_e32 v1, v25
	v_mov_b32_e32 v2, v24
	v_mov_b32_e32 v3, v29
	v_pk_mul_f32 v[0:1], v[0:1], v[120:121] op_sel_hi:[1,0]
	v_pk_mul_f32 v[2:3], v[2:3], v[120:121] op_sel_hi:[1,0]
	s_nop 0
	v_pk_mul_f32 v[132:133], v[130:131], v[2:3]
	v_pk_mul_f32 v[130:131], v[4:5], v[0:1]
	v_mul_f32_e32 v0, v30, v120
	v_mul_f32_e32 v147, v127, v0
	v_mov_b32_e32 v0, v27
	v_mov_b32_e32 v1, v31
	v_pk_mul_f32 v[0:1], v[0:1], v[120:121] op_sel_hi:[1,0]
	s_nop 0
	v_pk_mul_f32 v[124:125], v[124:125], v[0:1]
	s_cbranch_vccnz .LBB0_524
	ds_bpermute_b32 v0, v126, v128
	ds_bpermute_b32 v1, v126, v139
	ds_bpermute_b32 v2, v126, v122
	ds_bpermute_b32 v3, v126, v135
	ds_bpermute_b32 v4, v126, v130
	ds_bpermute_b32 v5, v126, v133
	ds_bpermute_b32 v6, v126, v147
	ds_bpermute_b32 v7, v126, v125
	s_waitcnt vmcnt(0) lgkmcnt(7)
	v_mul_f32_e32 v0, v117, v0
	s_waitcnt lgkmcnt(6)
	v_mul_f32_e32 v1, v119, v1
	s_waitcnt lgkmcnt(5)
	v_mul_f32_e32 v2, v113, v2
	s_waitcnt lgkmcnt(4)
	v_mul_f32_e32 v3, v115, v3
	s_waitcnt lgkmcnt(3)
	v_mul_f32_e32 v4, v109, v4
	s_waitcnt lgkmcnt(2)
	v_mul_f32_e32 v5, v111, v5
	s_waitcnt lgkmcnt(1)
	v_mul_f32_e32 v6, v105, v6
	s_waitcnt lgkmcnt(0)
	v_mul_f32_e32 v7, v107, v7
	v_cndmask_b32_e64 v0, v0, -v0, s[6:7]
	v_cndmask_b32_e64 v1, v1, -v1, s[6:7]
	v_cndmask_b32_e64 v2, v2, -v2, s[6:7]
	v_cndmask_b32_e64 v3, v3, -v3, s[6:7]
	v_cndmask_b32_e64 v4, v4, -v4, s[6:7]
	v_cndmask_b32_e64 v5, v5, -v5, s[6:7]
	v_cndmask_b32_e64 v6, v6, -v6, s[6:7]
	v_cndmask_b32_e64 v7, v7, -v7, s[6:7]
	v_fmac_f32_e32 v0, v116, v128
	v_fmac_f32_e32 v1, v118, v139
	v_fmac_f32_e32 v2, v112, v122
	v_fmac_f32_e32 v3, v114, v135
	v_fmac_f32_e32 v4, v108, v130
	v_fmac_f32_e32 v5, v110, v133
	v_fmac_f32_e32 v6, v104, v147
	v_fmac_f32_e32 v7, v106, v125
	v_cndmask_b32_e64 v0, v128, v0, s[8:9]
	v_cndmask_b32_e64 v1, v139, v1, s[8:9]
	v_cndmask_b32_e64 v2, v122, v2, s[8:9]
	v_cndmask_b32_e64 v3, v135, v3, s[8:9]
	v_cndmask_b32_e64 v4, v130, v4, s[8:9]
	v_cndmask_b32_e64 v5, v133, v5, s[8:9]
	v_cndmask_b32_e64 v6, v147, v6, s[8:9]
	v_cndmask_b32_e64 v7, v125, v7, s[8:9]
	s_mov_b64 s[0:1], 0
	v_mov_b32_e32 v127, v124
	v_mov_b32_e32 v145, v131
	v_mov_b32_e32 v144, v132
	v_mov_b32_e32 v143, v123
	v_mov_b32_e32 v142, v134
	v_mov_b32_e32 v141, v129
	v_mov_b32_e32 v140, v138

;     __device__ __forceinline__ void operator()(const f32x4 (&acc)[2][2][4][2], const Unit& u, int wr, int wc, int fr, int fq) const {
;     ...
;                 const int row = row0 + ai * HALF + m * 16;
;                 const float rs = rstd_of(ssq, row);
;                 float lo[8], hi[8];
; #pragma unroll
;                 for (int n = 0; n < 2; ++n)
; #pragma unroll
;                     for (int e = 0; e < 4; ++e) { lo[4 * n + e] = acc[ai][0][m][n][e] * rs; hi[4 * n + e] = acc[ai][1][m][n][e] * rs; }
;                 if (type != 0) {
;                     float ss = 0.f;
; #pragma unroll
;                     for (int k = 0; k < 8; ++k) ss += lo[k] * lo[k] + hi[k] * hi[k];
;                     ss += __shfl_xor(ss, 16); ss += __shfl_xor(ss, 32);
;                     const float rn = 1.0f / sqrtf(ss * (1.0f / 64.0f) + RMS_EPS);
; #pragma unroll
;                     for (int k = 0; k < 8; ++k) { lo[k] *= rn * g[k >> 2][k & 3]; hi[k] *= rn * g[2 + (k >> 2)][k & 3]; }
;                     const int t = (row < M_P) ? (row & 8191) : ((row - M_P) & 4095);
;                     const f32x4* rp = (const f32x4*)(rope + ((size_t)t * 40 + (type == 1 ? 8 * fq : 32)) * 2);
;                     const f32x4 c01 = rp[0], c23 = rp[1], c45 = rp[2], c67 = rp[3];
;                     const float cs[16] = {c01[0], c01[1], c01[2], c01[3], c23[0], c23[1], c23[2], c23[3], c45[0], c45[1], c45[2], c45[3], c67[0], c67[1], c67[2], c67[3]};
;                     if (type == 1) {
; #pragma unroll
;                         for (int k = 0; k < 8; ++k) { const float a = lo[k], b = hi[k]; lo[k] = a * cs[2 * k] - b * cs[2 * k + 1]; hi[k] = b * cs[2 * k] + a * cs[2 * k + 1]; }
;                     } else {
; #pragma unroll
;                         for (int k = 0; k < 8; ++k) { const float p = __shfl_xor(lo[k], 16); const float r = (fq == 0) ? lo[k] * cs[2 * k] - p * cs[2 * k + 1] : lo[k] * cs[2 * k] + p * cs[2 * k + 1]; lo[k] = (fq < 2) ? r : lo[k]; }
;                     }
; #pragma unroll
;                     for (int k = 0; k < 8; ++k) { lo[k] *= scale; hi[k] *= scale; }
;                 }
;                 u32x4 w0, w1;
;                 w0.x = cvt_pk_bf16(lo[0], lo[1]); w0.y = cvt_pk_bf16(lo[2], lo[3]); w0.z = cvt_pk_bf16(lo[4], lo[5]); w0.w = cvt_pk_bf16(lo[6], lo[7]);
.LBB0_528:
	v_cvt_pk_bf16_f32 v108, v108, v109
	v_cvt_pk_bf16_f32 v109, v106, v107
	v_cvt_pk_bf16_f32 v110, v104, v105
	v_cvt_pk_bf16_f32 v111, v127, v125
	v_cvt_pk_bf16_f32 v0, v0, v1
	v_cvt_pk_bf16_f32 v1, v2, v3
	v_cvt_pk_bf16_f32 v2, v4, v5
	v_mad_i64_i32 v[4:5], s[0:1], s76, v146, 0
	v_lshl_add_u64 v[4:5], v[4:5], 1, v[136:137]
	v_cvt_pk_bf16_f32 v3, v121, v7
	global_store_dwordx4 v[4:5], v[108:111], off
	global_store_dwordx4 v[4:5], v[0:3], off offset:64
	global_load_dwordx4 v[0:3], v[174:175], off offset:768
	s_nop 0
	global_load_dwordx4 v[4:7], v[176:177], off offset:768
	v_or_b32_e32 v128, 48, v172
	s_waitcnt vmcnt(0)
	v_pk_add_f32 v[104:105], v[2:3], v[6:7]
	v_pk_add_f32 v[106:107], v[0:1], v[4:5]
	global_load_dwordx4 v[0:3], v[178:179], off offset:768
	global_load_dwordx4 v[4:7], v[180:181], off offset:768
	s_waitcnt vmcnt(0)
	v_pk_add_f32 v[2:3], v[2:3], v[6:7]
	v_pk_add_f32 v[0:1], v[0:1], v[4:5]
	v_pk_add_f32 v[2:3], v[104:105], v[2:3]
	v_pk_add_f32 v[0:1], v[106:107], v[0:1]
	s_nop 0
	v_pk_mov_b32 v[4:5], v[0:1], v[2:3] op_sel:[1,0]
	v_mov_b32_e32 v1, v3
	v_pk_add_f32 v[0:1], v[4:5], v[0:1]
	s_nop 0
	v_add_f32_e32 v0, v0, v1
	v_fmamk_f32 v0, v0, 0x3a800000, v212
	v_cmp_gt_f32_e32 vcc, s95, v0
	v_rsq_f32_e32 v252, v0
	s_nop 0
	v_mul_f32_e32 v250, v0, v252
	v_fma_f32 v250, -v250, v252, 1.0
	v_mul_f32_e32 v251, 0.5, v252
	v_fma_f32 v104, v251, v250, v252
	v_mov_b32_e32 v0, v100
	v_mov_b32_e32 v1, v97
	v_mov_b32_e32 v97, v101
	v_mov_b32_e32 v2, v102
	v_mov_b32_e32 v3, v99
	v_mov_b32_e32 v99, v103
	v_mov_b32_e32 v4, v92
	v_mov_b32_e32 v5, v89
	v_mov_b32_e32 v89, v93
	v_pk_mul_f32 v[0:1], v[0:1], v[104:105] op_sel_hi:[1,0]
	v_pk_mul_f32 v[6:7], v[96:97], v[104:105] op_sel_hi:[1,0]
	v_pk_mul_f32 v[2:3], v[2:3], v[104:105] op_sel_hi:[1,0]
	v_pk_mul_f32 v[106:107], v[98:99], v[104:105] op_sel_hi:[1,0]
	v_pk_mul_f32 v[4:5], v[4:5], v[104:105] op_sel_hi:[1,0]
	v_pk_mul_f32 v[114:115], v[88:89], v[104:105] op_sel_hi:[1,0]
	v_mul_f32_e32 v111, v94, v104
	v_mul_f32_e32 v105, v90, v104
	v_mov_b32_e32 v94, v91
	v_pk_mul_f32 v[108:109], v[94:95], v[104:105] op_sel_hi:[1,0]
	s_and_b64 vcc, exec, s[14:15]
	s_cbranch_vccnz .LBB0_534
	v_pk_mul_f32 v[88:89], v[6:7], v[6:7]
	v_pk_mul_f32 v[90:91], v[106:107], v[106:107]
	v_pk_fma_f32 v[88:89], v[0:1], v[0:1], v[88:89]
	v_pk_fma_f32 v[90:91], v[2:3], v[2:3], v[90:91]
	v_add_f32_e32 v88, v88, v89
	v_pk_mul_f32 v[92:93], v[114:115], v[114:115]
	v_add_f32_e32 v88, v90, v88
	v_pk_fma_f32 v[92:93], v[4:5], v[4:5], v[92:93]
	v_mov_b32_e32 v104, v108
	v_add_f32_e32 v88, v91, v88
	v_and_b32_e32 v90, 64, v214
	v_mov_b32_e32 v110, v109
	v_pk_mul_f32 v[94:95], v[104:105], v[104:105]
	v_add_f32_e32 v88, v92, v88
	v_xor_b32_e32 v89, 16, v214
	v_add_u32_e32 v104, 64, v90
	v_pk_fma_f32 v[94:95], v[110:111], v[110:111], v[94:95]
	v_add_f32_e32 v88, v93, v88
	v_cmp_lt_i32_e32 vcc, v89, v104
	v_add_f32_e32 v88, v95, v88
	v_add_f32_e32 v88, v94, v88
	v_cndmask_b32_e32 v89, v214, v89, vcc
	v_lshlrev_b32_e32 v110, 2, v89
	ds_bpermute_b32 v89, v110, v88
	v_cmp_gt_i32_e32 vcc, s86, v128
	v_xor_b32_e32 v113, 32, v214
	s_waitcnt lgkmcnt(0)
	v_add_f32_e32 v112, v88, v89
	v_cndmask_b32_e32 v88, v221, v222, vcc
	v_and_b32_e32 v88, v88, v128
	v_mul_u32_u24_e32 v88, 40, v88
	v_add_lshl_u32 v100, v223, v88, 3
	global_load_dwordx4 v[88:91], v100, s[44:45] offset:48
	global_load_dwordx4 v[92:95], v100, s[44:45] offset:32
	global_load_dwordx4 v[96:99], v100, s[44:45] offset:16
	s_nop 0
	global_load_dwordx4 v[100:103], v100, s[44:45]
	v_cmp_lt_i32_e32 vcc, v113, v104
	s_nop 1
	v_cndmask_b32_e32 v104, v214, v113, vcc
	v_lshlrev_b32_e32 v104, 2, v104
	ds_bpermute_b32 v104, v104, v112
	s_waitcnt lgkmcnt(0)
	v_add_f32_e32 v104, v112, v104
	v_fmamk_f32 v104, v104, 0x3c800000, v212
	v_rsq_f32_e32 v252, v104
	s_nop 0
	v_mul_f32_e32 v250, v104, v252
	v_fma_f32 v250, -v250, v252, 1.0
	v_mul_f32_e32 v251, 0.5, v252
	s_mov_b64 s[0:1], -1
	v_fma_f32 v104, v251, v250, v252
	v_mov_b32_e32 v112, v32
	v_mov_b32_e32 v113, v37
	v_mov_b32_e32 v116, v36
	v_mov_b32_e32 v117, v33
	v_pk_mul_f32 v[112:113], v[112:113], v[104:105] op_sel_hi:[1,0]
	v_pk_mul_f32 v[116:117], v[116:117], v[104:105] op_sel_hi:[1,0]
	v_pk_mul_f32 v[112:113], v[0:1], v[112:113]
	v_pk_mul_f32 v[120:121], v[6:7], v[116:117]
	v_mov_b32_e32 v0, v34
	v_mov_b32_e32 v1, v39
	v_mov_b32_e32 v6, v38
	v_mov_b32_e32 v7, v35
	v_pk_mul_f32 v[0:1], v[0:1], v[104:105] op_sel_hi:[1,0]
	v_pk_mul_f32 v[6:7], v[6:7], v[104:105] op_sel_hi:[1,0]
	s_and_b64 vcc, exec, s[12:13]
	v_pk_mul_f32 v[118:119], v[106:107], v[6:7]
	v_pk_mul_f32 v[106:107], v[2:3], v[0:1]
	v_mov_b32_e32 v0, v28
	v_mov_b32_e32 v1, v25
	v_mov_b32_e32 v2, v24
	v_mov_b32_e32 v3, v29
	v_pk_mul_f32 v[0:1], v[0:1], v[104:105] op_sel_hi:[1,0]
	v_pk_mul_f32 v[2:3], v[2:3], v[104:105] op_sel_hi:[1,0]
	s_nop 0
	v_pk_mul_f32 v[116:117], v[114:115], v[2:3]
	v_pk_mul_f32 v[114:115], v[4:5], v[0:1]
	v_mul_f32_e32 v0, v30, v104
	v_mul_f32_e32 v129, v111, v0
	v_mov_b32_e32 v0, v27
	v_mov_b32_e32 v1, v31
	v_pk_mul_f32 v[0:1], v[0:1], v[104:105] op_sel_hi:[1,0]
	s_nop 0
	v_pk_mul_f32 v[108:109], v[108:109], v[0:1]
	s_cbranch_vccnz .LBB0_531
	ds_bpermute_b32 v0, v110, v112
	ds_bpermute_b32 v1, v110, v121
	ds_bpermute_b32 v2, v110, v106
	ds_bpermute_b32 v3, v110, v119
	ds_bpermute_b32 v4, v110, v114
	ds_bpermute_b32 v5, v110, v117
	ds_bpermute_b32 v6, v110, v129
	ds_bpermute_b32 v7, v110, v109
	s_waitcnt vmcnt(0) lgkmcnt(7)
	v_mul_f32_e32 v0, v101, v0
	s_waitcnt lgkmcnt(6)
	v_mul_f32_e32 v1, v103, v1
	s_waitcnt lgkmcnt(5)
	v_mul_f32_e32 v2, v97, v2
	s_waitcnt lgkmcnt(4)
	v_mul_f32_e32 v3, v99, v3
	s_waitcnt lgkmcnt(3)
	v_mul_f32_e32 v4, v93, v4
	s_waitcnt lgkmcnt(2)
	v_mul_f32_e32 v5, v95, v5
	s_waitcnt lgkmcnt(1)
	v_mul_f32_e32 v6, v89, v6
	s_waitcnt lgkmcnt(0)
	v_mul_f32_e32 v7, v91, v7
	v_cndmask_b32_e64 v0, v0, -v0, s[6:7]
	v_cndmask_b32_e64 v1, v1, -v1, s[6:7]
	v_cndmask_b32_e64 v2, v2, -v2, s[6:7]
	v_cndmask_b32_e64 v3, v3, -v3, s[6:7]
	v_cndmask_b32_e64 v4, v4, -v4, s[6:7]
	v_cndmask_b32_e64 v5, v5, -v5, s[6:7]
	v_cndmask_b32_e64 v6, v6, -v6, s[6:7]
	v_cndmask_b32_e64 v7, v7, -v7, s[6:7]
	v_fmac_f32_e32 v0, v100, v112
	v_fmac_f32_e32 v1, v102, v121
	v_fmac_f32_e32 v2, v96, v106
	v_fmac_f32_e32 v3, v98, v119
	v_fmac_f32_e32 v4, v92, v114
	v_fmac_f32_e32 v5, v94, v117
	v_fmac_f32_e32 v6, v88, v129
	v_fmac_f32_e32 v7, v90, v109
	v_cndmask_b32_e64 v0, v112, v0, s[8:9]
	v_cndmask_b32_e64 v1, v121, v1, s[8:9]
	v_cndmask_b32_e64 v2, v106, v2, s[8:9]
	v_cndmask_b32_e64 v3, v119, v3, s[8:9]
	v_cndmask_b32_e64 v4, v114, v4, s[8:9]
	v_cndmask_b32_e64 v5, v117, v5, s[8:9]
	v_cndmask_b32_e64 v6, v129, v6, s[8:9]
	v_cndmask_b32_e64 v7, v109, v7, s[8:9]
	s_mov_b64 s[0:1], 0
	v_mov_b32_e32 v111, v108
	v_mov_b32_e32 v127, v115
	v_mov_b32_e32 v126, v116
	v_mov_b32_e32 v125, v107
	v_mov_b32_e32 v124, v118
	v_mov_b32_e32 v123, v113
	v_mov_b32_e32 v122, v120

;     __device__ __forceinline__ void operator()(const f32x4 (&acc)[2][2][4][2], const Unit& u, int wr, int wc, int fr, int fq) const {
;     ...
;                 const int row = row0 + ai * HALF + m * 16;
;                 const float rs = rstd_of(ssq, row);
;                 float lo[8], hi[8];
; #pragma unroll
;                 for (int n = 0; n < 2; ++n)
; #pragma unroll
;                     for (int e = 0; e < 4; ++e) { lo[4 * n + e] = acc[ai][0][m][n][e] * rs; hi[4 * n + e] = acc[ai][1][m][n][e] * rs; }
;                 if (type != 0) {
;                     float ss = 0.f;
; #pragma unroll
;                     for (int k = 0; k < 8; ++k) ss += lo[k] * lo[k] + hi[k] * hi[k];
;                     ss += __shfl_xor(ss, 16); ss += __shfl_xor(ss, 32);
;                     const float rn = 1.0f / sqrtf(ss * (1.0f / 64.0f) + RMS_EPS);
; #pragma unroll
;                     for (int k = 0; k < 8; ++k) { lo[k] *= rn * g[k >> 2][k & 3]; hi[k] *= rn * g[2 + (k >> 2)][k & 3]; }
;                     const int t = (row < M_P) ? (row & 8191) : ((row - M_P) & 4095);
;                     const f32x4* rp = (const f32x4*)(rope + ((size_t)t * 40 + (type == 1 ? 8 * fq : 32)) * 2);
;                     const f32x4 c01 = rp[0], c23 = rp[1], c45 = rp[2], c67 = rp[3];
;                     const float cs[16] = {c01[0], c01[1], c01[2], c01[3], c23[0], c23[1], c23[2], c23[3], c45[0], c45[1], c45[2], c45[3], c67[0], c67[1], c67[2], c67[3]};
;                     if (type == 1) {
; #pragma unroll
;                         for (int k = 0; k < 8; ++k) { const float a = lo[k], b = hi[k]; lo[k] = a * cs[2 * k] - b * cs[2 * k + 1]; hi[k] = b * cs[2 * k] + a * cs[2 * k + 1]; }
;                     } else {
; #pragma unroll
;                         for (int k = 0; k < 8; ++k) { const float p = __shfl_xor(lo[k], 16); const float r = (fq == 0) ? lo[k] * cs[2 * k] - p * cs[2 * k + 1] : lo[k] * cs[2 * k] + p * cs[2 * k + 1]; lo[k] = (fq < 2) ? r : lo[k]; }
;                     }
; #pragma unroll
;                     for (int k = 0; k < 8; ++k) { lo[k] *= scale; hi[k] *= scale; }
;                 }
;                 u32x4 w0, w1;
;                 w0.x = cvt_pk_bf16(lo[0], lo[1]); w0.y = cvt_pk_bf16(lo[2], lo[3]); w0.z = cvt_pk_bf16(lo[4], lo[5]); w0.w = cvt_pk_bf16(lo[6], lo[7]);
.LBB0_535:
	v_cvt_pk_bf16_f32 v92, v92, v93
	v_cvt_pk_bf16_f32 v93, v90, v91
	v_cvt_pk_bf16_f32 v94, v88, v89
	v_cvt_pk_bf16_f32 v95, v111, v109
	v_cvt_pk_bf16_f32 v0, v0, v1
	v_cvt_pk_bf16_f32 v1, v2, v3
	v_cvt_pk_bf16_f32 v2, v4, v5
	v_mad_i64_i32 v[4:5], s[0:1], s76, v128, 0
	v_lshl_add_u64 v[4:5], v[4:5], 1, v[136:137]
	v_cvt_pk_bf16_f32 v3, v105, v7
	global_store_dwordx4 v[4:5], v[92:95], off
	global_store_dwordx4 v[4:5], v[0:3], off offset:64
	global_load_dwordx4 v[0:3], v[174:175], off offset:2048
	s_nop 0
	global_load_dwordx4 v[4:7], v[176:177], off offset:2048
	v_add_u32_e32 v112, 0x80, v172
	s_waitcnt vmcnt(0)
	v_pk_add_f32 v[88:89], v[2:3], v[6:7]
	v_pk_add_f32 v[90:91], v[0:1], v[4:5]
	global_load_dwordx4 v[0:3], v[178:179], off offset:2048
	global_load_dwordx4 v[4:7], v[180:181], off offset:2048
	s_waitcnt vmcnt(0)
	v_pk_add_f32 v[2:3], v[2:3], v[6:7]
	v_pk_add_f32 v[0:1], v[0:1], v[4:5]
	v_pk_add_f32 v[2:3], v[88:89], v[2:3]
	v_pk_add_f32 v[0:1], v[90:91], v[0:1]
	s_nop 0
	v_pk_mov_b32 v[4:5], v[0:1], v[2:3] op_sel:[1,0]
	v_mov_b32_e32 v1, v3
	v_pk_add_f32 v[0:1], v[4:5], v[0:1]
	s_nop 0
	v_add_f32_e32 v0, v0, v1
	v_fmamk_f32 v0, v0, 0x3a800000, v212
	v_cmp_gt_f32_e32 vcc, s95, v0
	v_rsq_f32_e32 v252, v0
	s_nop 0
	v_mul_f32_e32 v250, v0, v252
	v_fma_f32 v250, -v250, v252, 1.0
	v_mul_f32_e32 v251, 0.5, v252
	v_fma_f32 v88, v251, v250, v252
	v_mov_b32_e32 v0, v84
	v_mov_b32_e32 v1, v81
	v_mov_b32_e32 v81, v85
	v_mov_b32_e32 v2, v86
	v_mov_b32_e32 v3, v83
	v_mov_b32_e32 v83, v87
	v_mov_b32_e32 v4, v76
	v_mov_b32_e32 v5, v73
	v_mov_b32_e32 v73, v77
	v_pk_mul_f32 v[0:1], v[0:1], v[88:89] op_sel_hi:[1,0]
	v_pk_mul_f32 v[6:7], v[80:81], v[88:89] op_sel_hi:[1,0]
	v_pk_mul_f32 v[2:3], v[2:3], v[88:89] op_sel_hi:[1,0]
	v_pk_mul_f32 v[90:91], v[82:83], v[88:89] op_sel_hi:[1,0]
	v_pk_mul_f32 v[4:5], v[4:5], v[88:89] op_sel_hi:[1,0]
	v_pk_mul_f32 v[98:99], v[72:73], v[88:89] op_sel_hi:[1,0]
	v_mul_f32_e32 v95, v78, v88
	v_mul_f32_e32 v89, v74, v88
	v_mov_b32_e32 v78, v75
	v_pk_mul_f32 v[92:93], v[78:79], v[88:89] op_sel_hi:[1,0]
	s_and_b64 vcc, exec, s[14:15]
	s_cbranch_vccnz .LBB0_541
	v_pk_mul_f32 v[72:73], v[6:7], v[6:7]
	v_pk_mul_f32 v[74:75], v[90:91], v[90:91]
	v_pk_fma_f32 v[72:73], v[0:1], v[0:1], v[72:73]
	v_pk_fma_f32 v[74:75], v[2:3], v[2:3], v[74:75]
	v_add_f32_e32 v72, v72, v73
	v_pk_mul_f32 v[76:77], v[98:99], v[98:99]
	v_add_f32_e32 v72, v74, v72
	v_pk_fma_f32 v[76:77], v[4:5], v[4:5], v[76:77]
	v_mov_b32_e32 v88, v92
	v_add_f32_e32 v72, v75, v72
	v_and_b32_e32 v74, 64, v214
	v_mov_b32_e32 v94, v93
	v_pk_mul_f32 v[78:79], v[88:89], v[88:89]
	v_add_f32_e32 v72, v76, v72
	v_xor_b32_e32 v73, 16, v214
	v_add_u32_e32 v88, 64, v74
	v_pk_fma_f32 v[78:79], v[94:95], v[94:95], v[78:79]
	v_add_f32_e32 v72, v77, v72
	v_cmp_lt_i32_e32 vcc, v73, v88
	v_add_f32_e32 v72, v79, v72
	v_add_f32_e32 v72, v78, v72
	v_cndmask_b32_e32 v73, v214, v73, vcc
	v_lshlrev_b32_e32 v94, 2, v73
	ds_bpermute_b32 v73, v94, v72
	s_movk_i32 s0, 0x3f80
	v_cmp_gt_i32_e32 vcc, s0, v172
	v_xor_b32_e32 v97, 32, v214
	s_waitcnt lgkmcnt(0)
	v_add_f32_e32 v96, v72, v73
	v_cndmask_b32_e32 v72, v215, v216, vcc
	v_and_b32_e32 v72, v72, v112
	v_mul_u32_u24_e32 v72, 40, v72
	v_add_lshl_u32 v84, v223, v72, 3
	global_load_dwordx4 v[72:75], v84, s[44:45] offset:48
	global_load_dwordx4 v[76:79], v84, s[44:45] offset:32
	global_load_dwordx4 v[80:83], v84, s[44:45] offset:16
	s_nop 0
	global_load_dwordx4 v[84:87], v84, s[44:45]
	v_cmp_lt_i32_e32 vcc, v97, v88
	s_nop 1
	v_cndmask_b32_e32 v88, v214, v97, vcc
	v_lshlrev_b32_e32 v88, 2, v88
	ds_bpermute_b32 v88, v88, v96
	s_waitcnt lgkmcnt(0)
	v_add_f32_e32 v88, v96, v88
	v_fmamk_f32 v88, v88, 0x3c800000, v212
	v_rsq_f32_e32 v252, v88
	s_nop 0
	v_mul_f32_e32 v250, v88, v252
	v_fma_f32 v250, -v250, v252, 1.0
	v_mul_f32_e32 v251, 0.5, v252
	s_mov_b64 s[0:1], -1
	v_fma_f32 v88, v251, v250, v252
	v_mov_b32_e32 v96, v32
	v_mov_b32_e32 v97, v37
	v_mov_b32_e32 v100, v36
	v_mov_b32_e32 v101, v33
	v_pk_mul_f32 v[96:97], v[96:97], v[88:89] op_sel_hi:[1,0]
	v_pk_mul_f32 v[100:101], v[100:101], v[88:89] op_sel_hi:[1,0]
	v_pk_mul_f32 v[96:97], v[0:1], v[96:97]
	v_pk_mul_f32 v[104:105], v[6:7], v[100:101]
	v_mov_b32_e32 v0, v34
	v_mov_b32_e32 v1, v39
	v_mov_b32_e32 v6, v38
	v_mov_b32_e32 v7, v35
	v_pk_mul_f32 v[0:1], v[0:1], v[88:89] op_sel_hi:[1,0]
	v_pk_mul_f32 v[6:7], v[6:7], v[88:89] op_sel_hi:[1,0]
	s_and_b64 vcc, exec, s[12:13]
	v_pk_mul_f32 v[102:103], v[90:91], v[6:7]
	v_pk_mul_f32 v[90:91], v[2:3], v[0:1]
	v_mov_b32_e32 v0, v28
	v_mov_b32_e32 v1, v25
	v_mov_b32_e32 v2, v24
	v_mov_b32_e32 v3, v29
	v_pk_mul_f32 v[0:1], v[0:1], v[88:89] op_sel_hi:[1,0]
	v_pk_mul_f32 v[2:3], v[2:3], v[88:89] op_sel_hi:[1,0]
	s_nop 0
	v_pk_mul_f32 v[100:101], v[98:99], v[2:3]
	v_pk_mul_f32 v[98:99], v[4:5], v[0:1]
	v_mul_f32_e32 v0, v30, v88
	v_mul_f32_e32 v113, v95, v0
	v_mov_b32_e32 v0, v27
	v_mov_b32_e32 v1, v31
	v_pk_mul_f32 v[0:1], v[0:1], v[88:89] op_sel_hi:[1,0]
	s_nop 0
	v_pk_mul_f32 v[92:93], v[92:93], v[0:1]
	s_cbranch_vccnz .LBB0_538
	ds_bpermute_b32 v0, v94, v96
	ds_bpermute_b32 v1, v94, v105
	ds_bpermute_b32 v2, v94, v90
	ds_bpermute_b32 v3, v94, v103
	ds_bpermute_b32 v4, v94, v98
	ds_bpermute_b32 v5, v94, v101
	ds_bpermute_b32 v6, v94, v113
	ds_bpermute_b32 v7, v94, v93
	s_waitcnt vmcnt(0) lgkmcnt(7)
	v_mul_f32_e32 v0, v85, v0
	s_waitcnt lgkmcnt(6)
	v_mul_f32_e32 v1, v87, v1
	s_waitcnt lgkmcnt(5)
	v_mul_f32_e32 v2, v81, v2
	s_waitcnt lgkmcnt(4)
	v_mul_f32_e32 v3, v83, v3
	s_waitcnt lgkmcnt(3)
	v_mul_f32_e32 v4, v77, v4
	s_waitcnt lgkmcnt(2)
	v_mul_f32_e32 v5, v79, v5
	s_waitcnt lgkmcnt(1)
	v_mul_f32_e32 v6, v73, v6
	s_waitcnt lgkmcnt(0)
	v_mul_f32_e32 v7, v75, v7
	v_cndmask_b32_e64 v0, v0, -v0, s[6:7]
	v_cndmask_b32_e64 v1, v1, -v1, s[6:7]
	v_cndmask_b32_e64 v2, v2, -v2, s[6:7]
	v_cndmask_b32_e64 v3, v3, -v3, s[6:7]
	v_cndmask_b32_e64 v4, v4, -v4, s[6:7]
	v_cndmask_b32_e64 v5, v5, -v5, s[6:7]
	v_cndmask_b32_e64 v6, v6, -v6, s[6:7]
	v_cndmask_b32_e64 v7, v7, -v7, s[6:7]
	v_fmac_f32_e32 v0, v84, v96
	v_fmac_f32_e32 v1, v86, v105
	v_fmac_f32_e32 v2, v80, v90
	v_fmac_f32_e32 v3, v82, v103
	v_fmac_f32_e32 v4, v76, v98
	v_fmac_f32_e32 v5, v78, v101
	v_fmac_f32_e32 v6, v72, v113
	v_fmac_f32_e32 v7, v74, v93
	v_cndmask_b32_e64 v0, v96, v0, s[8:9]
	v_cndmask_b32_e64 v1, v105, v1, s[8:9]
	v_cndmask_b32_e64 v2, v90, v2, s[8:9]
	v_cndmask_b32_e64 v3, v103, v3, s[8:9]
	v_cndmask_b32_e64 v4, v98, v4, s[8:9]
	v_cndmask_b32_e64 v5, v101, v5, s[8:9]
	v_cndmask_b32_e64 v6, v113, v6, s[8:9]
	v_cndmask_b32_e64 v7, v93, v7, s[8:9]
	s_mov_b64 s[0:1], 0
	v_mov_b32_e32 v95, v92
	v_mov_b32_e32 v111, v99
	v_mov_b32_e32 v110, v100
	v_mov_b32_e32 v109, v91
	v_mov_b32_e32 v108, v102
	v_mov_b32_e32 v107, v97
	v_mov_b32_e32 v106, v104

;     __device__ __forceinline__ void operator()(const f32x4 (&acc)[2][2][4][2], const Unit& u, int wr, int wc, int fr, int fq) const {
;     ...
;                 const int row = row0 + ai * HALF + m * 16;
;                 const float rs = rstd_of(ssq, row);
;                 float lo[8], hi[8];
; #pragma unroll
;                 for (int n = 0; n < 2; ++n)
; #pragma unroll
;                     for (int e = 0; e < 4; ++e) { lo[4 * n + e] = acc[ai][0][m][n][e] * rs; hi[4 * n + e] = acc[ai][1][m][n][e] * rs; }
;                 if (type != 0) {
;                     float ss = 0.f;
; #pragma unroll
;                     for (int k = 0; k < 8; ++k) ss += lo[k] * lo[k] + hi[k] * hi[k];
;                     ss += __shfl_xor(ss, 16); ss += __shfl_xor(ss, 32);
;                     const float rn = 1.0f / sqrtf(ss * (1.0f / 64.0f) + RMS_EPS);
; #pragma unroll
;                     for (int k = 0; k < 8; ++k) { lo[k] *= rn * g[k >> 2][k & 3]; hi[k] *= rn * g[2 + (k >> 2)][k & 3]; }
;                     const int t = (row < M_P) ? (row & 8191) : ((row - M_P) & 4095);
;                     const f32x4* rp = (const f32x4*)(rope + ((size_t)t * 40 + (type == 1 ? 8 * fq : 32)) * 2);
;                     const f32x4 c01 = rp[0], c23 = rp[1], c45 = rp[2], c67 = rp[3];
;                     const float cs[16] = {c01[0], c01[1], c01[2], c01[3], c23[0], c23[1], c23[2], c23[3], c45[0], c45[1], c45[2], c45[3], c67[0], c67[1], c67[2], c67[3]};
;                     if (type == 1) {
; #pragma unroll
;                         for (int k = 0; k < 8; ++k) { const float a = lo[k], b = hi[k]; lo[k] = a * cs[2 * k] - b * cs[2 * k + 1]; hi[k] = b * cs[2 * k] + a * cs[2 * k + 1]; }
;                     } else {
; #pragma unroll
;                         for (int k = 0; k < 8; ++k) { const float p = __shfl_xor(lo[k], 16); const float r = (fq == 0) ? lo[k] * cs[2 * k] - p * cs[2 * k + 1] : lo[k] * cs[2 * k] + p * cs[2 * k + 1]; lo[k] = (fq < 2) ? r : lo[k]; }
;                     }
; #pragma unroll
;                     for (int k = 0; k < 8; ++k) { lo[k] *= scale; hi[k] *= scale; }
;                 }
;                 u32x4 w0, w1;
;                 w0.x = cvt_pk_bf16(lo[0], lo[1]); w0.y = cvt_pk_bf16(lo[2], lo[3]); w0.z = cvt_pk_bf16(lo[4], lo[5]); w0.w = cvt_pk_bf16(lo[6], lo[7]);
.LBB0_542:
	v_cvt_pk_bf16_f32 v76, v76, v77
	v_cvt_pk_bf16_f32 v77, v74, v75
	v_cvt_pk_bf16_f32 v78, v72, v73
	v_cvt_pk_bf16_f32 v79, v95, v93
	v_cvt_pk_bf16_f32 v0, v0, v1
	v_cvt_pk_bf16_f32 v1, v2, v3
	v_cvt_pk_bf16_f32 v2, v4, v5
	v_mad_i64_i32 v[4:5], s[0:1], s76, v112, 0
	v_lshl_add_u64 v[4:5], v[4:5], 1, v[136:137]
	v_cvt_pk_bf16_f32 v3, v89, v7
	global_store_dwordx4 v[4:5], v[76:79], off
	global_store_dwordx4 v[4:5], v[0:3], off offset:64
	global_load_dwordx4 v[0:3], v[174:175], off offset:2304
	s_nop 0
	global_load_dwordx4 v[4:7], v[176:177], off offset:2304
	v_add_u32_e32 v96, 0x90, v172
	s_waitcnt vmcnt(0)
	v_pk_add_f32 v[72:73], v[2:3], v[6:7]
	v_pk_add_f32 v[74:75], v[0:1], v[4:5]
	global_load_dwordx4 v[0:3], v[178:179], off offset:2304
	global_load_dwordx4 v[4:7], v[180:181], off offset:2304
	s_waitcnt vmcnt(0)
	v_pk_add_f32 v[2:3], v[2:3], v[6:7]
	v_pk_add_f32 v[0:1], v[0:1], v[4:5]
	v_pk_add_f32 v[2:3], v[72:73], v[2:3]
	v_pk_add_f32 v[0:1], v[74:75], v[0:1]
	s_nop 0
	v_pk_mov_b32 v[4:5], v[0:1], v[2:3] op_sel:[1,0]
	v_mov_b32_e32 v1, v3
	v_pk_add_f32 v[0:1], v[4:5], v[0:1]
	s_nop 0
	v_add_f32_e32 v0, v0, v1
	v_fmamk_f32 v0, v0, 0x3a800000, v212
	v_cmp_gt_f32_e32 vcc, s95, v0
	v_rsq_f32_e32 v252, v0
	s_nop 0
	v_mul_f32_e32 v250, v0, v252
	v_fma_f32 v250, -v250, v252, 1.0
	v_mul_f32_e32 v251, 0.5, v252
	v_fma_f32 v72, v251, v250, v252
	v_mov_b32_e32 v0, v68
	v_mov_b32_e32 v1, v65
	v_mov_b32_e32 v65, v69
	v_mov_b32_e32 v2, v70
	v_mov_b32_e32 v3, v67
	v_mov_b32_e32 v67, v71
	v_mov_b32_e32 v4, v60
	v_mov_b32_e32 v5, v57
	v_mov_b32_e32 v57, v61
	v_pk_mul_f32 v[0:1], v[0:1], v[72:73] op_sel_hi:[1,0]
	v_pk_mul_f32 v[6:7], v[64:65], v[72:73] op_sel_hi:[1,0]
	v_pk_mul_f32 v[2:3], v[2:3], v[72:73] op_sel_hi:[1,0]
	v_pk_mul_f32 v[74:75], v[66:67], v[72:73] op_sel_hi:[1,0]
	v_pk_mul_f32 v[4:5], v[4:5], v[72:73] op_sel_hi:[1,0]
	v_pk_mul_f32 v[82:83], v[56:57], v[72:73] op_sel_hi:[1,0]
	v_mul_f32_e32 v79, v62, v72
	v_mul_f32_e32 v73, v58, v72
	v_mov_b32_e32 v62, v59
	v_pk_mul_f32 v[76:77], v[62:63], v[72:73] op_sel_hi:[1,0]
	s_and_b64 vcc, exec, s[14:15]
	s_cbranch_vccnz .LBB0_548
	v_pk_mul_f32 v[56:57], v[6:7], v[6:7]
	v_pk_mul_f32 v[58:59], v[74:75], v[74:75]
	v_pk_fma_f32 v[56:57], v[0:1], v[0:1], v[56:57]
	v_pk_fma_f32 v[58:59], v[2:3], v[2:3], v[58:59]
	v_add_f32_e32 v56, v56, v57
	v_pk_mul_f32 v[60:61], v[82:83], v[82:83]
	v_add_f32_e32 v56, v58, v56
	v_pk_fma_f32 v[60:61], v[4:5], v[4:5], v[60:61]
	v_mov_b32_e32 v72, v76
	v_add_f32_e32 v56, v59, v56
	v_and_b32_e32 v58, 64, v214
	v_mov_b32_e32 v78, v77
	v_pk_mul_f32 v[62:63], v[72:73], v[72:73]
	v_add_f32_e32 v56, v60, v56
	v_xor_b32_e32 v57, 16, v214
	v_add_u32_e32 v72, 64, v58
	v_pk_fma_f32 v[62:63], v[78:79], v[78:79], v[62:63]
	v_add_f32_e32 v56, v61, v56
	v_cmp_lt_i32_e32 vcc, v57, v72
	v_add_f32_e32 v56, v63, v56
	v_add_f32_e32 v56, v62, v56
	v_cndmask_b32_e32 v57, v214, v57, vcc
	v_lshlrev_b32_e32 v78, 2, v57
	ds_bpermute_b32 v57, v78, v56
	s_movk_i32 s0, 0x3f70
	v_cmp_gt_i32_e32 vcc, s0, v172
	v_xor_b32_e32 v81, 32, v214
	s_waitcnt lgkmcnt(0)
	v_add_f32_e32 v80, v56, v57
	v_cndmask_b32_e32 v56, v217, v218, vcc
	v_and_b32_e32 v56, v56, v96
	v_mul_u32_u24_e32 v56, 40, v56
	v_add_lshl_u32 v68, v223, v56, 3
	global_load_dwordx4 v[56:59], v68, s[44:45] offset:48
	global_load_dwordx4 v[60:63], v68, s[44:45] offset:32
	global_load_dwordx4 v[64:67], v68, s[44:45] offset:16
	s_nop 0
	global_load_dwordx4 v[68:71], v68, s[44:45]
	v_cmp_lt_i32_e32 vcc, v81, v72
	s_nop 1
	v_cndmask_b32_e32 v72, v214, v81, vcc
	v_lshlrev_b32_e32 v72, 2, v72
	ds_bpermute_b32 v72, v72, v80
	s_waitcnt lgkmcnt(0)
	v_add_f32_e32 v72, v80, v72
	v_fmamk_f32 v72, v72, 0x3c800000, v212
	v_rsq_f32_e32 v252, v72
	s_nop 0
	v_mul_f32_e32 v250, v72, v252
	v_fma_f32 v250, -v250, v252, 1.0
	v_mul_f32_e32 v251, 0.5, v252
	s_mov_b64 s[0:1], -1
	v_fma_f32 v72, v251, v250, v252
	v_mov_b32_e32 v80, v32
	v_mov_b32_e32 v81, v37
	v_mov_b32_e32 v84, v36
	v_mov_b32_e32 v85, v33
	v_pk_mul_f32 v[80:81], v[80:81], v[72:73] op_sel_hi:[1,0]
	v_pk_mul_f32 v[84:85], v[84:85], v[72:73] op_sel_hi:[1,0]
	v_pk_mul_f32 v[80:81], v[0:1], v[80:81]
	v_pk_mul_f32 v[88:89], v[6:7], v[84:85]
	v_mov_b32_e32 v0, v34
	v_mov_b32_e32 v1, v39
	v_mov_b32_e32 v6, v38
	v_mov_b32_e32 v7, v35
	v_pk_mul_f32 v[0:1], v[0:1], v[72:73] op_sel_hi:[1,0]
	v_pk_mul_f32 v[6:7], v[6:7], v[72:73] op_sel_hi:[1,0]
	s_and_b64 vcc, exec, s[12:13]
	v_pk_mul_f32 v[86:87], v[74:75], v[6:7]
	v_pk_mul_f32 v[74:75], v[2:3], v[0:1]
	v_mov_b32_e32 v0, v28
	v_mov_b32_e32 v1, v25
	v_mov_b32_e32 v2, v24
	v_mov_b32_e32 v3, v29
	v_pk_mul_f32 v[0:1], v[0:1], v[72:73] op_sel_hi:[1,0]
	v_pk_mul_f32 v[2:3], v[2:3], v[72:73] op_sel_hi:[1,0]
	s_nop 0
	v_pk_mul_f32 v[84:85], v[82:83], v[2:3]
	v_pk_mul_f32 v[82:83], v[4:5], v[0:1]
	v_mul_f32_e32 v0, v30, v72
	v_mul_f32_e32 v97, v79, v0
	v_mov_b32_e32 v0, v27
	v_mov_b32_e32 v1, v31
	v_pk_mul_f32 v[0:1], v[0:1], v[72:73] op_sel_hi:[1,0]
	s_nop 0
	v_pk_mul_f32 v[76:77], v[76:77], v[0:1]
	s_cbranch_vccnz .LBB0_545
	ds_bpermute_b32 v0, v78, v80
	ds_bpermute_b32 v1, v78, v89
	ds_bpermute_b32 v2, v78, v74
	ds_bpermute_b32 v3, v78, v87
	ds_bpermute_b32 v4, v78, v82
	ds_bpermute_b32 v5, v78, v85
	ds_bpermute_b32 v6, v78, v97
	ds_bpermute_b32 v7, v78, v77
	s_waitcnt vmcnt(0) lgkmcnt(7)
	v_mul_f32_e32 v0, v69, v0
	s_waitcnt lgkmcnt(6)
	v_mul_f32_e32 v1, v71, v1
	s_waitcnt lgkmcnt(5)
	v_mul_f32_e32 v2, v65, v2
	s_waitcnt lgkmcnt(4)
	v_mul_f32_e32 v3, v67, v3
	s_waitcnt lgkmcnt(3)
	v_mul_f32_e32 v4, v61, v4
	s_waitcnt lgkmcnt(2)
	v_mul_f32_e32 v5, v63, v5
	s_waitcnt lgkmcnt(1)
	v_mul_f32_e32 v6, v57, v6
	s_waitcnt lgkmcnt(0)
	v_mul_f32_e32 v7, v59, v7
	v_cndmask_b32_e64 v0, v0, -v0, s[6:7]
	v_cndmask_b32_e64 v1, v1, -v1, s[6:7]
	v_cndmask_b32_e64 v2, v2, -v2, s[6:7]
	v_cndmask_b32_e64 v3, v3, -v3, s[6:7]
	v_cndmask_b32_e64 v4, v4, -v4, s[6:7]
	v_cndmask_b32_e64 v5, v5, -v5, s[6:7]
	v_cndmask_b32_e64 v6, v6, -v6, s[6:7]
	v_cndmask_b32_e64 v7, v7, -v7, s[6:7]
	v_fmac_f32_e32 v0, v68, v80
	v_fmac_f32_e32 v1, v70, v89
	v_fmac_f32_e32 v2, v64, v74
	v_fmac_f32_e32 v3, v66, v87
	v_fmac_f32_e32 v4, v60, v82
	v_fmac_f32_e32 v5, v62, v85
	v_fmac_f32_e32 v6, v56, v97
	v_fmac_f32_e32 v7, v58, v77
	v_cndmask_b32_e64 v0, v80, v0, s[8:9]
	v_cndmask_b32_e64 v1, v89, v1, s[8:9]
	v_cndmask_b32_e64 v2, v74, v2, s[8:9]
	v_cndmask_b32_e64 v3, v87, v3, s[8:9]
	v_cndmask_b32_e64 v4, v82, v4, s[8:9]
	v_cndmask_b32_e64 v5, v85, v5, s[8:9]
	v_cndmask_b32_e64 v6, v97, v6, s[8:9]
	v_cndmask_b32_e64 v7, v77, v7, s[8:9]
	s_mov_b64 s[0:1], 0
	v_mov_b32_e32 v79, v76
	v_mov_b32_e32 v95, v83
	v_mov_b32_e32 v94, v84
	v_mov_b32_e32 v93, v75
	v_mov_b32_e32 v92, v86
	v_mov_b32_e32 v91, v81
	v_mov_b32_e32 v90, v88

;     __device__ __forceinline__ void operator()(const f32x4 (&acc)[2][2][4][2], const Unit& u, int wr, int wc, int fr, int fq) const {
;     ...
;                 const int row = row0 + ai * HALF + m * 16;
;                 const float rs = rstd_of(ssq, row);
;                 float lo[8], hi[8];
; #pragma unroll
;                 for (int n = 0; n < 2; ++n)
; #pragma unroll
;                     for (int e = 0; e < 4; ++e) { lo[4 * n + e] = acc[ai][0][m][n][e] * rs; hi[4 * n + e] = acc[ai][1][m][n][e] * rs; }
;                 if (type != 0) {
;                     float ss = 0.f;
; #pragma unroll
;                     for (int k = 0; k < 8; ++k) ss += lo[k] * lo[k] + hi[k] * hi[k];
;                     ss += __shfl_xor(ss, 16); ss += __shfl_xor(ss, 32);
;                     const float rn = 1.0f / sqrtf(ss * (1.0f / 64.0f) + RMS_EPS);
; #pragma unroll
;                     for (int k = 0; k < 8; ++k) { lo[k] *= rn * g[k >> 2][k & 3]; hi[k] *= rn * g[2 + (k >> 2)][k & 3]; }
;                     const int t = (row < M_P) ? (row & 8191) : ((row - M_P) & 4095);
;                     const f32x4* rp = (const f32x4*)(rope + ((size_t)t * 40 + (type == 1 ? 8 * fq : 32)) * 2);
;                     const f32x4 c01 = rp[0], c23 = rp[1], c45 = rp[2], c67 = rp[3];
;                     const float cs[16] = {c01[0], c01[1], c01[2], c01[3], c23[0], c23[1], c23[2], c23[3], c45[0], c45[1], c45[2], c45[3], c67[0], c67[1], c67[2], c67[3]};
;                     if (type == 1) {
; #pragma unroll
;                         for (int k = 0; k < 8; ++k) { const float a = lo[k], b = hi[k]; lo[k] = a * cs[2 * k] - b * cs[2 * k + 1]; hi[k] = b * cs[2 * k] + a * cs[2 * k + 1]; }
;                     } else {
; #pragma unroll
;                         for (int k = 0; k < 8; ++k) { const float p = __shfl_xor(lo[k], 16); const float r = (fq == 0) ? lo[k] * cs[2 * k] - p * cs[2 * k + 1] : lo[k] * cs[2 * k] + p * cs[2 * k + 1]; lo[k] = (fq < 2) ? r : lo[k]; }
;                     }
; #pragma unroll
;                     for (int k = 0; k < 8; ++k) { lo[k] *= scale; hi[k] *= scale; }
;                 }
;                 u32x4 w0, w1;
;                 w0.x = cvt_pk_bf16(lo[0], lo[1]); w0.y = cvt_pk_bf16(lo[2], lo[3]); w0.z = cvt_pk_bf16(lo[4], lo[5]); w0.w = cvt_pk_bf16(lo[6], lo[7]);
.LBB0_549:
	v_cvt_pk_bf16_f32 v60, v60, v61
	v_cvt_pk_bf16_f32 v61, v58, v59
	v_cvt_pk_bf16_f32 v62, v56, v57
	v_cvt_pk_bf16_f32 v63, v79, v77
	v_cvt_pk_bf16_f32 v0, v0, v1
	v_cvt_pk_bf16_f32 v1, v2, v3
	v_cvt_pk_bf16_f32 v2, v4, v5
	v_mad_i64_i32 v[4:5], s[0:1], s76, v96, 0
	v_lshl_add_u64 v[4:5], v[4:5], 1, v[136:137]
	v_cvt_pk_bf16_f32 v3, v73, v7
	global_store_dwordx4 v[4:5], v[60:63], off
	global_store_dwordx4 v[4:5], v[0:3], off offset:64
	global_load_dwordx4 v[0:3], v[174:175], off offset:2560
	s_nop 0
	global_load_dwordx4 v[4:7], v[176:177], off offset:2560
	v_add_u32_e32 v80, 0xa0, v172
	s_waitcnt vmcnt(0)
	v_pk_add_f32 v[56:57], v[2:3], v[6:7]
	v_pk_add_f32 v[58:59], v[0:1], v[4:5]
	global_load_dwordx4 v[0:3], v[178:179], off offset:2560
	global_load_dwordx4 v[4:7], v[180:181], off offset:2560
	s_waitcnt vmcnt(0)
	v_pk_add_f32 v[2:3], v[2:3], v[6:7]
	v_pk_add_f32 v[0:1], v[0:1], v[4:5]
	v_pk_add_f32 v[2:3], v[56:57], v[2:3]
	v_pk_add_f32 v[0:1], v[58:59], v[0:1]
	s_nop 0
	v_pk_mov_b32 v[4:5], v[0:1], v[2:3] op_sel:[1,0]
	v_mov_b32_e32 v1, v3
	v_pk_add_f32 v[0:1], v[4:5], v[0:1]
	s_nop 0
	v_add_f32_e32 v0, v0, v1
	v_fmamk_f32 v0, v0, 0x3a800000, v212
	v_cmp_gt_f32_e32 vcc, s95, v0
	v_rsq_f32_e32 v252, v0
	s_nop 0
	v_mul_f32_e32 v250, v0, v252
	v_fma_f32 v250, -v250, v252, 1.0
	v_mul_f32_e32 v251, 0.5, v252
	v_fma_f32 v56, v251, v250, v252
	v_mov_b32_e32 v0, v52
	v_mov_b32_e32 v1, v49
	v_mov_b32_e32 v49, v53
	v_mov_b32_e32 v2, v54
	v_mov_b32_e32 v3, v51
	v_mov_b32_e32 v51, v55
	v_mov_b32_e32 v4, v44
	v_mov_b32_e32 v5, v41
	v_mov_b32_e32 v41, v45
	v_pk_mul_f32 v[0:1], v[0:1], v[56:57] op_sel_hi:[1,0]
	v_pk_mul_f32 v[6:7], v[48:49], v[56:57] op_sel_hi:[1,0]
	v_pk_mul_f32 v[2:3], v[2:3], v[56:57] op_sel_hi:[1,0]
	v_pk_mul_f32 v[58:59], v[50:51], v[56:57] op_sel_hi:[1,0]
	v_pk_mul_f32 v[4:5], v[4:5], v[56:57] op_sel_hi:[1,0]
	v_pk_mul_f32 v[66:67], v[40:41], v[56:57] op_sel_hi:[1,0]
	v_mul_f32_e32 v63, v46, v56
	v_mul_f32_e32 v57, v42, v56
	v_mov_b32_e32 v46, v43
	v_pk_mul_f32 v[60:61], v[46:47], v[56:57] op_sel_hi:[1,0]
	s_and_b64 vcc, exec, s[14:15]
	s_cbranch_vccnz .LBB0_555
	v_pk_mul_f32 v[40:41], v[6:7], v[6:7]
	v_pk_mul_f32 v[42:43], v[58:59], v[58:59]
	v_pk_fma_f32 v[40:41], v[0:1], v[0:1], v[40:41]
	v_pk_fma_f32 v[42:43], v[2:3], v[2:3], v[42:43]
	v_add_f32_e32 v40, v40, v41
	v_pk_mul_f32 v[44:45], v[66:67], v[66:67]
	v_add_f32_e32 v40, v42, v40
	v_pk_fma_f32 v[44:45], v[4:5], v[4:5], v[44:45]
	v_mov_b32_e32 v56, v60
	v_add_f32_e32 v40, v43, v40
	v_and_b32_e32 v42, 64, v214
	v_mov_b32_e32 v62, v61
	v_pk_mul_f32 v[46:47], v[56:57], v[56:57]
	v_add_f32_e32 v40, v44, v40
	v_xor_b32_e32 v41, 16, v214
	v_add_u32_e32 v56, 64, v42
	v_pk_fma_f32 v[46:47], v[62:63], v[62:63], v[46:47]
	v_add_f32_e32 v40, v45, v40
	v_cmp_lt_i32_e32 vcc, v41, v56
	v_add_f32_e32 v40, v47, v40
	v_add_f32_e32 v40, v46, v40
	v_cndmask_b32_e32 v41, v214, v41, vcc
	v_lshlrev_b32_e32 v62, 2, v41
	ds_bpermute_b32 v41, v62, v40
	s_movk_i32 s0, 0x3f60
	v_cmp_gt_i32_e32 vcc, s0, v172
	v_xor_b32_e32 v65, 32, v214
	s_waitcnt lgkmcnt(0)
	v_add_f32_e32 v64, v40, v41
	v_cndmask_b32_e32 v40, v219, v220, vcc
	v_and_b32_e32 v40, v40, v80
	v_mul_u32_u24_e32 v40, 40, v40
	v_add_lshl_u32 v52, v223, v40, 3
	global_load_dwordx4 v[40:43], v52, s[44:45] offset:48
	global_load_dwordx4 v[44:47], v52, s[44:45] offset:32
	global_load_dwordx4 v[48:51], v52, s[44:45] offset:16
	s_nop 0
	global_load_dwordx4 v[52:55], v52, s[44:45]
	v_cmp_lt_i32_e32 vcc, v65, v56
	s_nop 1
	v_cndmask_b32_e32 v56, v214, v65, vcc
	v_lshlrev_b32_e32 v56, 2, v56
	ds_bpermute_b32 v56, v56, v64
	s_waitcnt lgkmcnt(0)
	v_add_f32_e32 v56, v64, v56
	v_fmamk_f32 v56, v56, 0x3c800000, v212
	v_rsq_f32_e32 v252, v56
	s_nop 0
	v_mul_f32_e32 v250, v56, v252
	v_fma_f32 v250, -v250, v252, 1.0
	v_mul_f32_e32 v251, 0.5, v252
	s_mov_b64 s[0:1], -1
	v_fma_f32 v56, v251, v250, v252
	v_mov_b32_e32 v64, v32
	v_mov_b32_e32 v65, v37
	v_mov_b32_e32 v68, v36
	v_mov_b32_e32 v69, v33
	v_pk_mul_f32 v[64:65], v[64:65], v[56:57] op_sel_hi:[1,0]
	v_pk_mul_f32 v[68:69], v[68:69], v[56:57] op_sel_hi:[1,0]
	v_pk_mul_f32 v[64:65], v[0:1], v[64:65]
	v_pk_mul_f32 v[72:73], v[6:7], v[68:69]
	v_mov_b32_e32 v0, v34
	v_mov_b32_e32 v1, v39
	v_mov_b32_e32 v6, v38
	v_mov_b32_e32 v7, v35
	v_pk_mul_f32 v[0:1], v[0:1], v[56:57] op_sel_hi:[1,0]
	v_pk_mul_f32 v[6:7], v[6:7], v[56:57] op_sel_hi:[1,0]
	s_and_b64 vcc, exec, s[12:13]
	v_pk_mul_f32 v[70:71], v[58:59], v[6:7]
	v_pk_mul_f32 v[58:59], v[2:3], v[0:1]
	v_mov_b32_e32 v0, v28
	v_mov_b32_e32 v1, v25
	v_mov_b32_e32 v2, v24
	v_mov_b32_e32 v3, v29
	v_pk_mul_f32 v[0:1], v[0:1], v[56:57] op_sel_hi:[1,0]
	v_pk_mul_f32 v[2:3], v[2:3], v[56:57] op_sel_hi:[1,0]
	s_nop 0
	v_pk_mul_f32 v[68:69], v[66:67], v[2:3]
	v_pk_mul_f32 v[66:67], v[4:5], v[0:1]
	v_mul_f32_e32 v0, v30, v56
	v_mul_f32_e32 v81, v63, v0
	v_mov_b32_e32 v0, v27
	v_mov_b32_e32 v1, v31
	v_pk_mul_f32 v[0:1], v[0:1], v[56:57] op_sel_hi:[1,0]
	s_nop 0
	v_pk_mul_f32 v[60:61], v[60:61], v[0:1]
	s_cbranch_vccnz .LBB0_552
	ds_bpermute_b32 v0, v62, v64
	ds_bpermute_b32 v1, v62, v73
	ds_bpermute_b32 v2, v62, v58
	ds_bpermute_b32 v3, v62, v71
	ds_bpermute_b32 v4, v62, v66
	ds_bpermute_b32 v5, v62, v69
	ds_bpermute_b32 v6, v62, v81
	ds_bpermute_b32 v7, v62, v61
	s_waitcnt vmcnt(0) lgkmcnt(7)
	v_mul_f32_e32 v0, v53, v0
	s_waitcnt lgkmcnt(6)
	v_mul_f32_e32 v1, v55, v1
	s_waitcnt lgkmcnt(5)
	v_mul_f32_e32 v2, v49, v2
	s_waitcnt lgkmcnt(4)
	v_mul_f32_e32 v3, v51, v3
	s_waitcnt lgkmcnt(3)
	v_mul_f32_e32 v4, v45, v4
	s_waitcnt lgkmcnt(2)
	v_mul_f32_e32 v5, v47, v5
	s_waitcnt lgkmcnt(1)
	v_mul_f32_e32 v6, v41, v6
	s_waitcnt lgkmcnt(0)
	v_mul_f32_e32 v7, v43, v7
	v_cndmask_b32_e64 v0, v0, -v0, s[6:7]
	v_cndmask_b32_e64 v1, v1, -v1, s[6:7]
	v_cndmask_b32_e64 v2, v2, -v2, s[6:7]
	v_cndmask_b32_e64 v3, v3, -v3, s[6:7]
	v_cndmask_b32_e64 v4, v4, -v4, s[6:7]
	v_cndmask_b32_e64 v5, v5, -v5, s[6:7]
	v_cndmask_b32_e64 v6, v6, -v6, s[6:7]
	v_cndmask_b32_e64 v7, v7, -v7, s[6:7]
	v_fmac_f32_e32 v0, v52, v64
	v_fmac_f32_e32 v1, v54, v73
	v_fmac_f32_e32 v2, v48, v58
	v_fmac_f32_e32 v3, v50, v71
	v_fmac_f32_e32 v4, v44, v66
	v_fmac_f32_e32 v5, v46, v69
	v_fmac_f32_e32 v6, v40, v81
	v_fmac_f32_e32 v7, v42, v61
	v_cndmask_b32_e64 v0, v64, v0, s[8:9]
	v_cndmask_b32_e64 v1, v73, v1, s[8:9]
	v_cndmask_b32_e64 v2, v58, v2, s[8:9]
	v_cndmask_b32_e64 v3, v71, v3, s[8:9]
	v_cndmask_b32_e64 v4, v66, v4, s[8:9]
	v_cndmask_b32_e64 v5, v69, v5, s[8:9]
	v_cndmask_b32_e64 v6, v81, v6, s[8:9]
	v_cndmask_b32_e64 v7, v61, v7, s[8:9]
	s_mov_b64 s[0:1], 0
	v_mov_b32_e32 v63, v60
	v_mov_b32_e32 v79, v67
	v_mov_b32_e32 v78, v68
	v_mov_b32_e32 v77, v59
	v_mov_b32_e32 v76, v70
	v_mov_b32_e32 v75, v65
	v_mov_b32_e32 v74, v72

;     __device__ __forceinline__ void operator()(const f32x4 (&acc)[2][2][4][2], const Unit& u, int wr, int wc, int fr, int fq) const {
;     ...
;                 const int row = row0 + ai * HALF + m * 16;
;                 const float rs = rstd_of(ssq, row);
;                 float lo[8], hi[8];
; #pragma unroll
;                 for (int n = 0; n < 2; ++n)
; #pragma unroll
;                     for (int e = 0; e < 4; ++e) { lo[4 * n + e] = acc[ai][0][m][n][e] * rs; hi[4 * n + e] = acc[ai][1][m][n][e] * rs; }
;                 if (type != 0) {
;                     float ss = 0.f;
; #pragma unroll
;                     for (int k = 0; k < 8; ++k) ss += lo[k] * lo[k] + hi[k] * hi[k];
;                     ss += __shfl_xor(ss, 16); ss += __shfl_xor(ss, 32);
;                     const float rn = 1.0f / sqrtf(ss * (1.0f / 64.0f) + RMS_EPS);
; #pragma unroll
;                     for (int k = 0; k < 8; ++k) { lo[k] *= rn * g[k >> 2][k & 3]; hi[k] *= rn * g[2 + (k >> 2)][k & 3]; }
;                     const int t = (row < M_P) ? (row & 8191) : ((row - M_P) & 4095);
;                     const f32x4* rp = (const f32x4*)(rope + ((size_t)t * 40 + (type == 1 ? 8 * fq : 32)) * 2);
;                     const f32x4 c01 = rp[0], c23 = rp[1], c45 = rp[2], c67 = rp[3];
;                     const float cs[16] = {c01[0], c01[1], c01[2], c01[3], c23[0], c23[1], c23[2], c23[3], c45[0], c45[1], c45[2], c45[3], c67[0], c67[1], c67[2], c67[3]};
;                     if (type == 1) {
; #pragma unroll
;                         for (int k = 0; k < 8; ++k) { const float a = lo[k], b = hi[k]; lo[k] = a * cs[2 * k] - b * cs[2 * k + 1]; hi[k] = b * cs[2 * k] + a * cs[2 * k + 1]; }
;                     } else {
; #pragma unroll
;                         for (int k = 0; k < 8; ++k) { const float p = __shfl_xor(lo[k], 16); const float r = (fq == 0) ? lo[k] * cs[2 * k] - p * cs[2 * k + 1] : lo[k] * cs[2 * k] + p * cs[2 * k + 1]; lo[k] = (fq < 2) ? r : lo[k]; }
;                     }
; #pragma unroll
;                     for (int k = 0; k < 8; ++k) { lo[k] *= scale; hi[k] *= scale; }
;                 }
;                 u32x4 w0, w1;
;                 w0.x = cvt_pk_bf16(lo[0], lo[1]); w0.y = cvt_pk_bf16(lo[2], lo[3]); w0.z = cvt_pk_bf16(lo[4], lo[5]); w0.w = cvt_pk_bf16(lo[6], lo[7]);
.LBB0_556:
	v_cvt_pk_bf16_f32 v44, v44, v45
	v_cvt_pk_bf16_f32 v45, v42, v43
	v_cvt_pk_bf16_f32 v46, v40, v41
	v_cvt_pk_bf16_f32 v47, v63, v61
	v_cvt_pk_bf16_f32 v0, v0, v1
	v_cvt_pk_bf16_f32 v1, v2, v3
	v_cvt_pk_bf16_f32 v2, v4, v5
	v_mad_i64_i32 v[4:5], s[0:1], s76, v80, 0
	v_lshl_add_u64 v[4:5], v[4:5], 1, v[136:137]
	v_cvt_pk_bf16_f32 v3, v57, v7
	global_store_dwordx4 v[4:5], v[44:47], off
	global_store_dwordx4 v[4:5], v[0:3], off offset:64
	global_load_dwordx4 v[0:3], v[174:175], off offset:2816
	s_nop 0
	global_load_dwordx4 v[4:7], v[176:177], off offset:2816
	global_load_dwordx4 v[40:43], v[178:179], off offset:2816
	global_load_dwordx4 v[44:47], v[180:181], off offset:2816
	s_waitcnt vmcnt(7)
	v_mov_b32_e32 v48, v20
	v_mov_b32_e32 v49, v13
	v_mov_b32_e32 v13, v21
	v_mov_b32_e32 v20, v22
	v_mov_b32_e32 v21, v15
	v_mov_b32_e32 v15, v23
	v_add_u32_e32 v50, 0xb0, v172
	s_waitcnt vmcnt(2)
	v_pk_add_f32 v[2:3], v[2:3], v[6:7]
	v_pk_add_f32 v[0:1], v[0:1], v[4:5]
	s_waitcnt vmcnt(0)
	v_pk_add_f32 v[4:5], v[42:43], v[46:47]
	v_pk_add_f32 v[6:7], v[40:41], v[44:45]
	v_pk_add_f32 v[2:3], v[2:3], v[4:5]
	v_pk_add_f32 v[0:1], v[0:1], v[6:7]
	s_nop 0
	v_pk_mov_b32 v[4:5], v[0:1], v[2:3] op_sel:[1,0]
	v_mov_b32_e32 v1, v3
	v_pk_add_f32 v[0:1], v[4:5], v[0:1]
	s_nop 0
	v_add_f32_e32 v0, v0, v1
	v_fmamk_f32 v0, v0, 0x3a800000, v212
	v_rsq_f32_e32 v252, v0
	s_nop 0
	v_mul_f32_e32 v250, v0, v252
	v_fma_f32 v250, -v250, v252, 1.0
	v_mul_f32_e32 v251, 0.5, v252
	v_mov_b32_e32 v0, v16
	v_mov_b32_e32 v1, v9
	v_mov_b32_e32 v9, v17
	v_fma_f32 v6, v251, v250, v252
	v_mul_f32_e32 v43, v18, v6
	v_mov_b32_e32 v18, v11
	v_pk_mul_f32 v[4:5], v[48:49], v[6:7] op_sel_hi:[1,0]
	v_pk_mul_f32 v[48:49], v[12:13], v[6:7] op_sel_hi:[1,0]
	v_pk_mul_f32 v[2:3], v[20:21], v[6:7] op_sel_hi:[1,0]
	v_pk_mul_f32 v[46:47], v[14:15], v[6:7] op_sel_hi:[1,0]
	v_pk_mul_f32 v[0:1], v[0:1], v[6:7] op_sel_hi:[1,0]
	v_pk_mul_f32 v[44:45], v[8:9], v[6:7] op_sel_hi:[1,0]
	v_mul_f32_e32 v41, v10, v6
	s_and_b64 vcc, exec, s[14:15]
	v_pk_mul_f32 v[6:7], v[18:19], v[6:7] op_sel_hi:[1,0]
	s_cbranch_vccnz .LBB0_562
	v_pk_mul_f32 v[8:9], v[48:49], v[48:49]
	v_pk_mul_f32 v[10:11], v[46:47], v[46:47]
	v_pk_fma_f32 v[8:9], v[4:5], v[4:5], v[8:9]
	v_pk_fma_f32 v[10:11], v[2:3], v[2:3], v[10:11]
	v_add_f32_e32 v8, v8, v9
	v_pk_mul_f32 v[12:13], v[44:45], v[44:45]
	v_add_f32_e32 v8, v10, v8
	v_pk_fma_f32 v[12:13], v[0:1], v[0:1], v[12:13]
	v_mov_b32_e32 v40, v6
	v_add_f32_e32 v8, v11, v8
	v_mov_b32_e32 v42, v7
	v_pk_mul_f32 v[14:15], v[40:41], v[40:41]
	v_add_f32_e32 v8, v12, v8
	v_pk_fma_f32 v[14:15], v[42:43], v[42:43], v[14:15]
	v_add_f32_e32 v8, v13, v8
	v_add_f32_e32 v8, v15, v8
	v_and_b32_e32 v9, 64, v214
	v_add_f32_e32 v40, v14, v8
	v_xor_b32_e32 v8, 16, v214
	v_add_u32_e32 v51, 64, v9
	v_cmp_lt_i32_e32 vcc, v8, v51
	s_movk_i32 s0, 0x3f50
	s_nop 0
	v_cndmask_b32_e32 v8, v214, v8, vcc
	v_cmp_gt_i32_e32 vcc, s0, v172
	v_lshlrev_b32_e32 v42, 2, v8
	ds_bpermute_b32 v52, v42, v40
	v_cndmask_b32_e32 v8, v221, v222, vcc
	v_and_b32_e32 v8, v8, v50
	v_mul_u32_u24_e32 v8, 40, v8
	v_add_lshl_u32 v20, v223, v8, 3
	global_load_dwordx4 v[8:11], v20, s[44:45] offset:48
	global_load_dwordx4 v[12:15], v20, s[44:45] offset:32
	global_load_dwordx4 v[16:19], v20, s[44:45] offset:16
	s_nop 0
	global_load_dwordx4 v[20:23], v20, s[44:45]
	s_waitcnt lgkmcnt(0)
	v_add_f32_e32 v40, v40, v52
	v_xor_b32_e32 v52, 32, v214
	v_cmp_lt_i32_e32 vcc, v52, v51
	s_nop 1
	v_cndmask_b32_e32 v51, v214, v52, vcc
	v_lshlrev_b32_e32 v51, 2, v51
	ds_bpermute_b32 v51, v51, v40
	s_waitcnt lgkmcnt(0)
	v_add_f32_e32 v40, v40, v51
	v_fmamk_f32 v40, v40, 0x3c800000, v212
	v_rsq_f32_e32 v252, v40
	s_nop 0
	v_mul_f32_e32 v250, v40, v252
	v_fma_f32 v250, -v250, v252, 1.0
	v_mul_f32_e32 v251, 0.5, v252
	s_mov_b64 s[0:1], -1
	v_fma_f32 v40, v251, v250, v252
	v_mov_b32_e32 v52, v32
	v_mov_b32_e32 v53, v37
	v_mov_b32_e32 v37, v33
	v_pk_mul_f32 v[52:53], v[52:53], v[40:41] op_sel_hi:[1,0]
	v_pk_mul_f32 v[32:33], v[36:37], v[40:41] op_sel_hi:[1,0]
	s_and_b64 vcc, exec, s[12:13]
	v_pk_mul_f32 v[48:49], v[48:49], v[32:33]
	v_pk_mul_f32 v[32:33], v[4:5], v[52:53]
	v_mov_b32_e32 v4, v34
	v_mov_b32_e32 v5, v39
	v_mov_b32_e32 v39, v35
	v_pk_mul_f32 v[4:5], v[4:5], v[40:41] op_sel_hi:[1,0]
	v_pk_mul_f32 v[34:35], v[38:39], v[40:41] op_sel_hi:[1,0]
	s_nop 0
	v_pk_mul_f32 v[38:39], v[46:47], v[34:35]
	v_pk_mul_f32 v[34:35], v[2:3], v[4:5]
	v_mov_b32_e32 v2, v28
	v_mov_b32_e32 v3, v25
	v_pk_mul_f32 v[2:3], v[2:3], v[40:41] op_sel_hi:[1,0]
	v_mov_b32_e32 v25, v29
	v_pk_mul_f32 v[4:5], v[24:25], v[40:41] op_sel_hi:[1,0]
	v_pk_mul_f32 v[24:25], v[0:1], v[2:3]
	v_mul_f32_e32 v0, v30, v40
	v_mov_b32_e32 v30, v27
	v_mul_f32_e32 v46, v43, v0
	v_pk_mul_f32 v[0:1], v[30:31], v[40:41] op_sel_hi:[1,0]
	v_pk_mul_f32 v[36:37], v[44:45], v[4:5]
	v_pk_mul_f32 v[28:29], v[6:7], v[0:1]
	s_cbranch_vccnz .LBB0_559
	ds_bpermute_b32 v0, v42, v32
	ds_bpermute_b32 v1, v42, v49
	ds_bpermute_b32 v2, v42, v34
	ds_bpermute_b32 v3, v42, v39
	ds_bpermute_b32 v4, v42, v24
	ds_bpermute_b32 v5, v42, v37
	ds_bpermute_b32 v6, v42, v46
	ds_bpermute_b32 v7, v42, v29
	s_waitcnt vmcnt(0) lgkmcnt(7)
	v_mul_f32_e32 v0, v21, v0
	s_waitcnt lgkmcnt(6)
	v_mul_f32_e32 v1, v23, v1
	s_waitcnt lgkmcnt(5)
	v_mul_f32_e32 v2, v17, v2
	s_waitcnt lgkmcnt(4)
	v_mul_f32_e32 v3, v19, v3
	s_waitcnt lgkmcnt(3)
	v_mul_f32_e32 v4, v13, v4
	s_waitcnt lgkmcnt(2)
	v_mul_f32_e32 v5, v15, v5
	s_waitcnt lgkmcnt(1)
	v_mul_f32_e32 v6, v9, v6
	s_waitcnt lgkmcnt(0)
	v_mul_f32_e32 v7, v11, v7
	v_cndmask_b32_e64 v0, v0, -v0, s[6:7]
	v_cndmask_b32_e64 v1, v1, -v1, s[6:7]
	v_cndmask_b32_e64 v2, v2, -v2, s[6:7]
	v_cndmask_b32_e64 v3, v3, -v3, s[6:7]
	v_cndmask_b32_e64 v4, v4, -v4, s[6:7]
	v_cndmask_b32_e64 v5, v5, -v5, s[6:7]
	v_cndmask_b32_e64 v6, v6, -v6, s[6:7]
	v_cndmask_b32_e64 v7, v7, -v7, s[6:7]
	v_fmac_f32_e32 v0, v20, v32
	v_fmac_f32_e32 v1, v22, v49
	v_fmac_f32_e32 v2, v16, v34
	v_fmac_f32_e32 v3, v18, v39
	v_fmac_f32_e32 v4, v12, v24
	v_fmac_f32_e32 v5, v14, v37
	v_fmac_f32_e32 v6, v8, v46
	v_fmac_f32_e32 v7, v10, v29
	v_cndmask_b32_e64 v0, v32, v0, s[8:9]
	v_cndmask_b32_e64 v1, v49, v1, s[8:9]
	v_cndmask_b32_e64 v2, v34, v2, s[8:9]
	v_cndmask_b32_e64 v3, v39, v3, s[8:9]
	v_cndmask_b32_e64 v4, v24, v4, s[8:9]
	v_cndmask_b32_e64 v5, v37, v5, s[8:9]
	v_cndmask_b32_e64 v6, v46, v6, s[8:9]
	v_cndmask_b32_e64 v7, v29, v7, s[8:9]
	s_mov_b64 s[0:1], 0
	v_mov_b32_e32 v27, v28
	v_mov_b32_e32 v45, v25
	v_mov_b32_e32 v44, v36
	v_mov_b32_e32 v43, v35
	v_mov_b32_e32 v42, v38
	v_mov_b32_e32 v31, v33
	v_mov_b32_e32 v30, v48

; __device__ __forceinline__ unsigned cvt_pk_bf16(float lo, float hi) { unsigned r; asm volatile("v_cvt_pk_bf16_f32 %0, %1, %2" : "=v"(r) : "v"(lo), "v"(hi)); return r; }
; __device__ __forceinline__ float rstd_of(const float* ssq, int row) {
;     const f32x4* p = (const f32x4*)ssq + row; const f32x4 s = (p[0] + p[MROWS]) + (p[2 * MROWS] + p[3 * MROWS]);
;     return 1.0f / sqrtf(((s[0] + s[1]) + (s[2] + s[3])) * (1.0f / 1024.0f) + RMS_EPS); }
;     __device__ __forceinline__ void operator()(const f32x4 (&acc)[2][2][4][2], const Unit& u, int wr, int wc, int fr, int fq) const {
;         const int row0 = u.pm * BM + wr * 64 + fr;
;         bf16_t* base = G + u.pn * BM + wc * 32 + 8 * fq;
; #pragma unroll
;         for (int ai = 0; ai < 2; ++ai)
; #pragma unroll
;             for (int m = 0; m < 4; ++m) {
;                 const int row = row0 + ai * HALF + m * 16;
;                 const float rs = rstd_of(ssq, row);
; #pragma unroll
;                 for (int bj = 0; bj < 2; ++bj) {
;                     float v[8];
; #pragma unroll
;                     for (int n = 0; n < 2; ++n)
; #pragma unroll
;                         for (int e = 0; e < 4; ++e) v[n * 4 + e] = acc[ai][bj][m][n][e] * rs;
;                     u32x4 w; w.x = cvt_pk_bf16(v[0], v[1]); w.y = cvt_pk_bf16(v[2], v[3]); w.z = cvt_pk_bf16(v[4], v[5]); w.w = cvt_pk_bf16(v[6], v[7]);
;                     *(u32x4*)(base + (size_t)row * 2048 + bj * HALF) = w;
;                 }
.LBB0_958:
	v_lshl_add_u32 v156, s6, 8, v160
	v_ashrrev_i32_e32 v157, 31, v156
	v_lshl_add_u64 v[148:149], v[156:157], 4, s[24:25]
	v_add_co_u32_e32 v150, vcc, 0xc0000, v148
	s_lshl_b32 s6, s7, 8
	s_nop 0
	v_addc_co_u32_e32 v151, vcc, 0, v149, vcc
	v_add_co_u32_e32 v152, vcc, 0x180000, v148
	global_load_dwordx4 v[168:171], v[148:149], off
	global_load_dwordx4 v[172:175], v[150:151], off
	v_addc_co_u32_e32 v153, vcc, 0, v149, vcc
	v_add_co_u32_e32 v154, vcc, 0x240000, v148
	s_ashr_i32 s7, s6, 31
	s_nop 0
	v_addc_co_u32_e32 v155, vcc, 0, v149, vcc
	global_load_dwordx4 v[176:179], v[152:153], off
	global_load_dwordx4 v[180:183], v[154:155], off
	s_waitcnt vmcnt(0)
	v_pk_add_f32 v[146:147], v[170:171], v[174:175]
	v_pk_add_f32 v[158:159], v[168:169], v[172:173]
	v_pk_add_f32 v[168:169], v[178:179], v[182:183]
	v_pk_add_f32 v[170:171], v[176:177], v[180:181]
	v_pk_add_f32 v[146:147], v[146:147], v[168:169]
	v_pk_add_f32 v[158:159], v[158:159], v[170:171]
	s_nop 0
	v_pk_mov_b32 v[168:169], v[158:159], v[146:147] op_sel:[1,0]
	v_mov_b32_e32 v159, v147
	v_pk_add_f32 v[146:147], v[168:169], v[158:159]
	v_lshl_add_u64 v[158:159], s[6:7], 1, v[136:137]
	v_add_f32_e32 v146, v146, v147
	v_fmamk_f32 v146, v146, 0x3a800000, v165
	v_rsq_f32_e32 v252, v146
	s_nop 0
	v_mul_f32_e32 v250, v146, v252
	v_fma_f32 v250, -v250, v252, 1.0
	v_mul_f32_e32 v251, 0.5, v252
	v_lshlrev_b64 v[146:147], 12, v[156:157]
	v_lshl_add_u64 v[146:147], v[158:159], 0, v[146:147]
	v_fma_f32 v157, v251, v250, v252
	v_mul_f32_e32 v124, v124, v157
	v_mul_f32_e32 v125, v125, v157
	v_mul_f32_e32 v126, v126, v157
	v_mul_f32_e32 v127, v127, v157
	v_mul_f32_e32 v120, v120, v157
	v_mul_f32_e32 v121, v121, v157
	v_mul_f32_e32 v122, v122, v157
	v_mul_f32_e32 v123, v123, v157
	v_mul_f32_e32 v116, v116, v157
	v_mul_f32_e32 v117, v117, v157
	v_mul_f32_e32 v118, v118, v157
	v_mul_f32_e32 v119, v119, v157
	v_mul_f32_e32 v167, v112, v157
	v_mul_f32_e32 v168, v113, v157
	v_mul_f32_e32 v169, v114, v157
	v_mul_f32_e32 v157, v115, v157
	v_cvt_pk_bf16_f32 v112, v124, v125
	v_cvt_pk_bf16_f32 v113, v126, v127
	v_cvt_pk_bf16_f32 v114, v120, v121
	v_cvt_pk_bf16_f32 v115, v122, v123
	global_store_dwordx4 v[146:147], v[112:115], off
	s_nop 1
	v_cvt_pk_bf16_f32 v112, v116, v117
	v_cvt_pk_bf16_f32 v113, v118, v119
	v_cvt_pk_bf16_f32 v114, v167, v168
	v_cvt_pk_bf16_f32 v115, v169, v157
	global_store_dwordx4 v[146:147], v[112:115], off offset:256
	global_load_dwordx4 v[112:115], v[148:149], off offset:256
	s_nop 0
	global_load_dwordx4 v[116:119], v[150:151], off offset:256
	global_load_dwordx4 v[120:123], v[152:153], off offset:256
	global_load_dwordx4 v[124:127], v[154:155], off offset:256
	s_waitcnt vmcnt(2)
	v_pk_add_f32 v[114:115], v[114:115], v[118:119]
	v_pk_add_f32 v[112:113], v[112:113], v[116:117]
	s_waitcnt vmcnt(0)
	v_pk_add_f32 v[116:117], v[122:123], v[126:127]
	v_pk_add_f32 v[118:119], v[120:121], v[124:125]
	v_pk_add_f32 v[114:115], v[114:115], v[116:117]
	v_pk_add_f32 v[112:113], v[112:113], v[118:119]
	s_nop 0
	v_pk_mov_b32 v[116:117], v[112:113], v[114:115] op_sel:[1,0]
	v_mov_b32_e32 v113, v115
	v_pk_add_f32 v[112:113], v[116:117], v[112:113]
	s_nop 0
	v_add_f32_e32 v112, v112, v113
	v_fmamk_f32 v112, v112, 0x3a800000, v165
	v_rsq_f32_e32 v252, v112
	s_nop 0
	v_mul_f32_e32 v250, v112, v252
	v_fma_f32 v250, -v250, v252, 1.0
	v_mul_f32_e32 v251, 0.5, v252
	v_or_b32_e32 v112, 16, v156
	v_ashrrev_i32_e32 v113, 31, v112
	v_lshlrev_b64 v[112:113], 12, v[112:113]
	v_lshl_add_u64 v[112:113], v[158:159], 0, v[112:113]
	v_fma_f32 v114, v251, v250, v252
	v_mul_f32_e32 v108, v108, v114
	v_mul_f32_e32 v109, v109, v114
	v_mul_f32_e32 v110, v110, v114
	v_mul_f32_e32 v111, v111, v114
	v_mul_f32_e32 v104, v104, v114
	v_mul_f32_e32 v105, v105, v114
	v_mul_f32_e32 v106, v106, v114
	v_mul_f32_e32 v107, v107, v114
	v_mul_f32_e32 v100, v100, v114
	v_mul_f32_e32 v101, v101, v114
	v_mul_f32_e32 v102, v102, v114
	v_mul_f32_e32 v103, v103, v114
	v_mul_f32_e32 v115, v96, v114
	v_mul_f32_e32 v116, v97, v114
	v_mul_f32_e32 v117, v98, v114
	v_mul_f32_e32 v114, v99, v114
	v_cvt_pk_bf16_f32 v96, v108, v109
	v_cvt_pk_bf16_f32 v97, v110, v111
	v_cvt_pk_bf16_f32 v98, v104, v105
	v_cvt_pk_bf16_f32 v99, v106, v107
	global_store_dwordx4 v[112:113], v[96:99], off
	s_nop 1
	v_cvt_pk_bf16_f32 v96, v100, v101
	v_cvt_pk_bf16_f32 v97, v102, v103
	v_cvt_pk_bf16_f32 v98, v115, v116
	v_cvt_pk_bf16_f32 v99, v117, v114
	global_store_dwordx4 v[112:113], v[96:99], off offset:256
	global_load_dwordx4 v[96:99], v[148:149], off offset:512
	s_nop 0
	global_load_dwordx4 v[100:103], v[150:151], off offset:512
	global_load_dwordx4 v[104:107], v[152:153], off offset:512
	global_load_dwordx4 v[108:111], v[154:155], off offset:512
	s_waitcnt vmcnt(2)
	v_pk_add_f32 v[98:99], v[98:99], v[102:103]
	v_pk_add_f32 v[96:97], v[96:97], v[100:101]
	s_waitcnt vmcnt(0)
; __device__ __forceinline__ unsigned cvt_pk_bf16(float lo, float hi) { unsigned r; asm volatile("v_cvt_pk_bf16_f32 %0, %1, %2" : "=v"(r) : "v"(lo), "v"(hi)); return r; }
; __device__ __forceinline__ float rstd_of(const float* ssq, int row) {
;     const f32x4* p = (const f32x4*)ssq + row; const f32x4 s = (p[0] + p[MROWS]) + (p[2 * MROWS] + p[3 * MROWS]);
;     return 1.0f / sqrtf(((s[0] + s[1]) + (s[2] + s[3])) * (1.0f / 1024.0f) + RMS_EPS); }
;     __device__ __forceinline__ void operator()(const f32x4 (&acc)[2][2][4][2], const Unit& u, int wr, int wc, int fr, int fq) const {
;     ...
;         for (int ai = 0; ai < 2; ++ai)
; #pragma unroll
;             for (int m = 0; m < 4; ++m) {
;                 const int row = row0 + ai * HALF + m * 16;
;                 const float rs = rstd_of(ssq, row);
; #pragma unroll
;                 for (int bj = 0; bj < 2; ++bj) {
;                     float v[8];
; #pragma unroll
;                     for (int n = 0; n < 2; ++n)
; #pragma unroll
;                         for (int e = 0; e < 4; ++e) v[n * 4 + e] = acc[ai][bj][m][n][e] * rs;
;                     u32x4 w; w.x = cvt_pk_bf16(v[0], v[1]); w.y = cvt_pk_bf16(v[2], v[3]); w.z = cvt_pk_bf16(v[4], v[5]); w.w = cvt_pk_bf16(v[6], v[7]);
;                     *(u32x4*)(base + (size_t)row * 2048 + bj * HALF) = w;
;                 }
	v_pk_add_f32 v[100:101], v[106:107], v[110:111]
	v_pk_add_f32 v[102:103], v[104:105], v[108:109]
	v_pk_add_f32 v[98:99], v[98:99], v[100:101]
	v_pk_add_f32 v[96:97], v[96:97], v[102:103]
	s_nop 0
	v_pk_mov_b32 v[100:101], v[96:97], v[98:99] op_sel:[1,0]
	v_mov_b32_e32 v97, v99
	v_pk_add_f32 v[96:97], v[100:101], v[96:97]
	s_nop 0
	v_add_f32_e32 v96, v96, v97
	v_fmamk_f32 v96, v96, 0x3a800000, v165
	v_rsq_f32_e32 v252, v96
	s_nop 0
	v_mul_f32_e32 v250, v96, v252
	v_fma_f32 v250, -v250, v252, 1.0
	v_mul_f32_e32 v251, 0.5, v252
	v_or_b32_e32 v96, 32, v156
	v_ashrrev_i32_e32 v97, 31, v96
	v_lshlrev_b64 v[96:97], 12, v[96:97]
	v_lshl_add_u64 v[96:97], v[158:159], 0, v[96:97]
	v_fma_f32 v98, v251, v250, v252
	v_mul_f32_e32 v92, v92, v98
	v_mul_f32_e32 v93, v93, v98
	v_mul_f32_e32 v94, v94, v98
	v_mul_f32_e32 v95, v95, v98
	v_mul_f32_e32 v88, v88, v98
	v_mul_f32_e32 v89, v89, v98
	v_mul_f32_e32 v90, v90, v98
	v_mul_f32_e32 v91, v91, v98
	v_mul_f32_e32 v84, v84, v98
	v_mul_f32_e32 v85, v85, v98
	v_mul_f32_e32 v86, v86, v98
	v_mul_f32_e32 v87, v87, v98
	v_mul_f32_e32 v99, v80, v98
	v_mul_f32_e32 v100, v81, v98
	v_mul_f32_e32 v101, v82, v98
	v_mul_f32_e32 v98, v83, v98
	v_cvt_pk_bf16_f32 v80, v92, v93
	v_cvt_pk_bf16_f32 v81, v94, v95
	v_cvt_pk_bf16_f32 v82, v88, v89
	v_cvt_pk_bf16_f32 v83, v90, v91
	global_store_dwordx4 v[96:97], v[80:83], off
	s_nop 1
	v_cvt_pk_bf16_f32 v80, v84, v85
	v_cvt_pk_bf16_f32 v81, v86, v87
	v_cvt_pk_bf16_f32 v82, v99, v100
	v_cvt_pk_bf16_f32 v83, v101, v98
	global_store_dwordx4 v[96:97], v[80:83], off offset:256
	global_load_dwordx4 v[80:83], v[148:149], off offset:768
	s_nop 0
	global_load_dwordx4 v[84:87], v[150:151], off offset:768
	global_load_dwordx4 v[88:91], v[152:153], off offset:768
	global_load_dwordx4 v[92:95], v[154:155], off offset:768
	s_waitcnt vmcnt(2)
	v_pk_add_f32 v[82:83], v[82:83], v[86:87]
	v_pk_add_f32 v[80:81], v[80:81], v[84:85]
	s_waitcnt vmcnt(0)
	v_pk_add_f32 v[84:85], v[90:91], v[94:95]
	v_pk_add_f32 v[86:87], v[88:89], v[92:93]
	v_pk_add_f32 v[82:83], v[82:83], v[84:85]
	v_pk_add_f32 v[80:81], v[80:81], v[86:87]
	s_nop 0
	v_pk_mov_b32 v[84:85], v[80:81], v[82:83] op_sel:[1,0]
	v_mov_b32_e32 v81, v83
	v_pk_add_f32 v[80:81], v[84:85], v[80:81]
	s_nop 0
	v_add_f32_e32 v80, v80, v81
	v_fmamk_f32 v80, v80, 0x3a800000, v165
	v_rsq_f32_e32 v252, v80
	s_nop 0
	v_mul_f32_e32 v250, v80, v252
	v_fma_f32 v250, -v250, v252, 1.0
	v_mul_f32_e32 v251, 0.5, v252
	v_or_b32_e32 v80, 48, v156
	v_ashrrev_i32_e32 v81, 31, v80
	v_lshlrev_b64 v[80:81], 12, v[80:81]
	v_lshl_add_u64 v[80:81], v[158:159], 0, v[80:81]
	v_fma_f32 v82, v251, v250, v252
	v_mul_f32_e32 v76, v76, v82
	v_mul_f32_e32 v77, v77, v82
	v_mul_f32_e32 v78, v78, v82
	v_mul_f32_e32 v79, v79, v82
	v_mul_f32_e32 v72, v72, v82
	v_mul_f32_e32 v73, v73, v82
	v_mul_f32_e32 v74, v74, v82
	v_mul_f32_e32 v75, v75, v82
	v_mul_f32_e32 v68, v68, v82
	v_mul_f32_e32 v69, v69, v82
	v_mul_f32_e32 v70, v70, v82
	v_mul_f32_e32 v71, v71, v82
	v_mul_f32_e32 v83, v64, v82
	v_mul_f32_e32 v84, v65, v82
	v_mul_f32_e32 v85, v66, v82
	v_mul_f32_e32 v82, v67, v82
	v_cvt_pk_bf16_f32 v64, v76, v77
	v_cvt_pk_bf16_f32 v65, v78, v79
	v_cvt_pk_bf16_f32 v66, v72, v73
	v_cvt_pk_bf16_f32 v67, v74, v75
	global_store_dwordx4 v[80:81], v[64:67], off
	s_nop 1
	v_cvt_pk_bf16_f32 v64, v68, v69
	v_cvt_pk_bf16_f32 v65, v70, v71
	v_cvt_pk_bf16_f32 v66, v83, v84
	v_cvt_pk_bf16_f32 v67, v85, v82
	global_store_dwordx4 v[80:81], v[64:67], off offset:256
	global_load_dwordx4 v[64:67], v[148:149], off offset:2048
	s_nop 0
	global_load_dwordx4 v[68:71], v[150:151], off offset:2048
	global_load_dwordx4 v[72:75], v[152:153], off offset:2048
	global_load_dwordx4 v[76:79], v[154:155], off offset:2048
	s_waitcnt vmcnt(2)
	v_pk_add_f32 v[66:67], v[66:67], v[70:71]
	v_pk_add_f32 v[64:65], v[64:65], v[68:69]
	s_waitcnt vmcnt(0)
	v_pk_add_f32 v[68:69], v[74:75], v[78:79]
	v_pk_add_f32 v[70:71], v[72:73], v[76:77]
	v_pk_add_f32 v[66:67], v[66:67], v[68:69]
	v_pk_add_f32 v[64:65], v[64:65], v[70:71]
	s_nop 0
	v_pk_mov_b32 v[68:69], v[64:65], v[66:67] op_sel:[1,0]
	v_mov_b32_e32 v65, v67
	v_pk_add_f32 v[64:65], v[68:69], v[64:65]
	s_nop 0
	v_add_f32_e32 v64, v64, v65
	v_fmamk_f32 v64, v64, 0x3a800000, v165
	v_rsq_f32_e32 v252, v64
	s_nop 0
	v_mul_f32_e32 v250, v64, v252
	v_fma_f32 v250, -v250, v252, 1.0
	v_mul_f32_e32 v251, 0.5, v252
	v_lshl_add_u64 v[64:65], v[146:147], 0, s[36:37]
	v_add_co_u32_e32 v66, vcc, s69, v146
	s_nop 1
	v_addc_co_u32_e32 v67, vcc, 0, v147, vcc
	s_nop 1
	v_fma_f32 v68, v251, v250, v252
	v_mul_f32_e32 v60, v60, v68
	v_mul_f32_e32 v61, v61, v68
	v_mul_f32_e32 v62, v62, v68
	v_mul_f32_e32 v63, v63, v68
	v_mul_f32_e32 v56, v56, v68
	v_mul_f32_e32 v57, v57, v68
	v_mul_f32_e32 v58, v58, v68
	v_mul_f32_e32 v59, v59, v68
	v_mul_f32_e32 v52, v52, v68
	v_mul_f32_e32 v53, v53, v68
	v_mul_f32_e32 v54, v54, v68
	v_mul_f32_e32 v55, v55, v68
	v_mul_f32_e32 v69, v48, v68
	v_mul_f32_e32 v70, v49, v68
	v_mul_f32_e32 v71, v50, v68
	v_mul_f32_e32 v68, v51, v68
	v_cvt_pk_bf16_f32 v48, v60, v61
	v_cvt_pk_bf16_f32 v49, v62, v63
	v_cvt_pk_bf16_f32 v50, v56, v57
	v_cvt_pk_bf16_f32 v51, v58, v59
	global_store_dwordx4 v[66:67], v[48:51], off
	s_nop 1
	v_cvt_pk_bf16_f32 v48, v52, v53
	v_cvt_pk_bf16_f32 v49, v54, v55
	v_cvt_pk_bf16_f32 v50, v69, v70
	v_cvt_pk_bf16_f32 v51, v71, v68
	global_store_dwordx4 v[64:65], v[48:51], off offset:256
	global_load_dwordx4 v[48:51], v[148:149], off offset:2304
	s_nop 0
	global_load_dwordx4 v[52:55], v[150:151], off offset:2304
	global_load_dwordx4 v[56:59], v[152:153], off offset:2304
	global_load_dwordx4 v[60:63], v[154:155], off offset:2304
	s_waitcnt vmcnt(2)
; __device__ __forceinline__ unsigned cvt_pk_bf16(float lo, float hi) { unsigned r; asm volatile("v_cvt_pk_bf16_f32 %0, %1, %2" : "=v"(r) : "v"(lo), "v"(hi)); return r; }
; #define PG8_BAR __builtin_amdgcn_s_barrier()
;     __device__ __forceinline__ void operator()(const f32x4 (&acc)[2][2][4][2], const Unit& u, int wr, int wc, int fr, int fq) const {
;     ...
;         for (int ai = 0; ai < 2; ++ai)
; #pragma unroll
;             for (int m = 0; m < 4; ++m) {
;                 const int row = row0 + ai * HALF + m * 16;
;                 const float rs = rstd_of(ssq, row);
; #pragma unroll
;                 for (int bj = 0; bj < 2; ++bj) {
;                     float v[8];
; #pragma unroll
;                     for (int n = 0; n < 2; ++n)
; #pragma unroll
;                         for (int e = 0; e < 4; ++e) v[n * 4 + e] = acc[ai][bj][m][n][e] * rs;
;                     u32x4 w; w.x = cvt_pk_bf16(v[0], v[1]); w.y = cvt_pk_bf16(v[2], v[3]); w.z = cvt_pk_bf16(v[4], v[5]); w.w = cvt_pk_bf16(v[6], v[7]);
;                     *(u32x4*)(base + (size_t)row * 2048 + bj * HALF) = w;
;                 }
; template <class Epi, bool ALIGN_EPI = true, bool BLOCKDIAG = false>
; __device__ __forceinline__ void gemm_phase(PG8_LAS unsigned char* lds, const Gemm g, const StaticOrder& S, const Epi& E) {
;     ...
;         if constexpr (ALIGN_EPI) { if (wr == 0) PG8_BAR; }
;         E(acc, cur, wr, wc, fr, fq);
;         if (!has_next) break;
; #pragma unroll
;         for (int a = 0; a < 2; ++a)
; #pragma unroll
;             for (int b = 0; b < 2; ++b)
; #pragma unroll
;                 for (int m = 0; m < 4; ++m)
; #pragma unroll
;                     for (int n = 0; n < 2; ++n) acc[a][b][m][n] = (f32x4){0.f, 0.f, 0.f, 0.f};
;         cur = nxt; cA = nA; cB = nB; ++ui;
;         if constexpr (ALIGN_EPI) { if (wr == 1) PG8_BAR; }
	v_pk_add_f32 v[50:51], v[50:51], v[54:55]
	v_pk_add_f32 v[48:49], v[48:49], v[52:53]
	s_waitcnt vmcnt(0)
	v_pk_add_f32 v[52:53], v[58:59], v[62:63]
	v_pk_add_f32 v[54:55], v[56:57], v[60:61]
	v_pk_add_f32 v[50:51], v[50:51], v[52:53]
	v_pk_add_f32 v[48:49], v[48:49], v[54:55]
	s_nop 0
	v_pk_mov_b32 v[52:53], v[48:49], v[50:51] op_sel:[1,0]
	v_mov_b32_e32 v49, v51
	v_pk_add_f32 v[48:49], v[52:53], v[48:49]
	s_nop 0
	v_add_f32_e32 v48, v48, v49
	v_fmamk_f32 v48, v48, 0x3a800000, v165
	v_rsq_f32_e32 v252, v48
	s_nop 0
	v_mul_f32_e32 v250, v48, v252
	v_fma_f32 v250, -v250, v252, 1.0
	v_mul_f32_e32 v251, 0.5, v252
	v_lshl_add_u64 v[48:49], v[146:147], 0, s[38:39]
	v_add_co_u32_e32 v50, vcc, s70, v146
	s_nop 1
	v_addc_co_u32_e32 v51, vcc, 0, v147, vcc
	s_nop 1
	v_fma_f32 v52, v251, v250, v252
	v_mul_f32_e32 v44, v44, v52
	v_mul_f32_e32 v45, v45, v52
	v_mul_f32_e32 v46, v46, v52
	v_mul_f32_e32 v47, v47, v52
	v_mul_f32_e32 v40, v40, v52
	v_mul_f32_e32 v41, v41, v52
	v_mul_f32_e32 v42, v42, v52
	v_mul_f32_e32 v43, v43, v52
	v_mul_f32_e32 v36, v36, v52
	v_mul_f32_e32 v37, v37, v52
	v_mul_f32_e32 v38, v38, v52
	v_mul_f32_e32 v39, v39, v52
	v_mul_f32_e32 v53, v32, v52
	v_mul_f32_e32 v54, v33, v52
	v_mul_f32_e32 v55, v34, v52
	v_mul_f32_e32 v52, v35, v52
	v_cvt_pk_bf16_f32 v32, v44, v45
	v_cvt_pk_bf16_f32 v33, v46, v47
	v_cvt_pk_bf16_f32 v34, v40, v41
	v_cvt_pk_bf16_f32 v35, v42, v43
	global_store_dwordx4 v[50:51], v[32:35], off
	s_nop 1
	v_cvt_pk_bf16_f32 v32, v36, v37
	v_cvt_pk_bf16_f32 v33, v38, v39
	v_cvt_pk_bf16_f32 v34, v53, v54
	v_cvt_pk_bf16_f32 v35, v55, v52
	global_store_dwordx4 v[48:49], v[32:35], off offset:256
	global_load_dwordx4 v[32:35], v[148:149], off offset:2560
	s_nop 0
	global_load_dwordx4 v[36:39], v[150:151], off offset:2560
	global_load_dwordx4 v[40:43], v[152:153], off offset:2560
	global_load_dwordx4 v[44:47], v[154:155], off offset:2560
	s_waitcnt vmcnt(2)
	v_pk_add_f32 v[34:35], v[34:35], v[38:39]
	v_pk_add_f32 v[32:33], v[32:33], v[36:37]
	s_waitcnt vmcnt(0)
	v_pk_add_f32 v[36:37], v[42:43], v[46:47]
	v_pk_add_f32 v[38:39], v[40:41], v[44:45]
	v_pk_add_f32 v[34:35], v[34:35], v[36:37]
	v_pk_add_f32 v[32:33], v[32:33], v[38:39]
	s_nop 0
	v_pk_mov_b32 v[36:37], v[32:33], v[34:35] op_sel:[1,0]
	v_mov_b32_e32 v33, v35
	v_pk_add_f32 v[32:33], v[36:37], v[32:33]
	s_nop 0
	v_add_f32_e32 v32, v32, v33
	v_fmamk_f32 v32, v32, 0x3a800000, v165
	v_rsq_f32_e32 v252, v32
	s_nop 0
	v_mul_f32_e32 v250, v32, v252
	v_fma_f32 v250, -v250, v252, 1.0
	v_mul_f32_e32 v251, 0.5, v252
	v_lshl_add_u64 v[32:33], v[146:147], 0, s[40:41]
	v_add_co_u32_e32 v34, vcc, s71, v146
	s_nop 1
	v_addc_co_u32_e32 v35, vcc, 0, v147, vcc
	s_nop 1
	v_fma_f32 v36, v251, v250, v252
	v_mul_f32_e32 v28, v28, v36
	v_mul_f32_e32 v29, v29, v36
	v_mul_f32_e32 v30, v30, v36
	v_mul_f32_e32 v31, v31, v36
	v_mul_f32_e32 v24, v24, v36
	v_mul_f32_e32 v25, v25, v36
	v_mul_f32_e32 v26, v26, v36
	v_mul_f32_e32 v27, v27, v36
	v_mul_f32_e32 v20, v20, v36
	v_mul_f32_e32 v21, v21, v36
	v_mul_f32_e32 v22, v22, v36
	v_mul_f32_e32 v23, v23, v36
	v_mul_f32_e32 v37, v16, v36
	v_mul_f32_e32 v38, v17, v36
	v_mul_f32_e32 v39, v18, v36
	v_mul_f32_e32 v36, v19, v36
	v_cvt_pk_bf16_f32 v16, v28, v29
	v_cvt_pk_bf16_f32 v17, v30, v31
	v_cvt_pk_bf16_f32 v18, v24, v25
	v_cvt_pk_bf16_f32 v19, v26, v27
	global_store_dwordx4 v[34:35], v[16:19], off
	s_nop 1
	v_cvt_pk_bf16_f32 v16, v20, v21
	v_cvt_pk_bf16_f32 v17, v22, v23
	v_cvt_pk_bf16_f32 v18, v37, v38
	v_cvt_pk_bf16_f32 v19, v39, v36
	global_store_dwordx4 v[32:33], v[16:19], off offset:256
	global_load_dwordx4 v[16:19], v[148:149], off offset:2816
	s_nop 0
	global_load_dwordx4 v[20:23], v[150:151], off offset:2816
	global_load_dwordx4 v[24:27], v[152:153], off offset:2816
	global_load_dwordx4 v[28:31], v[154:155], off offset:2816
	s_waitcnt vmcnt(2)
	v_pk_add_f32 v[18:19], v[18:19], v[22:23]
	v_pk_add_f32 v[16:17], v[16:17], v[20:21]
	s_waitcnt vmcnt(0)
	v_pk_add_f32 v[20:21], v[26:27], v[30:31]
	v_pk_add_f32 v[22:23], v[24:25], v[28:29]
	v_pk_add_f32 v[18:19], v[18:19], v[20:21]
	v_pk_add_f32 v[16:17], v[16:17], v[22:23]
	s_nop 0
	v_pk_mov_b32 v[20:21], v[16:17], v[18:19] op_sel:[1,0]
	v_mov_b32_e32 v17, v19
	v_pk_add_f32 v[16:17], v[20:21], v[16:17]
	s_nop 0
	v_add_f32_e32 v16, v16, v17
	v_fmamk_f32 v16, v16, 0x3a800000, v165
	v_rsq_f32_e32 v252, v16
	s_nop 0
	v_mul_f32_e32 v250, v16, v252
	v_fma_f32 v250, -v250, v252, 1.0
	v_mul_f32_e32 v251, 0.5, v252
	v_lshl_add_u64 v[16:17], v[146:147], 0, s[42:43]
	v_add_co_u32_e32 v18, vcc, s74, v146
	s_nop 1
	v_addc_co_u32_e32 v19, vcc, 0, v147, vcc
	s_nop 1
	v_fma_f32 v20, v251, v250, v252
	s_andn2_b64 vcc, exec, s[0:1]
	v_mul_f32_e32 v12, v12, v20
	v_mul_f32_e32 v13, v13, v20
	v_mul_f32_e32 v14, v14, v20
	v_mul_f32_e32 v15, v15, v20
	v_mul_f32_e32 v8, v8, v20
	v_mul_f32_e32 v9, v9, v20
	v_mul_f32_e32 v10, v10, v20
	v_mul_f32_e32 v11, v11, v20
	v_mul_f32_e32 v4, v4, v20
	v_mul_f32_e32 v5, v5, v20
	v_mul_f32_e32 v6, v6, v20
	v_mul_f32_e32 v7, v7, v20
	v_mul_f32_e32 v21, v0, v20
	v_mul_f32_e32 v22, v1, v20
	v_mul_f32_e32 v23, v2, v20
	v_mul_f32_e32 v20, v3, v20
	v_cvt_pk_bf16_f32 v0, v12, v13
	v_cvt_pk_bf16_f32 v1, v14, v15
	v_cvt_pk_bf16_f32 v2, v8, v9
	v_cvt_pk_bf16_f32 v3, v10, v11
	s_mov_b64 s[0:1], -1
	global_store_dwordx4 v[18:19], v[0:3], off
	s_nop 1
	v_cvt_pk_bf16_f32 v0, v4, v5
	v_cvt_pk_bf16_f32 v1, v6, v7
	v_cvt_pk_bf16_f32 v2, v21, v22
	v_cvt_pk_bf16_f32 v3, v23, v20
	global_store_dwordx4 v[16:17], v[0:3], off offset:256
	s_cbranch_vccnz .LBB0_951
	s_andn2_b64 vcc, exec, s[10:11]
	s_cbranch_vccnz .LBB0_950
	s_barrier
	s_branch .LBB0_950

; __device__ __forceinline__ unsigned cvt_pk_bf16(float lo, float hi) { unsigned r; asm volatile("v_cvt_pk_bf16_f32 %0, %1, %2" : "=v"(r) : "v"(lo), "v"(hi)); return r; }
; __device__ __forceinline__ float sigmoidf_(float v) { return __builtin_amdgcn_rcpf(1.0f + __builtin_amdgcn_exp2f(-1.4426950408889634f * v)); }
; __device__ __forceinline__ float rstd_of(const float* ssq, int row) {
;     const f32x4* p = (const f32x4*)ssq + row; const f32x4 s = (p[0] + p[MROWS]) + (p[2 * MROWS] + p[3 * MROWS]);
;     return 1.0f / sqrtf(((s[0] + s[1]) + (s[2] + s[3])) * (1.0f / 1024.0f) + RMS_EPS); }
;     __device__ __forceinline__ void operator()(const f32x4 (&acc)[2][2][4][2], const Unit& u, int wr, int wc, int fr, int fq) const {
;         const int row0 = u.pm * BM + wr * 64 + fr, colh = u.pn * 128 + wc * 32 + 8 * fq;
; #pragma unroll
;         for (int ai = 0; ai < 2; ++ai)
; #pragma unroll
;             for (int m = 0; m < 4; ++m) {
;                 const int row = row0 + ai * HALF + m * 16;
;                 const float rs = ssq ? rstd_of(ssq, row) : 1.0f;
;                 float h[8];
; #pragma unroll
;                 for (int n = 0; n < 2; ++n)
; #pragma unroll
;                     for (int e = 0; e < 4; ++e) { const float g = acc[ai][0][m][n][e] * rs, uu = acc[ai][1][m][n][e] * rs; h[n * 4 + e] = g * sigmoidf_(g) * uu; }
;                 u32x4 w; w.x = cvt_pk_bf16(h[0], h[1]); w.y = cvt_pk_bf16(h[2], h[3]); w.z = cvt_pk_bf16(h[4], h[5]); w.w = cvt_pk_bf16(h[6], h[7]);
;                 *(u32x4*)(H + (size_t)row * DFF + colh) = w;
.LBB0_1160:
	v_lshl_add_u32 v144, s8, 8, v149
	v_ashrrev_i32_e32 v145, 31, v144
	v_cndmask_b32_e64 v146, 0, 1, s[84:85]
	v_mov_b32_e32 v148, 1.0
	v_cmp_ne_u32_e64 s[0:1], 1, v146
	s_andn2_b64 vcc, exec, s[84:85]
	v_lshl_add_u64 v[146:147], v[144:145], 4, s[24:25]
	v_mov_b32_e32 v150, 1.0
	s_cbranch_vccnz .LBB0_1162
	v_add_co_u32_e32 v162, vcc, 0xc0000, v146
	global_load_dwordx4 v[158:161], v[146:147], off
	s_nop 0
	v_addc_co_u32_e32 v163, vcc, 0, v147, vcc
	v_add_co_u32_e32 v166, vcc, 0x180000, v146
	s_nop 1
	v_addc_co_u32_e32 v167, vcc, 0, v147, vcc
	v_add_co_u32_e32 v170, vcc, 0x240000, v146
	global_load_dwordx4 v[162:165], v[162:163], off
	s_nop 0
	global_load_dwordx4 v[166:169], v[166:167], off
	v_addc_co_u32_e32 v171, vcc, 0, v147, vcc
	global_load_dwordx4 v[170:173], v[170:171], off
	s_waitcnt vmcnt(0)
	v_pk_add_f32 v[160:161], v[160:161], v[164:165]
	v_pk_add_f32 v[158:159], v[158:159], v[162:163]
	v_pk_add_f32 v[162:163], v[168:169], v[172:173]
	v_pk_add_f32 v[164:165], v[166:167], v[170:171]
	v_pk_add_f32 v[160:161], v[160:161], v[162:163]
	v_pk_add_f32 v[158:159], v[158:159], v[164:165]
	s_nop 0
	v_pk_mov_b32 v[162:163], v[158:159], v[160:161] op_sel:[1,0]
	v_mov_b32_e32 v159, v161
	v_pk_add_f32 v[158:159], v[162:163], v[158:159]
	s_nop 0
	v_add_f32_e32 v145, v158, v159
	v_fmamk_f32 v145, v145, 0x3a800000, v156
	v_rsq_f32_e32 v252, v145
	s_nop 0
	v_mul_f32_e32 v250, v145, v252
	v_fma_f32 v250, -v250, v252, 1.0
	v_mul_f32_e32 v251, 0.5, v252
	v_fma_f32 v150, v251, v250, v252
.LBB0_1162:
	v_mov_b32_e32 v158, v120
	v_mov_b32_e32 v159, v124
	v_pk_mul_f32 v[158:159], v[158:159], v[150:151] op_sel_hi:[1,0]
	v_mov_b32_e32 v124, v121
	v_mul_f32_e32 v120, 0xbfb8aa3b, v159
	v_exp_f32_e32 v145, v120
	v_pk_mul_f32 v[124:125], v[124:125], v[150:151] op_sel_hi:[1,0]
	s_and_b64 vcc, exec, s[0:1]
	v_mul_f32_e32 v120, 0xbfb8aa3b, v125
	v_exp_f32_e32 v121, v120
	v_add_f32_e32 v145, 1.0, v145
	v_rcp_f32_e32 v145, v145
	v_lshl_or_b32 v120, s44, 7, v152
	v_add_f32_e32 v121, 1.0, v121
	v_rcp_f32_e32 v160, v121
	v_mul_f32_e32 v145, v159, v145
	v_mul_f32_e32 v145, v158, v145
	v_mov_b32_e32 v158, v122
	v_mov_b32_e32 v159, v126
	v_pk_mul_f32 v[158:159], v[158:159], v[150:151] op_sel_hi:[1,0]
	v_mov_b32_e32 v126, v123
	v_mul_f32_e32 v122, 0xbfb8aa3b, v159
	v_mul_f32_e32 v125, v125, v160
	v_exp_f32_e32 v160, v122
	v_pk_mul_f32 v[122:123], v[126:127], v[150:151] op_sel_hi:[1,0]
	v_mul_f32_e32 v127, v124, v125
	v_mul_f32_e32 v126, 0xbfb8aa3b, v123
	v_exp_f32_e32 v126, v126
	v_add_f32_e32 v124, 1.0, v160
	v_rcp_f32_e32 v160, v124
	v_mov_b32_e32 v125, v116
	v_add_f32_e32 v124, 1.0, v126
	v_rcp_f32_e32 v126, v124
	v_mov_b32_e32 v124, v112
	v_pk_mul_f32 v[124:125], v[124:125], v[150:151] op_sel_hi:[1,0]
	v_mul_f32_e32 v116, v159, v160
	v_mul_f32_e32 v112, 0xbfb8aa3b, v125
	v_exp_f32_e32 v112, v112
	v_mul_f32_e32 v158, v158, v116
	v_mov_b32_e32 v116, v113
	v_mul_f32_e32 v123, v123, v126
	v_add_f32_e32 v112, 1.0, v112
	v_rcp_f32_e32 v126, v112
	v_pk_mul_f32 v[112:113], v[116:117], v[150:151] op_sel_hi:[1,0]
	v_mul_f32_e32 v122, v122, v123
	v_mul_f32_e32 v116, 0xbfb8aa3b, v113
	v_exp_f32_e32 v116, v116
	v_mul_f32_e32 v117, v125, v126
	v_mul_f32_e32 v123, v124, v117
	v_mov_b32_e32 v117, v118
	v_add_f32_e32 v116, 1.0, v116
	v_rcp_f32_e32 v124, v116
	v_mov_b32_e32 v116, v114
	v_pk_mul_f32 v[116:117], v[116:117], v[150:151] op_sel_hi:[1,0]
	v_mov_b32_e32 v118, v115
	v_mul_f32_e32 v114, 0xbfb8aa3b, v117
	v_exp_f32_e32 v125, v114
	v_pk_mul_f32 v[114:115], v[118:119], v[150:151] op_sel_hi:[1,0]
	v_mul_f32_e32 v113, v113, v124
	v_mul_f32_e32 v118, 0xbfb8aa3b, v115
	v_exp_f32_e32 v118, v118
	v_add_f32_e32 v119, 1.0, v125
	v_rcp_f32_e32 v119, v119
	v_mul_f32_e32 v124, v112, v113
	v_add_f32_e32 v118, 1.0, v118
	v_rcp_f32_e32 v118, v118
	v_mul_f32_e32 v112, v117, v119
	v_mul_f32_e32 v116, v116, v112
	v_ashrrev_i32_e32 v121, 31, v120
	v_mul_f32_e32 v112, v115, v118
	v_mul_f32_e32 v115, v114, v112
	v_cvt_pk_bf16_f32 v112, v145, v127
	v_cvt_pk_bf16_f32 v113, v158, v122
	v_cvt_pk_bf16_f32 v114, v123, v124
	v_cvt_pk_bf16_f32 v115, v116, v115
	v_mov_b64_e32 v[116:117], s[30:31]
	v_mad_i64_i32 v[116:117], s[8:9], v144, s60, v[116:117]
	v_lshl_add_u64 v[116:117], v[120:121], 1, v[116:117]
	global_store_dwordx4 v[116:117], v[112:115], off
	s_cbranch_vccnz .LBB0_1164
	v_add_co_u32_e32 v116, vcc, 0xc0000, v146
	global_load_dwordx4 v[112:115], v[146:147], off offset:256
	s_nop 0
	v_addc_co_u32_e32 v117, vcc, 0, v147, vcc
	v_add_co_u32_e32 v122, vcc, 0x180000, v146
	s_nop 1
	v_addc_co_u32_e32 v123, vcc, 0, v147, vcc
	v_add_co_u32_e32 v126, vcc, 0x240000, v146
	global_load_dwordx4 v[116:119], v[116:117], off offset:256
	s_nop 0
	global_load_dwordx4 v[122:125], v[122:123], off offset:256
	v_addc_co_u32_e32 v127, vcc, 0, v147, vcc
	global_load_dwordx4 v[158:161], v[126:127], off offset:256
	s_waitcnt vmcnt(0)
	v_pk_add_f32 v[114:115], v[114:115], v[118:119]
	v_pk_add_f32 v[112:113], v[112:113], v[116:117]
	v_pk_add_f32 v[116:117], v[124:125], v[160:161]
	v_pk_add_f32 v[118:119], v[122:123], v[158:159]
	v_pk_add_f32 v[114:115], v[114:115], v[116:117]
	v_pk_add_f32 v[112:113], v[112:113], v[118:119]
	s_nop 0
	v_pk_mov_b32 v[116:117], v[112:113], v[114:115] op_sel:[1,0]
	v_mov_b32_e32 v113, v115
	v_pk_add_f32 v[112:113], v[116:117], v[112:113]
	s_nop 0
	v_add_f32_e32 v112, v112, v113
	v_fmamk_f32 v112, v112, 0x3a800000, v156
	v_rsq_f32_e32 v252, v112
	s_nop 0
	v_mul_f32_e32 v250, v112, v252
	v_fma_f32 v250, -v250, v252, 1.0
	v_mul_f32_e32 v251, 0.5, v252
	v_fma_f32 v148, v251, v250, v252
; __device__ __forceinline__ unsigned cvt_pk_bf16(float lo, float hi) { unsigned r; asm volatile("v_cvt_pk_bf16_f32 %0, %1, %2" : "=v"(r) : "v"(lo), "v"(hi)); return r; }
; __device__ __forceinline__ float sigmoidf_(float v) { return __builtin_amdgcn_rcpf(1.0f + __builtin_amdgcn_exp2f(-1.4426950408889634f * v)); }
; __device__ __forceinline__ float rstd_of(const float* ssq, int row) {
;     const f32x4* p = (const f32x4*)ssq + row; const f32x4 s = (p[0] + p[MROWS]) + (p[2 * MROWS] + p[3 * MROWS]);
;     return 1.0f / sqrtf(((s[0] + s[1]) + (s[2] + s[3])) * (1.0f / 1024.0f) + RMS_EPS); }
;     __device__ __forceinline__ void operator()(const f32x4 (&acc)[2][2][4][2], const Unit& u, int wr, int wc, int fr, int fq) const {
;     ...
;             for (int m = 0; m < 4; ++m) {
;                 const int row = row0 + ai * HALF + m * 16;
;                 const float rs = ssq ? rstd_of(ssq, row) : 1.0f;
;                 float h[8];
; #pragma unroll
;                 for (int n = 0; n < 2; ++n)
; #pragma unroll
;                     for (int e = 0; e < 4; ++e) { const float g = acc[ai][0][m][n][e] * rs, uu = acc[ai][1][m][n][e] * rs; h[n * 4 + e] = g * sigmoidf_(g) * uu; }
;                 u32x4 w; w.x = cvt_pk_bf16(h[0], h[1]); w.y = cvt_pk_bf16(h[2], h[3]); w.z = cvt_pk_bf16(h[4], h[5]); w.w = cvt_pk_bf16(h[6], h[7]);
;                 *(u32x4*)(H + (size_t)row * DFF + colh) = w;
.LBB0_1164:
	s_nop 0
	v_mov_b32_e32 v112, v104
	v_mov_b32_e32 v113, v108
	v_pk_mul_f32 v[112:113], v[112:113], v[148:149] op_sel_hi:[1,0]
	v_mov_b32_e32 v108, v105
	v_mul_f32_e32 v104, 0xbfb8aa3b, v113
	v_exp_f32_e32 v104, v104
	v_pk_mul_f32 v[108:109], v[108:109], v[148:149] op_sel_hi:[1,0]
	v_or_b32_e32 v114, 16, v144
	v_mul_f32_e32 v105, 0xbfb8aa3b, v109
	v_exp_f32_e32 v105, v105
	v_add_f32_e32 v104, 1.0, v104
	v_rcp_f32_e32 v115, v104
	s_and_b64 vcc, exec, s[0:1]
	v_add_f32_e32 v104, 1.0, v105
	v_rcp_f32_e32 v105, v104
	v_mul_f32_e32 v113, v113, v115
	v_mul_f32_e32 v115, v112, v113
	v_mov_b32_e32 v112, v106
	v_mov_b32_e32 v113, v110
	v_pk_mul_f32 v[112:113], v[112:113], v[148:149] op_sel_hi:[1,0]
	v_mov_b32_e32 v110, v107
	v_mul_f32_e32 v106, 0xbfb8aa3b, v113
	v_mul_f32_e32 v105, v109, v105
	v_exp_f32_e32 v109, v106
	v_pk_mul_f32 v[106:107], v[110:111], v[148:149] op_sel_hi:[1,0]
	v_mul_f32_e32 v105, v108, v105
	v_mul_f32_e32 v110, 0xbfb8aa3b, v107
	v_exp_f32_e32 v110, v110
	v_add_f32_e32 v108, 1.0, v109
	v_rcp_f32_e32 v111, v108
	v_mov_b32_e32 v109, v100
	v_add_f32_e32 v108, 1.0, v110
	v_rcp_f32_e32 v110, v108
	v_mov_b32_e32 v108, v96
	v_pk_mul_f32 v[108:109], v[108:109], v[148:149] op_sel_hi:[1,0]
	v_mul_f32_e32 v100, v113, v111
	v_mul_f32_e32 v96, 0xbfb8aa3b, v109
	v_exp_f32_e32 v96, v96
	v_mul_f32_e32 v111, v112, v100
	v_mov_b32_e32 v100, v97
	v_mul_f32_e32 v107, v107, v110
	v_add_f32_e32 v96, 1.0, v96
	v_rcp_f32_e32 v110, v96
	v_pk_mul_f32 v[96:97], v[100:101], v[148:149] op_sel_hi:[1,0]
	v_mul_f32_e32 v106, v106, v107
	v_mul_f32_e32 v100, 0xbfb8aa3b, v97
	v_exp_f32_e32 v100, v100
	v_mul_f32_e32 v101, v109, v110
	v_mul_f32_e32 v107, v108, v101
	v_mov_b32_e32 v101, v102
	v_add_f32_e32 v100, 1.0, v100
	v_rcp_f32_e32 v108, v100
	v_mov_b32_e32 v100, v98
	v_pk_mul_f32 v[100:101], v[100:101], v[148:149] op_sel_hi:[1,0]
	v_mov_b32_e32 v102, v99
	v_mul_f32_e32 v98, 0xbfb8aa3b, v101
	v_exp_f32_e32 v109, v98
	v_pk_mul_f32 v[98:99], v[102:103], v[148:149] op_sel_hi:[1,0]
	v_mul_f32_e32 v97, v97, v108
	v_mul_f32_e32 v102, 0xbfb8aa3b, v99
	v_exp_f32_e32 v102, v102
	v_add_f32_e32 v103, 1.0, v109
	v_rcp_f32_e32 v103, v103
	v_mul_f32_e32 v108, v96, v97
	v_add_f32_e32 v102, 1.0, v102
	v_rcp_f32_e32 v102, v102
	v_mul_f32_e32 v96, v101, v103
	v_mul_f32_e32 v100, v100, v96
	v_mov_b32_e32 v104, 1.0
	v_mul_f32_e32 v96, v99, v102
	v_mul_f32_e32 v99, v98, v96
	v_cvt_pk_bf16_f32 v96, v115, v105
	v_cvt_pk_bf16_f32 v97, v111, v106
	v_cvt_pk_bf16_f32 v98, v107, v108
	v_cvt_pk_bf16_f32 v99, v100, v99
	v_mov_b64_e32 v[100:101], s[30:31]
	v_mad_i64_i32 v[100:101], s[8:9], v114, s60, v[100:101]
	v_lshl_add_u64 v[100:101], v[120:121], 1, v[100:101]
	global_store_dwordx4 v[100:101], v[96:99], off
	s_nop 1
	v_mov_b32_e32 v96, 1.0
	s_cbranch_vccnz .LBB0_1166
	v_add_co_u32_e32 v100, vcc, 0xc0000, v146
	global_load_dwordx4 v[96:99], v[146:147], off offset:512
	s_nop 0
	v_addc_co_u32_e32 v101, vcc, 0, v147, vcc
	v_add_co_u32_e32 v106, vcc, 0x180000, v146
	s_nop 1
	v_addc_co_u32_e32 v107, vcc, 0, v147, vcc
	v_add_co_u32_e32 v110, vcc, 0x240000, v146
	global_load_dwordx4 v[100:103], v[100:101], off offset:512
	s_nop 0
	global_load_dwordx4 v[106:109], v[106:107], off offset:512
	v_addc_co_u32_e32 v111, vcc, 0, v147, vcc
	global_load_dwordx4 v[110:113], v[110:111], off offset:512
	s_waitcnt vmcnt(0)
	v_pk_add_f32 v[98:99], v[98:99], v[102:103]
	v_pk_add_f32 v[96:97], v[96:97], v[100:101]
	v_pk_add_f32 v[100:101], v[108:109], v[112:113]
	v_pk_add_f32 v[102:103], v[106:107], v[110:111]
	v_pk_add_f32 v[98:99], v[98:99], v[100:101]
	v_pk_add_f32 v[96:97], v[96:97], v[102:103]
	s_nop 0
	v_pk_mov_b32 v[100:101], v[96:97], v[98:99] op_sel:[1,0]
	v_mov_b32_e32 v97, v99
	v_pk_add_f32 v[96:97], v[100:101], v[96:97]
	s_nop 0
	v_add_f32_e32 v96, v96, v97
	v_fmamk_f32 v96, v96, 0x3a800000, v156
	v_rsq_f32_e32 v252, v96
	s_nop 0
	v_mul_f32_e32 v250, v96, v252
	v_fma_f32 v250, -v250, v252, 1.0
	v_mul_f32_e32 v251, 0.5, v252
	v_fma_f32 v96, v251, v250, v252
.LBB0_1166:
	v_mov_b32_e32 v98, v88
	v_mov_b32_e32 v99, v92
	v_pk_mul_f32 v[98:99], v[98:99], v[96:97] op_sel_hi:[1,0]
	v_mov_b32_e32 v92, v89
	v_mul_f32_e32 v88, 0xbfb8aa3b, v99
	v_exp_f32_e32 v97, v88
	s_and_b64 vcc, exec, s[0:1]
	v_pk_mul_f32 v[88:89], v[92:93], v[96:97] op_sel_hi:[1,0]
	s_nop 0
	v_mul_f32_e32 v92, 0xbfb8aa3b, v89
	v_exp_f32_e32 v92, v92
	v_add_f32_e32 v93, 1.0, v97
	v_rcp_f32_e32 v93, v93
	v_or_b32_e32 v97, 32, v144
	v_add_f32_e32 v92, 1.0, v92
	v_rcp_f32_e32 v92, v92
	v_mul_f32_e32 v93, v99, v93
	v_mul_f32_e32 v98, v98, v93
	v_mov_b32_e32 v93, v94
	v_mul_f32_e32 v89, v89, v92
	v_mov_b32_e32 v92, v90
	v_pk_mul_f32 v[92:93], v[92:93], v[96:97] op_sel_hi:[1,0]
	v_mov_b32_e32 v94, v91
	v_mul_f32_e32 v90, 0xbfb8aa3b, v93
	v_exp_f32_e32 v99, v90
	v_pk_mul_f32 v[90:91], v[94:95], v[96:97] op_sel_hi:[1,0]
	v_mul_f32_e32 v95, v88, v89
	v_mul_f32_e32 v94, 0xbfb8aa3b, v91
	v_exp_f32_e32 v94, v94
	v_add_f32_e32 v88, 1.0, v99
	v_rcp_f32_e32 v99, v88
	v_mov_b32_e32 v89, v84
	v_add_f32_e32 v88, 1.0, v94
	v_rcp_f32_e32 v94, v88
	v_mov_b32_e32 v88, v80
	v_pk_mul_f32 v[88:89], v[88:89], v[96:97] op_sel_hi:[1,0]
	v_mul_f32_e32 v84, v93, v99
	v_mul_f32_e32 v80, 0xbfb8aa3b, v89
	v_exp_f32_e32 v80, v80
	v_mul_f32_e32 v92, v92, v84
	v_mov_b32_e32 v84, v81
	v_mul_f32_e32 v91, v91, v94
	v_add_f32_e32 v80, 1.0, v80
	v_rcp_f32_e32 v93, v80
	v_pk_mul_f32 v[80:81], v[84:85], v[96:97] op_sel_hi:[1,0]
	v_mul_f32_e32 v90, v90, v91
	v_mul_f32_e32 v84, 0xbfb8aa3b, v81
	v_exp_f32_e32 v84, v84
	v_mul_f32_e32 v85, v89, v93
	v_mul_f32_e32 v88, v88, v85
	v_mov_b32_e32 v85, v86
	v_add_f32_e32 v84, 1.0, v84
	v_rcp_f32_e32 v89, v84
	v_mov_b32_e32 v84, v82
	v_pk_mul_f32 v[84:85], v[84:85], v[96:97] op_sel_hi:[1,0]
	v_mov_b32_e32 v86, v83
	v_mul_f32_e32 v82, 0xbfb8aa3b, v85
	v_exp_f32_e32 v91, v82
	v_pk_mul_f32 v[82:83], v[86:87], v[96:97] op_sel_hi:[1,0]
	v_mul_f32_e32 v81, v81, v89
	v_mul_f32_e32 v86, 0xbfb8aa3b, v83
	v_exp_f32_e32 v86, v86
	v_add_f32_e32 v87, 1.0, v91
	v_rcp_f32_e32 v87, v87
	v_mul_f32_e32 v89, v80, v81
	v_add_f32_e32 v86, 1.0, v86
	v_rcp_f32_e32 v86, v86
	v_mul_f32_e32 v80, v85, v87
	v_mul_f32_e32 v84, v84, v80
	v_mul_f32_e32 v80, v83, v86
	v_mul_f32_e32 v83, v82, v80
	v_cvt_pk_bf16_f32 v80, v98, v95
	v_cvt_pk_bf16_f32 v81, v92, v90
	v_cvt_pk_bf16_f32 v82, v88, v89
	v_cvt_pk_bf16_f32 v83, v84, v83
	v_mov_b64_e32 v[84:85], s[30:31]
	v_mad_i64_i32 v[84:85], s[8:9], v97, s60, v[84:85]
	v_lshl_add_u64 v[84:85], v[120:121], 1, v[84:85]
	global_store_dwordx4 v[84:85], v[80:83], off
	s_cbranch_vccnz .LBB0_1168
; __device__ __forceinline__ unsigned cvt_pk_bf16(float lo, float hi) { unsigned r; asm volatile("v_cvt_pk_bf16_f32 %0, %1, %2" : "=v"(r) : "v"(lo), "v"(hi)); return r; }
; __device__ __forceinline__ float sigmoidf_(float v) { return __builtin_amdgcn_rcpf(1.0f + __builtin_amdgcn_exp2f(-1.4426950408889634f * v)); }
; __device__ __forceinline__ float rstd_of(const float* ssq, int row) {
;     const f32x4* p = (const f32x4*)ssq + row; const f32x4 s = (p[0] + p[MROWS]) + (p[2 * MROWS] + p[3 * MROWS]);
;     return 1.0f / sqrtf(((s[0] + s[1]) + (s[2] + s[3])) * (1.0f / 1024.0f) + RMS_EPS); }
;     __device__ __forceinline__ void operator()(const f32x4 (&acc)[2][2][4][2], const Unit& u, int wr, int wc, int fr, int fq) const {
;         const int row0 = u.pm * BM + wr * 64 + fr, colh = u.pn * 128 + wc * 32 + 8 * fq;
; #pragma unroll
;         for (int ai = 0; ai < 2; ++ai)
; #pragma unroll
;             for (int m = 0; m < 4; ++m) {
;                 const int row = row0 + ai * HALF + m * 16;
;                 const float rs = ssq ? rstd_of(ssq, row) : 1.0f;
;                 float h[8];
; #pragma unroll
;                 for (int n = 0; n < 2; ++n)
; #pragma unroll
;                     for (int e = 0; e < 4; ++e) { const float g = acc[ai][0][m][n][e] * rs, uu = acc[ai][1][m][n][e] * rs; h[n * 4 + e] = g * sigmoidf_(g) * uu; }
;                 u32x4 w; w.x = cvt_pk_bf16(h[0], h[1]); w.y = cvt_pk_bf16(h[2], h[3]); w.z = cvt_pk_bf16(h[4], h[5]); w.w = cvt_pk_bf16(h[6], h[7]);
;                 *(u32x4*)(H + (size_t)row * DFF + colh) = w;
	v_add_co_u32_e32 v84, vcc, 0xc0000, v146
	global_load_dwordx4 v[80:83], v[146:147], off offset:768
	s_nop 0
	v_addc_co_u32_e32 v85, vcc, 0, v147, vcc
	v_add_co_u32_e32 v88, vcc, 0x180000, v146
	s_nop 1
	v_addc_co_u32_e32 v89, vcc, 0, v147, vcc
	v_add_co_u32_e32 v92, vcc, 0x240000, v146
	global_load_dwordx4 v[84:87], v[84:85], off offset:768
	s_nop 0
	global_load_dwordx4 v[88:91], v[88:89], off offset:768
	v_addc_co_u32_e32 v93, vcc, 0, v147, vcc
	global_load_dwordx4 v[92:95], v[92:93], off offset:768
	s_waitcnt vmcnt(0)
	v_pk_add_f32 v[82:83], v[82:83], v[86:87]
	v_pk_add_f32 v[80:81], v[80:81], v[84:85]
	v_pk_add_f32 v[84:85], v[90:91], v[94:95]
	v_pk_add_f32 v[86:87], v[88:89], v[92:93]
	v_pk_add_f32 v[82:83], v[82:83], v[84:85]
	v_pk_add_f32 v[80:81], v[80:81], v[86:87]
	s_nop 0
	v_pk_mov_b32 v[84:85], v[80:81], v[82:83] op_sel:[1,0]
	v_mov_b32_e32 v81, v83
	v_pk_add_f32 v[80:81], v[84:85], v[80:81]
	s_nop 0
	v_add_f32_e32 v80, v80, v81
	v_fmamk_f32 v80, v80, 0x3a800000, v156
	v_rsq_f32_e32 v252, v80
	s_nop 0
	v_mul_f32_e32 v250, v80, v252
	v_fma_f32 v250, -v250, v252, 1.0
	v_mul_f32_e32 v251, 0.5, v252
	v_fma_f32 v104, v251, v250, v252
.LBB0_1168:
	s_nop 0
	v_mov_b32_e32 v80, v72
	v_mov_b32_e32 v81, v76
	v_pk_mul_f32 v[80:81], v[80:81], v[104:105] op_sel_hi:[1,0]
	v_mov_b32_e32 v76, v73
	v_mul_f32_e32 v72, 0xbfb8aa3b, v81
	v_exp_f32_e32 v72, v72
	v_pk_mul_f32 v[76:77], v[76:77], v[104:105] op_sel_hi:[1,0]
	v_or_b32_e32 v82, 48, v144
	v_mul_f32_e32 v73, 0xbfb8aa3b, v77
	v_exp_f32_e32 v73, v73
	v_add_f32_e32 v72, 1.0, v72
	v_rcp_f32_e32 v83, v72
	s_and_b64 vcc, exec, s[0:1]
	v_add_f32_e32 v72, 1.0, v73
	v_rcp_f32_e32 v73, v72
	v_mul_f32_e32 v81, v81, v83
	v_mul_f32_e32 v83, v80, v81
	v_mov_b32_e32 v80, v74
	v_mov_b32_e32 v81, v78
	v_pk_mul_f32 v[80:81], v[80:81], v[104:105] op_sel_hi:[1,0]
	v_mov_b32_e32 v78, v75
	v_mul_f32_e32 v74, 0xbfb8aa3b, v81
	v_mul_f32_e32 v73, v77, v73
	v_exp_f32_e32 v77, v74
	v_pk_mul_f32 v[74:75], v[78:79], v[104:105] op_sel_hi:[1,0]
	v_mul_f32_e32 v73, v76, v73
	v_mul_f32_e32 v78, 0xbfb8aa3b, v75
	v_exp_f32_e32 v78, v78
	v_add_f32_e32 v76, 1.0, v77
	v_rcp_f32_e32 v79, v76
	v_mov_b32_e32 v77, v68
	v_add_f32_e32 v76, 1.0, v78
	v_rcp_f32_e32 v78, v76
	v_mov_b32_e32 v76, v64
	v_pk_mul_f32 v[76:77], v[76:77], v[104:105] op_sel_hi:[1,0]
	v_mul_f32_e32 v68, v81, v79
	v_mul_f32_e32 v64, 0xbfb8aa3b, v77
	v_exp_f32_e32 v64, v64
	v_mul_f32_e32 v79, v80, v68
	v_mov_b32_e32 v68, v65
	v_mul_f32_e32 v75, v75, v78
	v_add_f32_e32 v64, 1.0, v64
	v_rcp_f32_e32 v78, v64
	v_pk_mul_f32 v[64:65], v[68:69], v[104:105] op_sel_hi:[1,0]
	v_mul_f32_e32 v74, v74, v75
	v_mul_f32_e32 v68, 0xbfb8aa3b, v65
	v_exp_f32_e32 v68, v68
	v_mul_f32_e32 v69, v77, v78
	v_mul_f32_e32 v75, v76, v69
	v_mov_b32_e32 v69, v70
	v_add_f32_e32 v68, 1.0, v68
	v_rcp_f32_e32 v76, v68
	v_mov_b32_e32 v68, v66
	v_pk_mul_f32 v[68:69], v[68:69], v[104:105] op_sel_hi:[1,0]
	v_mov_b32_e32 v70, v67
	v_mul_f32_e32 v66, 0xbfb8aa3b, v69
	v_exp_f32_e32 v77, v66
	v_pk_mul_f32 v[66:67], v[70:71], v[104:105] op_sel_hi:[1,0]
	v_mul_f32_e32 v65, v65, v76
	v_mul_f32_e32 v70, 0xbfb8aa3b, v67
	v_exp_f32_e32 v70, v70
	v_add_f32_e32 v71, 1.0, v77
	v_rcp_f32_e32 v71, v71
	v_mul_f32_e32 v76, v64, v65
	v_add_f32_e32 v70, 1.0, v70
	v_rcp_f32_e32 v70, v70
	v_mul_f32_e32 v64, v69, v71
	v_mul_f32_e32 v68, v68, v64
	v_mov_b32_e32 v72, 1.0
	v_mul_f32_e32 v64, v67, v70
	v_mul_f32_e32 v67, v66, v64
	v_cvt_pk_bf16_f32 v64, v83, v73
	v_cvt_pk_bf16_f32 v65, v79, v74
	v_cvt_pk_bf16_f32 v66, v75, v76
	v_cvt_pk_bf16_f32 v67, v68, v67
	v_mov_b64_e32 v[68:69], s[30:31]
	v_mad_i64_i32 v[68:69], s[8:9], v82, s60, v[68:69]
	v_lshl_add_u64 v[68:69], v[120:121], 1, v[68:69]
	global_store_dwordx4 v[68:69], v[64:67], off
	s_nop 1
	v_mov_b32_e32 v64, 1.0
	s_cbranch_vccnz .LBB0_1170
	v_add_co_u32_e32 v68, vcc, 0xc0000, v146
	global_load_dwordx4 v[64:67], v[146:147], off offset:2048
	s_nop 0
	v_addc_co_u32_e32 v69, vcc, 0, v147, vcc
	v_add_co_u32_e32 v74, vcc, 0x180000, v146
	s_nop 1
	v_addc_co_u32_e32 v75, vcc, 0, v147, vcc
	v_add_co_u32_e32 v78, vcc, 0x240000, v146
	global_load_dwordx4 v[68:71], v[68:69], off offset:2048
	s_nop 0
	global_load_dwordx4 v[74:77], v[74:75], off offset:2048
	v_addc_co_u32_e32 v79, vcc, 0, v147, vcc
	global_load_dwordx4 v[78:81], v[78:79], off offset:2048
	s_waitcnt vmcnt(0)
	v_pk_add_f32 v[66:67], v[66:67], v[70:71]
	v_pk_add_f32 v[64:65], v[64:65], v[68:69]
	v_pk_add_f32 v[68:69], v[76:77], v[80:81]
	v_pk_add_f32 v[70:71], v[74:75], v[78:79]
	v_pk_add_f32 v[66:67], v[66:67], v[68:69]
	v_pk_add_f32 v[64:65], v[64:65], v[70:71]
	s_nop 0
	v_pk_mov_b32 v[68:69], v[64:65], v[66:67] op_sel:[1,0]
	v_mov_b32_e32 v65, v67
	v_pk_add_f32 v[64:65], v[68:69], v[64:65]
	s_nop 0
	v_add_f32_e32 v64, v64, v65
	v_fmamk_f32 v64, v64, 0x3a800000, v156
	v_rsq_f32_e32 v252, v64
	s_nop 0
	v_mul_f32_e32 v250, v64, v252
	v_fma_f32 v250, -v250, v252, 1.0
	v_mul_f32_e32 v251, 0.5, v252
	v_fma_f32 v64, v251, v250, v252
; __device__ __forceinline__ unsigned cvt_pk_bf16(float lo, float hi) { unsigned r; asm volatile("v_cvt_pk_bf16_f32 %0, %1, %2" : "=v"(r) : "v"(lo), "v"(hi)); return r; }
; __device__ __forceinline__ float sigmoidf_(float v) { return __builtin_amdgcn_rcpf(1.0f + __builtin_amdgcn_exp2f(-1.4426950408889634f * v)); }
; __device__ __forceinline__ float rstd_of(const float* ssq, int row) {
;     const f32x4* p = (const f32x4*)ssq + row; const f32x4 s = (p[0] + p[MROWS]) + (p[2 * MROWS] + p[3 * MROWS]);
;     return 1.0f / sqrtf(((s[0] + s[1]) + (s[2] + s[3])) * (1.0f / 1024.0f) + RMS_EPS); }
;     __device__ __forceinline__ void operator()(const f32x4 (&acc)[2][2][4][2], const Unit& u, int wr, int wc, int fr, int fq) const {
;         const int row0 = u.pm * BM + wr * 64 + fr, colh = u.pn * 128 + wc * 32 + 8 * fq;
; #pragma unroll
;         for (int ai = 0; ai < 2; ++ai)
; #pragma unroll
;             for (int m = 0; m < 4; ++m) {
;                 const int row = row0 + ai * HALF + m * 16;
;                 const float rs = ssq ? rstd_of(ssq, row) : 1.0f;
;                 float h[8];
; #pragma unroll
;                 for (int n = 0; n < 2; ++n)
; #pragma unroll
;                     for (int e = 0; e < 4; ++e) { const float g = acc[ai][0][m][n][e] * rs, uu = acc[ai][1][m][n][e] * rs; h[n * 4 + e] = g * sigmoidf_(g) * uu; }
;                 u32x4 w; w.x = cvt_pk_bf16(h[0], h[1]); w.y = cvt_pk_bf16(h[2], h[3]); w.z = cvt_pk_bf16(h[4], h[5]); w.w = cvt_pk_bf16(h[6], h[7]);
;                 *(u32x4*)(H + (size_t)row * DFF + colh) = w;
.LBB0_1170:
	v_mov_b32_e32 v66, v56
	v_mov_b32_e32 v67, v60
	v_pk_mul_f32 v[66:67], v[66:67], v[64:65] op_sel_hi:[1,0]
	v_mov_b32_e32 v60, v57
	v_mul_f32_e32 v56, 0xbfb8aa3b, v67
	v_exp_f32_e32 v65, v56
	s_and_b64 vcc, exec, s[0:1]
	v_pk_mul_f32 v[56:57], v[60:61], v[64:65] op_sel_hi:[1,0]
	s_nop 0
	v_mul_f32_e32 v60, 0xbfb8aa3b, v57
	v_exp_f32_e32 v60, v60
	v_add_f32_e32 v61, 1.0, v65
	v_rcp_f32_e32 v61, v61
	v_add_u32_e32 v65, 0x80, v144
	v_add_f32_e32 v60, 1.0, v60
	v_rcp_f32_e32 v60, v60
	v_mul_f32_e32 v61, v67, v61
	v_mul_f32_e32 v66, v66, v61
	v_mov_b32_e32 v61, v62
	v_mul_f32_e32 v57, v57, v60
	v_mov_b32_e32 v60, v58
	v_pk_mul_f32 v[60:61], v[60:61], v[64:65] op_sel_hi:[1,0]
	v_mov_b32_e32 v62, v59
	v_mul_f32_e32 v58, 0xbfb8aa3b, v61
	v_exp_f32_e32 v67, v58
	v_pk_mul_f32 v[58:59], v[62:63], v[64:65] op_sel_hi:[1,0]
	v_mul_f32_e32 v63, v56, v57
	v_mul_f32_e32 v62, 0xbfb8aa3b, v59
	v_exp_f32_e32 v62, v62
	v_add_f32_e32 v56, 1.0, v67
	v_rcp_f32_e32 v67, v56
	v_mov_b32_e32 v57, v52
	v_add_f32_e32 v56, 1.0, v62
	v_rcp_f32_e32 v62, v56
	v_mov_b32_e32 v56, v48
	v_pk_mul_f32 v[56:57], v[56:57], v[64:65] op_sel_hi:[1,0]
	v_mul_f32_e32 v52, v61, v67
	v_mul_f32_e32 v48, 0xbfb8aa3b, v57
	v_exp_f32_e32 v48, v48
	v_mul_f32_e32 v60, v60, v52
	v_mov_b32_e32 v52, v49
	v_mul_f32_e32 v59, v59, v62
	v_add_f32_e32 v48, 1.0, v48
	v_rcp_f32_e32 v61, v48
	v_pk_mul_f32 v[48:49], v[52:53], v[64:65] op_sel_hi:[1,0]
	v_mul_f32_e32 v58, v58, v59
	v_mul_f32_e32 v52, 0xbfb8aa3b, v49
	v_exp_f32_e32 v52, v52
	v_mul_f32_e32 v53, v57, v61
	v_mul_f32_e32 v56, v56, v53
	v_mov_b32_e32 v53, v54
	v_add_f32_e32 v52, 1.0, v52
	v_rcp_f32_e32 v57, v52
	v_mov_b32_e32 v52, v50
	v_pk_mul_f32 v[52:53], v[52:53], v[64:65] op_sel_hi:[1,0]
	v_mov_b32_e32 v54, v51
	v_mul_f32_e32 v50, 0xbfb8aa3b, v53
	v_exp_f32_e32 v59, v50
	v_pk_mul_f32 v[50:51], v[54:55], v[64:65] op_sel_hi:[1,0]
	v_mul_f32_e32 v49, v49, v57
	v_mul_f32_e32 v54, 0xbfb8aa3b, v51
	v_exp_f32_e32 v54, v54
	v_add_f32_e32 v55, 1.0, v59
	v_rcp_f32_e32 v55, v55
	v_mul_f32_e32 v57, v48, v49
	v_add_f32_e32 v54, 1.0, v54
	v_rcp_f32_e32 v54, v54
	v_mul_f32_e32 v48, v53, v55
	v_mul_f32_e32 v52, v52, v48
	v_mul_f32_e32 v48, v51, v54
	v_mul_f32_e32 v51, v50, v48
	v_cvt_pk_bf16_f32 v48, v66, v63
	v_cvt_pk_bf16_f32 v49, v60, v58
	v_cvt_pk_bf16_f32 v50, v56, v57
	v_cvt_pk_bf16_f32 v51, v52, v51
	v_mov_b64_e32 v[52:53], s[30:31]
	v_mad_i64_i32 v[52:53], s[8:9], v65, s60, v[52:53]
	v_lshl_add_u64 v[52:53], v[120:121], 1, v[52:53]
	global_store_dwordx4 v[52:53], v[48:51], off
	s_cbranch_vccnz .LBB0_1172
	v_add_co_u32_e32 v52, vcc, 0xc0000, v146
	global_load_dwordx4 v[48:51], v[146:147], off offset:2304
	s_nop 0
	v_addc_co_u32_e32 v53, vcc, 0, v147, vcc
	v_add_co_u32_e32 v56, vcc, 0x180000, v146
	s_nop 1
	v_addc_co_u32_e32 v57, vcc, 0, v147, vcc
	v_add_co_u32_e32 v60, vcc, 0x240000, v146
	global_load_dwordx4 v[52:55], v[52:53], off offset:2304
	s_nop 0
	global_load_dwordx4 v[56:59], v[56:57], off offset:2304
	v_addc_co_u32_e32 v61, vcc, 0, v147, vcc
	global_load_dwordx4 v[60:63], v[60:61], off offset:2304
	s_waitcnt vmcnt(0)
	v_pk_add_f32 v[50:51], v[50:51], v[54:55]
	v_pk_add_f32 v[48:49], v[48:49], v[52:53]
	v_pk_add_f32 v[52:53], v[58:59], v[62:63]
	v_pk_add_f32 v[54:55], v[56:57], v[60:61]
	v_pk_add_f32 v[50:51], v[50:51], v[52:53]
	v_pk_add_f32 v[48:49], v[48:49], v[54:55]
	s_nop 0
	v_pk_mov_b32 v[52:53], v[48:49], v[50:51] op_sel:[1,0]
	v_mov_b32_e32 v49, v51
	v_pk_add_f32 v[48:49], v[52:53], v[48:49]
	s_nop 0
	v_add_f32_e32 v48, v48, v49
	v_fmamk_f32 v48, v48, 0x3a800000, v156
	v_rsq_f32_e32 v252, v48
	s_nop 0
	v_mul_f32_e32 v250, v48, v252
	v_fma_f32 v250, -v250, v252, 1.0
	v_mul_f32_e32 v251, 0.5, v252
	v_fma_f32 v72, v251, v250, v252
.LBB0_1172:
	s_nop 0
	v_mov_b32_e32 v48, v40
	v_mov_b32_e32 v49, v44
	v_pk_mul_f32 v[48:49], v[48:49], v[72:73] op_sel_hi:[1,0]
	v_mov_b32_e32 v44, v41
	v_mul_f32_e32 v40, 0xbfb8aa3b, v49
	v_exp_f32_e32 v40, v40
	v_pk_mul_f32 v[44:45], v[44:45], v[72:73] op_sel_hi:[1,0]
	v_add_u32_e32 v50, 0x90, v144
	v_mul_f32_e32 v41, 0xbfb8aa3b, v45
	v_exp_f32_e32 v41, v41
	v_add_f32_e32 v40, 1.0, v40
	v_rcp_f32_e32 v51, v40
	s_and_b64 vcc, exec, s[0:1]
	v_add_f32_e32 v40, 1.0, v41
	v_rcp_f32_e32 v41, v40
	v_mul_f32_e32 v49, v49, v51
	v_mul_f32_e32 v51, v48, v49
	v_mov_b32_e32 v48, v42
	v_mov_b32_e32 v49, v46
	v_pk_mul_f32 v[48:49], v[48:49], v[72:73] op_sel_hi:[1,0]
	v_mov_b32_e32 v46, v43
	v_mul_f32_e32 v42, 0xbfb8aa3b, v49
	v_mul_f32_e32 v41, v45, v41
	v_exp_f32_e32 v45, v42
	v_pk_mul_f32 v[42:43], v[46:47], v[72:73] op_sel_hi:[1,0]
	v_mul_f32_e32 v41, v44, v41
	v_mul_f32_e32 v46, 0xbfb8aa3b, v43
	v_exp_f32_e32 v46, v46
	v_add_f32_e32 v44, 1.0, v45
	v_rcp_f32_e32 v47, v44
	v_mov_b32_e32 v45, v36
	v_add_f32_e32 v44, 1.0, v46
	v_rcp_f32_e32 v46, v44
	v_mov_b32_e32 v44, v32
	v_pk_mul_f32 v[44:45], v[44:45], v[72:73] op_sel_hi:[1,0]
	v_mul_f32_e32 v36, v49, v47
	v_mul_f32_e32 v32, 0xbfb8aa3b, v45
	v_exp_f32_e32 v32, v32
	v_mul_f32_e32 v47, v48, v36
	v_mov_b32_e32 v36, v33
	v_mul_f32_e32 v43, v43, v46
	v_add_f32_e32 v32, 1.0, v32
	v_rcp_f32_e32 v46, v32
	v_pk_mul_f32 v[32:33], v[36:37], v[72:73] op_sel_hi:[1,0]
	v_mul_f32_e32 v42, v42, v43
	v_mul_f32_e32 v36, 0xbfb8aa3b, v33
	v_exp_f32_e32 v36, v36
	v_mul_f32_e32 v37, v45, v46
	v_mul_f32_e32 v43, v44, v37
	v_mov_b32_e32 v37, v38
	v_add_f32_e32 v36, 1.0, v36
	v_rcp_f32_e32 v44, v36
	v_mov_b32_e32 v36, v34
	v_pk_mul_f32 v[36:37], v[36:37], v[72:73] op_sel_hi:[1,0]
	v_mov_b32_e32 v38, v35
	v_mul_f32_e32 v34, 0xbfb8aa3b, v37
	v_exp_f32_e32 v45, v34
	v_pk_mul_f32 v[34:35], v[38:39], v[72:73] op_sel_hi:[1,0]
	v_mul_f32_e32 v33, v33, v44
	v_mul_f32_e32 v38, 0xbfb8aa3b, v35
	v_exp_f32_e32 v38, v38
	v_add_f32_e32 v39, 1.0, v45
	v_rcp_f32_e32 v39, v39
	v_mul_f32_e32 v44, v32, v33
	v_add_f32_e32 v38, 1.0, v38
	v_rcp_f32_e32 v38, v38
	v_mul_f32_e32 v32, v37, v39
	v_mul_f32_e32 v36, v36, v32
	v_mov_b32_e32 v40, 1.0
	v_mul_f32_e32 v32, v35, v38
	v_mul_f32_e32 v35, v34, v32
	v_cvt_pk_bf16_f32 v32, v51, v41
	v_cvt_pk_bf16_f32 v33, v47, v42
	v_cvt_pk_bf16_f32 v34, v43, v44
	v_cvt_pk_bf16_f32 v35, v36, v35
	v_mov_b64_e32 v[36:37], s[30:31]
	v_mad_i64_i32 v[36:37], s[8:9], v50, s60, v[36:37]
	v_lshl_add_u64 v[36:37], v[120:121], 1, v[36:37]
	global_store_dwordx4 v[36:37], v[32:35], off
	s_nop 1
	v_mov_b32_e32 v32, 1.0
	s_cbranch_vccnz .LBB0_1174
; __device__ __forceinline__ unsigned cvt_pk_bf16(float lo, float hi) { unsigned r; asm volatile("v_cvt_pk_bf16_f32 %0, %1, %2" : "=v"(r) : "v"(lo), "v"(hi)); return r; }
; __device__ __forceinline__ float sigmoidf_(float v) { return __builtin_amdgcn_rcpf(1.0f + __builtin_amdgcn_exp2f(-1.4426950408889634f * v)); }
; __device__ __forceinline__ float rstd_of(const float* ssq, int row) {
;     const f32x4* p = (const f32x4*)ssq + row; const f32x4 s = (p[0] + p[MROWS]) + (p[2 * MROWS] + p[3 * MROWS]);
;     return 1.0f / sqrtf(((s[0] + s[1]) + (s[2] + s[3])) * (1.0f / 1024.0f) + RMS_EPS); }
;     __device__ __forceinline__ void operator()(const f32x4 (&acc)[2][2][4][2], const Unit& u, int wr, int wc, int fr, int fq) const {
;         const int row0 = u.pm * BM + wr * 64 + fr, colh = u.pn * 128 + wc * 32 + 8 * fq;
; #pragma unroll
;         for (int ai = 0; ai < 2; ++ai)
; #pragma unroll
;             for (int m = 0; m < 4; ++m) {
;                 const int row = row0 + ai * HALF + m * 16;
;                 const float rs = ssq ? rstd_of(ssq, row) : 1.0f;
;                 float h[8];
; #pragma unroll
;                 for (int n = 0; n < 2; ++n)
; #pragma unroll
;                     for (int e = 0; e < 4; ++e) { const float g = acc[ai][0][m][n][e] * rs, uu = acc[ai][1][m][n][e] * rs; h[n * 4 + e] = g * sigmoidf_(g) * uu; }
;                 u32x4 w; w.x = cvt_pk_bf16(h[0], h[1]); w.y = cvt_pk_bf16(h[2], h[3]); w.z = cvt_pk_bf16(h[4], h[5]); w.w = cvt_pk_bf16(h[6], h[7]);
;                 *(u32x4*)(H + (size_t)row * DFF + colh) = w;
	v_add_co_u32_e32 v36, vcc, 0xc0000, v146
	global_load_dwordx4 v[32:35], v[146:147], off offset:2560
	s_nop 0
	v_addc_co_u32_e32 v37, vcc, 0, v147, vcc
	v_add_co_u32_e32 v42, vcc, 0x180000, v146
	s_nop 1
	v_addc_co_u32_e32 v43, vcc, 0, v147, vcc
	v_add_co_u32_e32 v46, vcc, 0x240000, v146
	global_load_dwordx4 v[36:39], v[36:37], off offset:2560
	s_nop 0
	global_load_dwordx4 v[42:45], v[42:43], off offset:2560
	v_addc_co_u32_e32 v47, vcc, 0, v147, vcc
	global_load_dwordx4 v[46:49], v[46:47], off offset:2560
	s_waitcnt vmcnt(0)
	v_pk_add_f32 v[34:35], v[34:35], v[38:39]
	v_pk_add_f32 v[32:33], v[32:33], v[36:37]
	v_pk_add_f32 v[36:37], v[44:45], v[48:49]
	v_pk_add_f32 v[38:39], v[42:43], v[46:47]
	v_pk_add_f32 v[34:35], v[34:35], v[36:37]
	v_pk_add_f32 v[32:33], v[32:33], v[38:39]
	s_nop 0
	v_pk_mov_b32 v[36:37], v[32:33], v[34:35] op_sel:[1,0]
	v_mov_b32_e32 v33, v35
	v_pk_add_f32 v[32:33], v[36:37], v[32:33]
	s_nop 0
	v_add_f32_e32 v32, v32, v33
	v_fmamk_f32 v32, v32, 0x3a800000, v156
	v_rsq_f32_e32 v252, v32
	s_nop 0
	v_mul_f32_e32 v250, v32, v252
	v_fma_f32 v250, -v250, v252, 1.0
	v_mul_f32_e32 v251, 0.5, v252
	v_fma_f32 v32, v251, v250, v252
.LBB0_1174:
	v_mov_b32_e32 v34, v24
	v_mov_b32_e32 v35, v28
	v_pk_mul_f32 v[34:35], v[34:35], v[32:33] op_sel_hi:[1,0]
	v_mov_b32_e32 v28, v25
	v_mul_f32_e32 v24, 0xbfb8aa3b, v35
	v_exp_f32_e32 v33, v24
	s_and_b64 vcc, exec, s[0:1]
	v_pk_mul_f32 v[24:25], v[28:29], v[32:33] op_sel_hi:[1,0]
	s_nop 0
	v_mul_f32_e32 v28, 0xbfb8aa3b, v25
	v_exp_f32_e32 v28, v28
	v_add_f32_e32 v29, 1.0, v33
	v_rcp_f32_e32 v29, v29
	v_add_u32_e32 v33, 0xa0, v144
	v_add_f32_e32 v28, 1.0, v28
	v_rcp_f32_e32 v28, v28
	v_mul_f32_e32 v29, v35, v29
	v_mul_f32_e32 v34, v34, v29
	v_mov_b32_e32 v29, v30
	v_mul_f32_e32 v25, v25, v28
	v_mov_b32_e32 v28, v26
	v_pk_mul_f32 v[28:29], v[28:29], v[32:33] op_sel_hi:[1,0]
	v_mov_b32_e32 v30, v27
	v_mul_f32_e32 v26, 0xbfb8aa3b, v29
	v_exp_f32_e32 v35, v26
	v_pk_mul_f32 v[26:27], v[30:31], v[32:33] op_sel_hi:[1,0]
	v_mul_f32_e32 v31, v24, v25
	v_mul_f32_e32 v30, 0xbfb8aa3b, v27
	v_exp_f32_e32 v30, v30
	v_add_f32_e32 v24, 1.0, v35
	v_rcp_f32_e32 v35, v24
	v_mov_b32_e32 v25, v20
	v_add_f32_e32 v24, 1.0, v30
	v_rcp_f32_e32 v30, v24
	v_mov_b32_e32 v24, v16
	v_pk_mul_f32 v[24:25], v[24:25], v[32:33] op_sel_hi:[1,0]
	v_mul_f32_e32 v20, v29, v35
	v_mul_f32_e32 v16, 0xbfb8aa3b, v25
	v_exp_f32_e32 v16, v16
	v_mul_f32_e32 v28, v28, v20
	v_mov_b32_e32 v20, v17
	v_mul_f32_e32 v27, v27, v30
	v_add_f32_e32 v16, 1.0, v16
	v_rcp_f32_e32 v29, v16
	v_pk_mul_f32 v[16:17], v[20:21], v[32:33] op_sel_hi:[1,0]
	v_mul_f32_e32 v26, v26, v27
	v_mul_f32_e32 v20, 0xbfb8aa3b, v17
	v_exp_f32_e32 v20, v20
	v_mul_f32_e32 v21, v25, v29
	v_mul_f32_e32 v24, v24, v21
	v_mov_b32_e32 v21, v22
	v_add_f32_e32 v20, 1.0, v20
	v_rcp_f32_e32 v25, v20
	v_mov_b32_e32 v20, v18
	v_pk_mul_f32 v[20:21], v[20:21], v[32:33] op_sel_hi:[1,0]
	v_mov_b32_e32 v22, v19
	v_mul_f32_e32 v18, 0xbfb8aa3b, v21
	v_exp_f32_e32 v27, v18
	v_pk_mul_f32 v[18:19], v[22:23], v[32:33] op_sel_hi:[1,0]
	v_mul_f32_e32 v17, v17, v25
	v_mul_f32_e32 v22, 0xbfb8aa3b, v19
	v_exp_f32_e32 v22, v22
	v_add_f32_e32 v23, 1.0, v27
	v_rcp_f32_e32 v23, v23
	v_mul_f32_e32 v25, v16, v17
	v_add_f32_e32 v22, 1.0, v22
	v_rcp_f32_e32 v22, v22
	v_mul_f32_e32 v16, v21, v23
	v_mul_f32_e32 v20, v20, v16
	v_mul_f32_e32 v16, v19, v22
	v_mul_f32_e32 v19, v18, v16
	v_cvt_pk_bf16_f32 v16, v34, v31
	v_cvt_pk_bf16_f32 v17, v28, v26
	v_cvt_pk_bf16_f32 v18, v24, v25
	v_cvt_pk_bf16_f32 v19, v20, v19
	v_mov_b64_e32 v[20:21], s[30:31]
	v_mad_i64_i32 v[20:21], s[8:9], v33, s60, v[20:21]
	v_lshl_add_u64 v[20:21], v[120:121], 1, v[20:21]
	global_store_dwordx4 v[20:21], v[16:19], off
	s_cbranch_vccnz .LBB0_1176
	v_add_co_u32_e32 v20, vcc, 0xc0000, v146
	global_load_dwordx4 v[16:19], v[146:147], off offset:2816
	s_nop 0
	v_addc_co_u32_e32 v21, vcc, 0, v147, vcc
	v_add_co_u32_e32 v24, vcc, 0x180000, v146
	s_nop 1
	v_addc_co_u32_e32 v25, vcc, 0, v147, vcc
	v_add_co_u32_e32 v28, vcc, 0x240000, v146
	global_load_dwordx4 v[20:23], v[20:21], off offset:2816
	s_nop 0
	global_load_dwordx4 v[24:27], v[24:25], off offset:2816
	v_addc_co_u32_e32 v29, vcc, 0, v147, vcc
	global_load_dwordx4 v[28:31], v[28:29], off offset:2816
	s_waitcnt vmcnt(0)
	v_pk_add_f32 v[18:19], v[18:19], v[22:23]
	v_pk_add_f32 v[16:17], v[16:17], v[20:21]
	v_pk_add_f32 v[20:21], v[26:27], v[30:31]
	v_pk_add_f32 v[22:23], v[24:25], v[28:29]
	v_pk_add_f32 v[18:19], v[18:19], v[20:21]
	v_pk_add_f32 v[16:17], v[16:17], v[22:23]
	s_nop 0
	v_pk_mov_b32 v[20:21], v[16:17], v[18:19] op_sel:[1,0]
	v_mov_b32_e32 v17, v19
	v_pk_add_f32 v[16:17], v[20:21], v[16:17]
	s_nop 0
	v_add_f32_e32 v16, v16, v17
	v_fmamk_f32 v16, v16, 0x3a800000, v156
	v_rsq_f32_e32 v252, v16
	s_nop 0
	v_mul_f32_e32 v250, v16, v252
	v_fma_f32 v250, -v250, v252, 1.0
	v_mul_f32_e32 v251, 0.5, v252
	v_fma_f32 v40, v251, v250, v252
